# GEMM K-loops: 40 redundant lgkmcnt(0) waits at the MFMA block heads removed (counter already drained before the barrier)
# speedup vs baseline: 1.0011x; 1.0011x over previous
; #define PG8_STAGE(bufoff, gbase, voff) do { _Pragma("unroll") for (int _i = 0; _i < 2; ++_i) \
;         __builtin_amdgcn_global_load_lds((const unsigned*)((const char*)(gbase) + (voff)[_i]), (PG8_LAS unsigned*)(lds + (bufoff) + ldsw + _i * 8192), 16, 0, 0); } while (0)
; #define PG8_LDA(dst, b, h) do { _Pragma("unroll") for (int m = 0; m < 4; ++m) _Pragma("unroll") for (int k = 0; k < 2; ++k) dst[m][k] = *(const PG8_LAS bf16x8*)(lds + PG8_SA(b, h) + aoff + m * 2048 + k * 1024); } while (0)
; #define PG8_LDB(dst, b, h) do { _Pragma("unroll") for (int n = 0; n < 2; ++n) _Pragma("unroll") for (int k = 0; k < 2; ++k) dst[n][k] = *(const PG8_LAS bf16x8*)(lds + PG8_SB(b, h) + boff + n * 2048 + k * 1024); } while (0)
; #define PG8_MMA(ai, bj, At, Bt) do { __builtin_amdgcn_s_setprio(1); _Pragma("unroll") for (int m = 0; m < 4; ++m) _Pragma("unroll") for (int n = 0; n < 2; ++n) _Pragma("unroll") for (int k = 0; k < 2; ++k) \
;         acc[ai][bj][m][n] = __builtin_amdgcn_mfma_f32_16x16x32_bf16(Bt[n][k], At[m][k], acc[ai][bj][m][n], 0, 0, 0); __builtin_amdgcn_s_setprio(0); } while (0)
; #define PG8_WAIT_V(n) asm volatile("s_waitcnt vmcnt(" #n ")" ::: "memory")
; #define PG8_WAIT_L(n) asm volatile("s_waitcnt lgkmcnt(" #n ")" ::: "memory")
; template <class Epi, class Sched, bool ALIGN_EPI = false, bool SP2 = false>
; __device__ __forceinline__ void gemm_phase(PG8_LAS unsigned char* lds, const Gemm g, const Sched& S, const Epi& E) {
;     ...
;             const bool last = (t == nt - 2);
;             const char* a1 = cA + (size_t)(t + 1) * kstep;
;             const char* a2 = last ? nA : cA + (size_t)(t + 2) * kstep; const char* b2 = last ? nB : cB + (size_t)(t + 2) * kstep;
;             const char* a3 = a2 + kstep; const char* b3 = b2 + kstep;
;             if (last && has_next) S.a_ready(nxt);
;             if constexpr (SP2) {
;             PG8_LDB(B0, 0, 0); PG8_LDB(B1, 0, 1); PG8_SCHED; PG8_LDA(At, 0, 0); PG8_STAGE(PG8_SA(1, 1), a1 + hstepA, voffA);
;             PG8_WAIT_V(8); PG8_WAIT_L(0); PG8_BAR; PG8_MMA(0, 0, At, B0); PG8_MMA(0, 1, At, B1); PG8_BAR; PG8_SCHED;
;             PG8_LDA(At, 0, 1); PG8_STAGE(PG8_SB(0, 0), b2, voffB); PG8_STAGE(PG8_SB(0, 1), b2 + hstepB, voffB); PG8_STAGE(PG8_SA(0, 0), a2, voffA);
;             PG8_WAIT_V(8); PG8_WAIT_L(0); PG8_BAR; PG8_MMA(1, 0, At, B0); PG8_MMA(1, 1, At, B1); PG8_BAR; PG8_SCHED;
.LBB0_146:
	s_add_u32 s10, s46, 0xfffc0080
	s_addc_u32 s11, s47, -1
	s_add_i32 s69, 0, 0x10000
	s_cmp_eq_u32 s68, 12
	s_cselect_b32 s51, s41, s11
	s_cselect_b32 s50, s57, s10
	v_add_u32_e32 v130, s69, v161
	s_cselect_b32 s49, s4, s63
	s_cselect_b32 s48, s39, s62
	s_add_i32 s81, 0, 0x14000
	ds_read_b128 v[164:167], v130
	ds_read_b128 v[168:171], v130 offset:1024
	ds_read_b128 v[186:189], v130 offset:2048
	ds_read_b128 v[190:193], v130 offset:3072
	v_add_u32_e32 v130, s81, v161
	ds_read_b128 v[198:201], v130
	ds_read_b128 v[202:205], v130 offset:1024
	ds_read_b128 v[206:209], v130 offset:2048
	ds_read_b128 v[210:213], v130 offset:3072
	v_lshl_add_u64 v[172:173], s[46:47], 0, v[156:157]
	s_add_i32 m0, s9, 0xc000
	ds_read_b128 v[214:217], v163
	ds_read_b128 v[218:221], v163 offset:1024
	ds_read_b128 v[222:225], v163 offset:2048
	ds_read_b128 v[226:229], v163 offset:3072
	ds_read_b128 v[230:233], v163 offset:4096
	ds_read_b128 v[234:237], v163 offset:5120
	ds_read_b128 v[238:241], v163 offset:6144
	ds_read_b128 v[242:245], v163 offset:7168
	global_load_lds_dwordx4 v[172:173], off
	v_lshl_add_u64 v[172:173], s[46:47], 0, v[158:159]
	s_add_i32 m0, s9, 0xe000
	s_nop 0
	global_load_lds_dwordx4 v[172:173], off
	s_waitcnt vmcnt(8)
	s_waitcnt lgkmcnt(0)
	s_barrier
	s_setprio 1
	v_mfma_f32_16x16x32_bf16 v[126:129], v[164:167], v[214:217], v[126:129]
	v_mfma_f32_16x16x32_bf16 v[122:125], v[186:189], v[214:217], v[122:125]
	v_mfma_f32_16x16x32_bf16 v[118:121], v[164:167], v[222:225], v[118:121]
	v_mfma_f32_16x16x32_bf16 v[114:117], v[186:189], v[222:225], v[114:117]
	v_mfma_f32_16x16x32_bf16 v[102:105], v[164:167], v[230:233], v[102:105]
	v_mfma_f32_16x16x32_bf16 v[98:101], v[186:189], v[230:233], v[98:101]
	v_mfma_f32_16x16x32_bf16 v[86:89], v[164:167], v[238:241], v[86:89]
	v_mfma_f32_16x16x32_bf16 v[82:85], v[186:189], v[238:241], v[82:85]
	v_mfma_f32_16x16x32_bf16 v[126:129], v[168:171], v[218:221], v[126:129]
	v_mfma_f32_16x16x32_bf16 v[122:125], v[190:193], v[218:221], v[122:125]
	v_mfma_f32_16x16x32_bf16 v[118:121], v[168:171], v[226:229], v[118:121]
	v_mfma_f32_16x16x32_bf16 v[114:117], v[190:193], v[226:229], v[114:117]
	v_mfma_f32_16x16x32_bf16 v[102:105], v[168:171], v[234:237], v[102:105]
	v_mfma_f32_16x16x32_bf16 v[98:101], v[190:193], v[234:237], v[98:101]
	v_mfma_f32_16x16x32_bf16 v[86:89], v[168:171], v[242:245], v[86:89]
	v_mfma_f32_16x16x32_bf16 v[82:85], v[190:193], v[242:245], v[82:85]
	s_setprio 0
	s_setprio 1
	v_mfma_f32_16x16x32_bf16 v[110:113], v[198:201], v[214:217], v[110:113]
	v_mfma_f32_16x16x32_bf16 v[106:109], v[206:209], v[214:217], v[106:109]
	v_mfma_f32_16x16x32_bf16 v[94:97], v[198:201], v[222:225], v[94:97]
	v_mfma_f32_16x16x32_bf16 v[90:93], v[206:209], v[222:225], v[90:93]
	v_mfma_f32_16x16x32_bf16 v[78:81], v[198:201], v[230:233], v[78:81]
	v_mfma_f32_16x16x32_bf16 v[74:77], v[206:209], v[230:233], v[74:77]
	v_mfma_f32_16x16x32_bf16 v[70:73], v[198:201], v[238:241], v[70:73]
	v_mfma_f32_16x16x32_bf16 v[66:69], v[206:209], v[238:241], v[66:69]
	v_mfma_f32_16x16x32_bf16 v[110:113], v[202:205], v[218:221], v[110:113]
	v_mfma_f32_16x16x32_bf16 v[106:109], v[210:213], v[218:221], v[106:109]
	v_mfma_f32_16x16x32_bf16 v[94:97], v[202:205], v[226:229], v[94:97]
	v_mfma_f32_16x16x32_bf16 v[90:93], v[210:213], v[226:229], v[90:93]
	v_mfma_f32_16x16x32_bf16 v[78:81], v[202:205], v[234:237], v[78:81]
	v_mfma_f32_16x16x32_bf16 v[74:77], v[210:213], v[234:237], v[74:77]
	v_mfma_f32_16x16x32_bf16 v[70:73], v[202:205], v[242:245], v[70:73]
	v_mfma_f32_16x16x32_bf16 v[66:69], v[210:213], v[242:245], v[66:69]
	s_setprio 0
	s_barrier
	s_add_i32 s10, s69, s8
	v_lshl_add_u64 v[172:173], s[48:49], 0, v[0:1]
	s_mov_b32 m0, s10
	ds_read_b128 v[214:217], v163 offset:16384
	ds_read_b128 v[218:221], v163 offset:17408
	ds_read_b128 v[222:225], v163 offset:18432
	ds_read_b128 v[226:229], v163 offset:19456
	ds_read_b128 v[230:233], v163 offset:20480
	ds_read_b128 v[234:237], v163 offset:21504
	ds_read_b128 v[238:241], v163 offset:22528
	ds_read_b128 v[242:245], v163 offset:23552
	global_load_lds_dwordx4 v[172:173], off
	s_add_i32 m0, s10, 0x2000
	s_add_u32 s10, s48, 0x40000
	v_lshl_add_u64 v[246:247], s[48:49], 0, v[150:151]
	s_addc_u32 s11, s49, 0
	s_add_i32 s69, s81, s8
	global_load_lds_dwordx4 v[246:247], off
	v_lshl_add_u64 v[248:249], s[10:11], 0, v[0:1]
	s_mov_b32 m0, s69
	v_lshl_add_u64 v[130:131], s[50:51], 0, v[152:153]
	global_load_lds_dwordx4 v[248:249], off
	v_lshl_add_u64 v[248:249], s[10:11], 0, v[150:151]
	s_add_i32 m0, s69, 0x2000
	s_nop 0
	global_load_lds_dwordx4 v[248:249], off
	v_lshl_add_u64 v[248:249], s[50:51], 0, v[154:155]
	s_mov_b32 m0, s9
	s_nop 0
	global_load_lds_dwordx4 v[248:249], off
	s_mov_b32 m0, s30
	s_nop 0
	global_load_lds_dwordx4 v[130:131], off
	s_waitcnt vmcnt(8)
	s_waitcnt lgkmcnt(0)
	s_barrier
; #define PG8_STAGE(bufoff, gbase, voff) do { _Pragma("unroll") for (int _i = 0; _i < 2; ++_i) \
;         __builtin_amdgcn_global_load_lds((const unsigned*)((const char*)(gbase) + (voff)[_i]), (PG8_LAS unsigned*)(lds + (bufoff) + ldsw + _i * 8192), 16, 0, 0); } while (0)
; #define PG8_LDA(dst, b, h) do { _Pragma("unroll") for (int m = 0; m < 4; ++m) _Pragma("unroll") for (int k = 0; k < 2; ++k) dst[m][k] = *(const PG8_LAS bf16x8*)(lds + PG8_SA(b, h) + aoff + m * 2048 + k * 1024); } while (0)
; #define PG8_LDB(dst, b, h) do { _Pragma("unroll") for (int n = 0; n < 2; ++n) _Pragma("unroll") for (int k = 0; k < 2; ++k) dst[n][k] = *(const PG8_LAS bf16x8*)(lds + PG8_SB(b, h) + boff + n * 2048 + k * 1024); } while (0)
; #define PG8_MMA(ai, bj, At, Bt) do { __builtin_amdgcn_s_setprio(1); _Pragma("unroll") for (int m = 0; m < 4; ++m) _Pragma("unroll") for (int n = 0; n < 2; ++n) _Pragma("unroll") for (int k = 0; k < 2; ++k) \
;         acc[ai][bj][m][n] = __builtin_amdgcn_mfma_f32_16x16x32_bf16(Bt[n][k], At[m][k], acc[ai][bj][m][n], 0, 0, 0); __builtin_amdgcn_s_setprio(0); } while (0)
; #define PG8_WAIT_V(n) asm volatile("s_waitcnt vmcnt(" #n ")" ::: "memory")
; #define PG8_WAIT_L(n) asm volatile("s_waitcnt lgkmcnt(" #n ")" ::: "memory")
; #define PG8_BAR __builtin_amdgcn_s_barrier()
; #define PG8_SCHED __builtin_amdgcn_sched_barrier(0)
; template <class Epi, class Sched, bool ALIGN_EPI = false, bool SP2 = false>
; __device__ __forceinline__ void gemm_phase(PG8_LAS unsigned char* lds, const Gemm g, const Sched& S, const Epi& E) {
;     ...
;             PG8_WAIT_V(8); PG8_WAIT_L(0); PG8_BAR; PG8_MMA(1, 0, At, B0); PG8_MMA(1, 1, At, B1); PG8_BAR; PG8_SCHED;
;             PG8_LDB(B0, 1, 0); PG8_LDB(B1, 1, 1); PG8_SCHED; PG8_LDA(At, 1, 0); PG8_STAGE(PG8_SA(0, 1), a2 + hstepA, voffA);
;             PG8_WAIT_V(8); PG8_WAIT_L(0); PG8_BAR; PG8_MMA(0, 0, At, B0); PG8_MMA(0, 1, At, B1); PG8_BAR; PG8_SCHED;
	s_setprio 1
	v_mfma_f32_16x16x32_bf16 v[62:65], v[164:167], v[214:217], v[62:65]
	v_mfma_f32_16x16x32_bf16 v[58:61], v[186:189], v[214:217], v[58:61]
	v_mfma_f32_16x16x32_bf16 v[54:57], v[164:167], v[222:225], v[54:57]
	v_mfma_f32_16x16x32_bf16 v[50:53], v[186:189], v[222:225], v[50:53]
	v_mfma_f32_16x16x32_bf16 v[38:41], v[164:167], v[230:233], v[38:41]
	v_mfma_f32_16x16x32_bf16 v[34:37], v[186:189], v[230:233], v[34:37]
	v_mfma_f32_16x16x32_bf16 v[22:25], v[164:167], v[238:241], v[22:25]
	v_mfma_f32_16x16x32_bf16 v[18:21], v[186:189], v[238:241], v[18:21]
	v_mfma_f32_16x16x32_bf16 v[62:65], v[168:171], v[218:221], v[62:65]
	v_mfma_f32_16x16x32_bf16 v[58:61], v[190:193], v[218:221], v[58:61]
	v_mfma_f32_16x16x32_bf16 v[54:57], v[168:171], v[226:229], v[54:57]
	v_mfma_f32_16x16x32_bf16 v[50:53], v[190:193], v[226:229], v[50:53]
	v_mfma_f32_16x16x32_bf16 v[38:41], v[168:171], v[234:237], v[38:41]
	v_mfma_f32_16x16x32_bf16 v[34:37], v[190:193], v[234:237], v[34:37]
	v_mfma_f32_16x16x32_bf16 v[22:25], v[168:171], v[242:245], v[22:25]
	v_mfma_f32_16x16x32_bf16 v[18:21], v[190:193], v[242:245], v[18:21]
	s_setprio 0
	s_setprio 1
	v_mfma_f32_16x16x32_bf16 v[46:49], v[198:201], v[214:217], v[46:49]
	v_mfma_f32_16x16x32_bf16 v[42:45], v[206:209], v[214:217], v[42:45]
	v_mfma_f32_16x16x32_bf16 v[30:33], v[198:201], v[222:225], v[30:33]
	v_mfma_f32_16x16x32_bf16 v[26:29], v[206:209], v[222:225], v[26:29]
	v_mfma_f32_16x16x32_bf16 v[14:17], v[198:201], v[230:233], v[14:17]
	v_mfma_f32_16x16x32_bf16 v[10:13], v[206:209], v[230:233], v[10:13]
	v_mfma_f32_16x16x32_bf16 v[6:9], v[198:201], v[238:241], v[6:9]
	v_mfma_f32_16x16x32_bf16 v[2:5], v[206:209], v[238:241], v[2:5]
	v_mfma_f32_16x16x32_bf16 v[46:49], v[202:205], v[218:221], v[46:49]
	v_mfma_f32_16x16x32_bf16 v[42:45], v[210:213], v[218:221], v[42:45]
	v_mfma_f32_16x16x32_bf16 v[30:33], v[202:205], v[226:229], v[30:33]
	v_mfma_f32_16x16x32_bf16 v[26:29], v[210:213], v[226:229], v[26:29]
	v_mfma_f32_16x16x32_bf16 v[14:17], v[202:205], v[234:237], v[14:17]
	v_mfma_f32_16x16x32_bf16 v[10:13], v[210:213], v[234:237], v[10:13]
	v_mfma_f32_16x16x32_bf16 v[6:9], v[202:205], v[242:245], v[6:9]
	v_mfma_f32_16x16x32_bf16 v[2:5], v[210:213], v[242:245], v[2:5]
	s_setprio 0
	s_barrier
	s_add_i32 s69, 0, 0x18000
	v_add_u32_e32 v132, s69, v161
	s_add_i32 s81, 0, 0x1c000
	ds_read_b128 v[164:167], v132
	ds_read_b128 v[168:171], v132 offset:1024
	ds_read_b128 v[186:189], v132 offset:2048
	ds_read_b128 v[190:193], v132 offset:3072
	v_add_u32_e32 v132, s81, v161
	ds_read_b128 v[198:201], v132
	ds_read_b128 v[202:205], v132 offset:1024
	ds_read_b128 v[206:209], v132 offset:2048
	ds_read_b128 v[210:213], v132 offset:3072
	s_add_u32 s10, s50, 0x40000
	s_addc_u32 s11, s51, 0
	s_mov_b32 m0, s31
	v_lshl_add_u64 v[132:133], s[10:11], 0, v[154:155]
	ds_read_b128 v[214:217], v163 offset:32768
	ds_read_b128 v[218:221], v163 offset:33792
	ds_read_b128 v[222:225], v163 offset:34816
	ds_read_b128 v[226:229], v163 offset:35840
	ds_read_b128 v[230:233], v163 offset:36864
	ds_read_b128 v[234:237], v163 offset:37888
	ds_read_b128 v[238:241], v163 offset:38912
	ds_read_b128 v[242:245], v163 offset:39936
	global_load_lds_dwordx4 v[132:133], off
	v_lshl_add_u64 v[132:133], s[10:11], 0, v[152:153]
	s_mov_b32 m0, s34
	s_nop 0
	global_load_lds_dwordx4 v[132:133], off
	s_waitcnt vmcnt(8)
	s_waitcnt lgkmcnt(0)
	s_barrier
	s_setprio 1
	v_mfma_f32_16x16x32_bf16 v[126:129], v[164:167], v[214:217], v[126:129]
	v_mfma_f32_16x16x32_bf16 v[122:125], v[186:189], v[214:217], v[122:125]
	v_mfma_f32_16x16x32_bf16 v[118:121], v[164:167], v[222:225], v[118:121]
	v_mfma_f32_16x16x32_bf16 v[114:117], v[186:189], v[222:225], v[114:117]
	v_mfma_f32_16x16x32_bf16 v[102:105], v[164:167], v[230:233], v[102:105]
	v_mfma_f32_16x16x32_bf16 v[98:101], v[186:189], v[230:233], v[98:101]
	v_mfma_f32_16x16x32_bf16 v[86:89], v[164:167], v[238:241], v[86:89]
	v_mfma_f32_16x16x32_bf16 v[82:85], v[186:189], v[238:241], v[82:85]
	v_mfma_f32_16x16x32_bf16 v[126:129], v[168:171], v[218:221], v[126:129]
	v_mfma_f32_16x16x32_bf16 v[122:125], v[190:193], v[218:221], v[122:125]
	v_mfma_f32_16x16x32_bf16 v[118:121], v[168:171], v[226:229], v[118:121]
	v_mfma_f32_16x16x32_bf16 v[114:117], v[190:193], v[226:229], v[114:117]
	v_mfma_f32_16x16x32_bf16 v[102:105], v[168:171], v[234:237], v[102:105]
	v_mfma_f32_16x16x32_bf16 v[98:101], v[190:193], v[234:237], v[98:101]
	v_mfma_f32_16x16x32_bf16 v[86:89], v[168:171], v[242:245], v[86:89]
	v_mfma_f32_16x16x32_bf16 v[82:85], v[190:193], v[242:245], v[82:85]
	s_setprio 0
	s_setprio 1
	v_mfma_f32_16x16x32_bf16 v[110:113], v[198:201], v[214:217], v[110:113]
	v_mfma_f32_16x16x32_bf16 v[106:109], v[206:209], v[214:217], v[106:109]
	v_mfma_f32_16x16x32_bf16 v[94:97], v[198:201], v[222:225], v[94:97]
	v_mfma_f32_16x16x32_bf16 v[90:93], v[206:209], v[222:225], v[90:93]
	v_mfma_f32_16x16x32_bf16 v[78:81], v[198:201], v[230:233], v[78:81]
	v_mfma_f32_16x16x32_bf16 v[74:77], v[206:209], v[230:233], v[74:77]
	v_mfma_f32_16x16x32_bf16 v[70:73], v[198:201], v[238:241], v[70:73]
	v_mfma_f32_16x16x32_bf16 v[66:69], v[206:209], v[238:241], v[66:69]
	v_mfma_f32_16x16x32_bf16 v[110:113], v[202:205], v[218:221], v[110:113]
	v_mfma_f32_16x16x32_bf16 v[106:109], v[210:213], v[218:221], v[106:109]
	v_mfma_f32_16x16x32_bf16 v[94:97], v[202:205], v[226:229], v[94:97]
	v_mfma_f32_16x16x32_bf16 v[90:93], v[210:213], v[226:229], v[90:93]
	v_mfma_f32_16x16x32_bf16 v[78:81], v[202:205], v[234:237], v[78:81]
	v_mfma_f32_16x16x32_bf16 v[74:77], v[210:213], v[234:237], v[74:77]
	v_mfma_f32_16x16x32_bf16 v[70:73], v[202:205], v[242:245], v[70:73]
	v_mfma_f32_16x16x32_bf16 v[66:69], v[210:213], v[242:245], v[66:69]
	s_setprio 0
	s_barrier
; #define PG8_STAGE(bufoff, gbase, voff) do { _Pragma("unroll") for (int _i = 0; _i < 2; ++_i) \
;         __builtin_amdgcn_global_load_lds((const unsigned*)((const char*)(gbase) + (voff)[_i]), (PG8_LAS unsigned*)(lds + (bufoff) + ldsw + _i * 8192), 16, 0, 0); } while (0)
; #define PG8_LDA(dst, b, h) do { _Pragma("unroll") for (int m = 0; m < 4; ++m) _Pragma("unroll") for (int k = 0; k < 2; ++k) dst[m][k] = *(const PG8_LAS bf16x8*)(lds + PG8_SA(b, h) + aoff + m * 2048 + k * 1024); } while (0)
; #define PG8_MMA(ai, bj, At, Bt) do { __builtin_amdgcn_s_setprio(1); _Pragma("unroll") for (int m = 0; m < 4; ++m) _Pragma("unroll") for (int n = 0; n < 2; ++n) _Pragma("unroll") for (int k = 0; k < 2; ++k) \
;         acc[ai][bj][m][n] = __builtin_amdgcn_mfma_f32_16x16x32_bf16(Bt[n][k], At[m][k], acc[ai][bj][m][n], 0, 0, 0); __builtin_amdgcn_s_setprio(0); } while (0)
; #define PG8_WAIT_V(n) asm volatile("s_waitcnt vmcnt(" #n ")" ::: "memory")
; #define PG8_WAIT_L(n) asm volatile("s_waitcnt lgkmcnt(" #n ")" ::: "memory")
; #define PG8_BAR __builtin_amdgcn_s_barrier()
; #define PG8_SCHED __builtin_amdgcn_sched_barrier(0)
; template <class Epi, class Sched, bool ALIGN_EPI = false, bool SP2 = false>
; __device__ __forceinline__ void gemm_phase(PG8_LAS unsigned char* lds, const Gemm g, const Sched& S, const Epi& E) {
;     ...
;             PG8_LDA(At, 1, 1); PG8_STAGE(PG8_SB(1, 0), b3, voffB); PG8_STAGE(PG8_SB(1, 1), b3 + hstepB, voffB); PG8_STAGE(PG8_SA(1, 0), a3, voffA);
;             PG8_WAIT_V(8); PG8_WAIT_L(0); PG8_BAR; PG8_MMA(1, 0, At, B0); PG8_MMA(1, 1, At, B1); PG8_BAR; PG8_SCHED;
;     ...
;         if constexpr (ALIGN_EPI) { if (wr == 0) PG8_BAR; }
	s_add_i32 s10, s69, s8
	v_lshl_add_u64 v[132:133], v[172:173], 0, s[2:3]
	s_mov_b32 m0, s10
	ds_read_b128 v[214:217], v163 offset:49152
	ds_read_b128 v[218:221], v163 offset:50176
	ds_read_b128 v[222:225], v163 offset:51200
	ds_read_b128 v[226:229], v163 offset:52224
	ds_read_b128 v[230:233], v163 offset:53248
	ds_read_b128 v[234:237], v163 offset:54272
	ds_read_b128 v[238:241], v163 offset:55296
	ds_read_b128 v[242:245], v163 offset:56320
	global_load_lds_dwordx4 v[132:133], off
	s_add_i32 m0, s10, 0x2000
	s_add_u32 s10, s48, 0x40080
	v_lshl_add_u64 v[132:133], v[246:247], 0, s[2:3]
	s_addc_u32 s11, s49, 0
	s_add_i32 s48, s81, s8
	global_load_lds_dwordx4 v[132:133], off
	v_lshl_add_u64 v[132:133], s[10:11], 0, v[0:1]
	s_mov_b32 m0, s48
	v_lshl_add_u64 v[130:131], v[130:131], 0, s[2:3]
	global_load_lds_dwordx4 v[132:133], off
	v_lshl_add_u64 v[132:133], s[10:11], 0, v[150:151]
	s_add_i32 m0, s48, 0x2000
	s_nop 0
	global_load_lds_dwordx4 v[132:133], off
	v_lshl_add_u64 v[132:133], v[248:249], 0, s[2:3]
	s_mov_b32 m0, s35
	s_nop 0
	global_load_lds_dwordx4 v[132:133], off
	s_mov_b32 m0, s52
	s_nop 0
	global_load_lds_dwordx4 v[130:131], off
	s_waitcnt vmcnt(8)
	s_waitcnt lgkmcnt(0)
	s_barrier
	s_setprio 1
	v_mfma_f32_16x16x32_bf16 v[62:65], v[164:167], v[214:217], v[62:65]
	v_mfma_f32_16x16x32_bf16 v[58:61], v[186:189], v[214:217], v[58:61]
	v_mfma_f32_16x16x32_bf16 v[54:57], v[164:167], v[222:225], v[54:57]
	v_mfma_f32_16x16x32_bf16 v[50:53], v[186:189], v[222:225], v[50:53]
	v_mfma_f32_16x16x32_bf16 v[38:41], v[164:167], v[230:233], v[38:41]
	v_mfma_f32_16x16x32_bf16 v[34:37], v[186:189], v[230:233], v[34:37]
	v_mfma_f32_16x16x32_bf16 v[22:25], v[164:167], v[238:241], v[22:25]
	v_mfma_f32_16x16x32_bf16 v[18:21], v[186:189], v[238:241], v[18:21]
	v_mfma_f32_16x16x32_bf16 v[62:65], v[168:171], v[218:221], v[62:65]
	v_mfma_f32_16x16x32_bf16 v[58:61], v[190:193], v[218:221], v[58:61]
	v_mfma_f32_16x16x32_bf16 v[54:57], v[168:171], v[226:229], v[54:57]
	v_mfma_f32_16x16x32_bf16 v[50:53], v[190:193], v[226:229], v[50:53]
	v_mfma_f32_16x16x32_bf16 v[38:41], v[168:171], v[234:237], v[38:41]
	v_mfma_f32_16x16x32_bf16 v[34:37], v[190:193], v[234:237], v[34:37]
	v_mfma_f32_16x16x32_bf16 v[22:25], v[168:171], v[242:245], v[22:25]
	v_mfma_f32_16x16x32_bf16 v[18:21], v[190:193], v[242:245], v[18:21]
	s_setprio 0
	s_setprio 1
	v_mfma_f32_16x16x32_bf16 v[46:49], v[198:201], v[214:217], v[46:49]
	v_mfma_f32_16x16x32_bf16 v[42:45], v[206:209], v[214:217], v[42:45]
	v_mfma_f32_16x16x32_bf16 v[30:33], v[198:201], v[222:225], v[30:33]
	v_mfma_f32_16x16x32_bf16 v[26:29], v[206:209], v[222:225], v[26:29]
	v_mfma_f32_16x16x32_bf16 v[14:17], v[198:201], v[230:233], v[14:17]
	v_mfma_f32_16x16x32_bf16 v[10:13], v[206:209], v[230:233], v[10:13]
	v_mfma_f32_16x16x32_bf16 v[6:9], v[198:201], v[238:241], v[6:9]
	v_mfma_f32_16x16x32_bf16 v[2:5], v[206:209], v[238:241], v[2:5]
	v_mfma_f32_16x16x32_bf16 v[46:49], v[202:205], v[218:221], v[46:49]
	v_mfma_f32_16x16x32_bf16 v[42:45], v[210:213], v[218:221], v[42:45]
	v_mfma_f32_16x16x32_bf16 v[30:33], v[202:205], v[226:229], v[30:33]
	v_mfma_f32_16x16x32_bf16 v[26:29], v[210:213], v[226:229], v[26:29]
	v_mfma_f32_16x16x32_bf16 v[14:17], v[202:205], v[234:237], v[14:17]
	v_mfma_f32_16x16x32_bf16 v[10:13], v[210:213], v[234:237], v[10:13]
	v_mfma_f32_16x16x32_bf16 v[6:9], v[202:205], v[242:245], v[6:9]
	v_mfma_f32_16x16x32_bf16 v[2:5], v[210:213], v[242:245], v[2:5]
	s_setprio 0
	s_barrier
	s_add_i32 s68, s68, 2
	s_add_u32 s46, s46, 0x100
	s_addc_u32 s47, s47, 0
	s_add_u32 s62, s62, 0x100
	s_addc_u32 s63, s63, 0
	s_cmp_gt_u32 s68, 13
	s_cbranch_scc0 .LBB0_146
	s_and_b64 vcc, exec, s[20:21]
	s_cbranch_vccz .LBB0_149
	s_barrier

; #define PG8_STAGE(bufoff, gbase, voff) do { _Pragma("unroll") for (int _i = 0; _i < 2; ++_i) \
;         __builtin_amdgcn_global_load_lds((const unsigned*)((const char*)(gbase) + (voff)[_i]), (PG8_LAS unsigned*)(lds + (bufoff) + ldsw + _i * 8192), 16, 0, 0); } while (0)
; #define PG8_LDA(dst, b, h) do { _Pragma("unroll") for (int m = 0; m < 4; ++m) _Pragma("unroll") for (int k = 0; k < 2; ++k) dst[m][k] = *(const PG8_LAS bf16x8*)(lds + PG8_SA(b, h) + aoff + m * 2048 + k * 1024); } while (0)
; #define PG8_LDB(dst, b, h) do { _Pragma("unroll") for (int n = 0; n < 2; ++n) _Pragma("unroll") for (int k = 0; k < 2; ++k) dst[n][k] = *(const PG8_LAS bf16x8*)(lds + PG8_SB(b, h) + boff + n * 2048 + k * 1024); } while (0)
; #define PG8_MMA(ai, bj, At, Bt) do { __builtin_amdgcn_s_setprio(1); _Pragma("unroll") for (int m = 0; m < 4; ++m) _Pragma("unroll") for (int n = 0; n < 2; ++n) _Pragma("unroll") for (int k = 0; k < 2; ++k) \
;         acc[ai][bj][m][n] = __builtin_amdgcn_mfma_f32_16x16x32_bf16(Bt[n][k], At[m][k], acc[ai][bj][m][n], 0, 0, 0); __builtin_amdgcn_s_setprio(0); } while (0)
; #define PG8_WAIT_V(n) asm volatile("s_waitcnt vmcnt(" #n ")" ::: "memory")
; #define PG8_WAIT_L(n) asm volatile("s_waitcnt lgkmcnt(" #n ")" ::: "memory")
; template <class Epi, class Sched, bool ALIGN_EPI = false, bool SP2 = false>
; __device__ __forceinline__ void gemm_phase(PG8_LAS unsigned char* lds, const Gemm g, const Sched& S, const Epi& E) {
;     ...
;             const bool last = (t == nt - 2);
;             const char* a1 = cA + (size_t)(t + 1) * kstep;
;             const char* a2 = last ? nA : cA + (size_t)(t + 2) * kstep; const char* b2 = last ? nB : cB + (size_t)(t + 2) * kstep;
;             const char* a3 = a2 + kstep; const char* b3 = b2 + kstep;
;             if (last && has_next) S.a_ready(nxt);
;             if constexpr (SP2) {
;             PG8_LDB(B0, 0, 0); PG8_LDB(B1, 0, 1); PG8_SCHED; PG8_LDA(At, 0, 0); PG8_STAGE(PG8_SA(1, 1), a1 + hstepA, voffA);
;             PG8_WAIT_V(8); PG8_WAIT_L(0); PG8_BAR; PG8_MMA(0, 0, At, B0); PG8_MMA(0, 1, At, B1); PG8_BAR; PG8_SCHED;
;             PG8_LDA(At, 0, 1); PG8_STAGE(PG8_SB(0, 0), b2, voffB); PG8_STAGE(PG8_SB(0, 1), b2 + hstepB, voffB); PG8_STAGE(PG8_SA(0, 0), a2, voffA);
;             PG8_WAIT_V(8); PG8_WAIT_L(0); PG8_BAR; PG8_MMA(1, 0, At, B0); PG8_MMA(1, 1, At, B1); PG8_BAR; PG8_SCHED;
.LBB0_168:
	s_add_u32 s10, s48, 0xfffc0080
	s_addc_u32 s11, s49, -1
	s_add_i32 s69, 0, 0x10000
	s_cmp_eq_u32 s68, 12
	s_cselect_b32 s53, s43, s11
	s_cselect_b32 s52, s57, s10
	v_add_u32_e32 v130, s69, v161
	s_cselect_b32 s51, s4, s63
	s_cselect_b32 s50, s41, s62
	s_add_i32 s81, 0, 0x14000
	ds_read_b128 v[164:167], v130
	ds_read_b128 v[168:171], v130 offset:1024
	ds_read_b128 v[186:189], v130 offset:2048
	ds_read_b128 v[190:193], v130 offset:3072
	v_add_u32_e32 v130, s81, v161
	ds_read_b128 v[198:201], v130
	ds_read_b128 v[202:205], v130 offset:1024
	ds_read_b128 v[206:209], v130 offset:2048
	ds_read_b128 v[210:213], v130 offset:3072
	v_lshl_add_u64 v[130:131], s[48:49], 0, v[156:157]
	s_add_i32 m0, s9, 0xc000
	ds_read_b128 v[214:217], v163
	ds_read_b128 v[218:221], v163 offset:1024
	ds_read_b128 v[222:225], v163 offset:2048
	ds_read_b128 v[226:229], v163 offset:3072
	ds_read_b128 v[230:233], v163 offset:4096
	ds_read_b128 v[234:237], v163 offset:5120
	ds_read_b128 v[238:241], v163 offset:6144
	ds_read_b128 v[242:245], v163 offset:7168
	global_load_lds_dwordx4 v[130:131], off
	v_lshl_add_u64 v[130:131], s[48:49], 0, v[158:159]
	s_add_i32 m0, s9, 0xe000
	s_nop 0
	global_load_lds_dwordx4 v[130:131], off
	s_waitcnt vmcnt(8)
	s_waitcnt lgkmcnt(0)
	s_barrier
	s_setprio 1
	v_mfma_f32_16x16x32_bf16 v[126:129], v[164:167], v[214:217], v[126:129]
	v_mfma_f32_16x16x32_bf16 v[122:125], v[186:189], v[214:217], v[122:125]
	v_mfma_f32_16x16x32_bf16 v[118:121], v[164:167], v[222:225], v[118:121]
	v_mfma_f32_16x16x32_bf16 v[114:117], v[186:189], v[222:225], v[114:117]
	v_mfma_f32_16x16x32_bf16 v[102:105], v[164:167], v[230:233], v[102:105]
	v_mfma_f32_16x16x32_bf16 v[98:101], v[186:189], v[230:233], v[98:101]
	v_mfma_f32_16x16x32_bf16 v[86:89], v[164:167], v[238:241], v[86:89]
	v_mfma_f32_16x16x32_bf16 v[82:85], v[186:189], v[238:241], v[82:85]
	v_mfma_f32_16x16x32_bf16 v[126:129], v[168:171], v[218:221], v[126:129]
	v_mfma_f32_16x16x32_bf16 v[122:125], v[190:193], v[218:221], v[122:125]
	v_mfma_f32_16x16x32_bf16 v[118:121], v[168:171], v[226:229], v[118:121]
	v_mfma_f32_16x16x32_bf16 v[114:117], v[190:193], v[226:229], v[114:117]
	v_mfma_f32_16x16x32_bf16 v[102:105], v[168:171], v[234:237], v[102:105]
	v_mfma_f32_16x16x32_bf16 v[98:101], v[190:193], v[234:237], v[98:101]
	v_mfma_f32_16x16x32_bf16 v[86:89], v[168:171], v[242:245], v[86:89]
	v_mfma_f32_16x16x32_bf16 v[82:85], v[190:193], v[242:245], v[82:85]
	s_setprio 0
	s_setprio 1
	v_mfma_f32_16x16x32_bf16 v[110:113], v[198:201], v[214:217], v[110:113]
	v_mfma_f32_16x16x32_bf16 v[106:109], v[206:209], v[214:217], v[106:109]
	v_mfma_f32_16x16x32_bf16 v[94:97], v[198:201], v[222:225], v[94:97]
	v_mfma_f32_16x16x32_bf16 v[90:93], v[206:209], v[222:225], v[90:93]
	v_mfma_f32_16x16x32_bf16 v[78:81], v[198:201], v[230:233], v[78:81]
	v_mfma_f32_16x16x32_bf16 v[74:77], v[206:209], v[230:233], v[74:77]
	v_mfma_f32_16x16x32_bf16 v[70:73], v[198:201], v[238:241], v[70:73]
	v_mfma_f32_16x16x32_bf16 v[66:69], v[206:209], v[238:241], v[66:69]
	v_mfma_f32_16x16x32_bf16 v[110:113], v[202:205], v[218:221], v[110:113]
	v_mfma_f32_16x16x32_bf16 v[106:109], v[210:213], v[218:221], v[106:109]
	v_mfma_f32_16x16x32_bf16 v[94:97], v[202:205], v[226:229], v[94:97]
	v_mfma_f32_16x16x32_bf16 v[90:93], v[210:213], v[226:229], v[90:93]
	v_mfma_f32_16x16x32_bf16 v[78:81], v[202:205], v[234:237], v[78:81]
	v_mfma_f32_16x16x32_bf16 v[74:77], v[210:213], v[234:237], v[74:77]
	v_mfma_f32_16x16x32_bf16 v[70:73], v[202:205], v[242:245], v[70:73]
	v_mfma_f32_16x16x32_bf16 v[66:69], v[210:213], v[242:245], v[66:69]
	s_setprio 0
	s_barrier
	s_add_i32 s10, s69, s8
	v_lshl_add_u64 v[130:131], s[50:51], 0, v[0:1]
	s_mov_b32 m0, s10
	ds_read_b128 v[214:217], v163 offset:16384
	ds_read_b128 v[218:221], v163 offset:17408
	ds_read_b128 v[222:225], v163 offset:18432
	ds_read_b128 v[226:229], v163 offset:19456
	ds_read_b128 v[230:233], v163 offset:20480
	ds_read_b128 v[234:237], v163 offset:21504
	ds_read_b128 v[238:241], v163 offset:22528
	ds_read_b128 v[242:245], v163 offset:23552
	global_load_lds_dwordx4 v[130:131], off
	s_add_i32 m0, s10, 0x2000
	s_add_u32 s10, s50, 0x40000
	v_lshl_add_u64 v[132:133], s[50:51], 0, v[154:155]
	s_addc_u32 s11, s51, 0
	s_add_i32 s69, s81, s8
	global_load_lds_dwordx4 v[132:133], off
	v_lshl_add_u64 v[172:173], s[10:11], 0, v[0:1]
	s_mov_b32 m0, s69
	v_lshl_add_u64 v[246:247], s[52:53], 0, v[152:153]
	global_load_lds_dwordx4 v[172:173], off
	v_lshl_add_u64 v[172:173], s[10:11], 0, v[154:155]
	s_add_i32 m0, s69, 0x2000
	s_nop 0
	global_load_lds_dwordx4 v[172:173], off
	v_lshl_add_u64 v[172:173], s[52:53], 0, v[150:151]
	s_mov_b32 m0, s9
	s_nop 0
	global_load_lds_dwordx4 v[172:173], off
	s_mov_b32 m0, s30
	s_nop 0
	global_load_lds_dwordx4 v[246:247], off
	s_waitcnt vmcnt(8)
	s_waitcnt lgkmcnt(0)
	s_barrier
; #define PG8_STAGE(bufoff, gbase, voff) do { _Pragma("unroll") for (int _i = 0; _i < 2; ++_i) \
;         __builtin_amdgcn_global_load_lds((const unsigned*)((const char*)(gbase) + (voff)[_i]), (PG8_LAS unsigned*)(lds + (bufoff) + ldsw + _i * 8192), 16, 0, 0); } while (0)
; #define PG8_LDA(dst, b, h) do { _Pragma("unroll") for (int m = 0; m < 4; ++m) _Pragma("unroll") for (int k = 0; k < 2; ++k) dst[m][k] = *(const PG8_LAS bf16x8*)(lds + PG8_SA(b, h) + aoff + m * 2048 + k * 1024); } while (0)
; #define PG8_LDB(dst, b, h) do { _Pragma("unroll") for (int n = 0; n < 2; ++n) _Pragma("unroll") for (int k = 0; k < 2; ++k) dst[n][k] = *(const PG8_LAS bf16x8*)(lds + PG8_SB(b, h) + boff + n * 2048 + k * 1024); } while (0)
; #define PG8_MMA(ai, bj, At, Bt) do { __builtin_amdgcn_s_setprio(1); _Pragma("unroll") for (int m = 0; m < 4; ++m) _Pragma("unroll") for (int n = 0; n < 2; ++n) _Pragma("unroll") for (int k = 0; k < 2; ++k) \
;         acc[ai][bj][m][n] = __builtin_amdgcn_mfma_f32_16x16x32_bf16(Bt[n][k], At[m][k], acc[ai][bj][m][n], 0, 0, 0); __builtin_amdgcn_s_setprio(0); } while (0)
; #define PG8_WAIT_V(n) asm volatile("s_waitcnt vmcnt(" #n ")" ::: "memory")
; #define PG8_WAIT_L(n) asm volatile("s_waitcnt lgkmcnt(" #n ")" ::: "memory")
; #define PG8_BAR __builtin_amdgcn_s_barrier()
; #define PG8_SCHED __builtin_amdgcn_sched_barrier(0)
; template <class Epi, class Sched, bool ALIGN_EPI = false, bool SP2 = false>
; __device__ __forceinline__ void gemm_phase(PG8_LAS unsigned char* lds, const Gemm g, const Sched& S, const Epi& E) {
;     ...
;             PG8_WAIT_V(8); PG8_WAIT_L(0); PG8_BAR; PG8_MMA(1, 0, At, B0); PG8_MMA(1, 1, At, B1); PG8_BAR; PG8_SCHED;
;             PG8_LDB(B0, 1, 0); PG8_LDB(B1, 1, 1); PG8_SCHED; PG8_LDA(At, 1, 0); PG8_STAGE(PG8_SA(0, 1), a2 + hstepA, voffA);
;             PG8_WAIT_V(8); PG8_WAIT_L(0); PG8_BAR; PG8_MMA(0, 0, At, B0); PG8_MMA(0, 1, At, B1); PG8_BAR; PG8_SCHED;
	s_setprio 1
	v_mfma_f32_16x16x32_bf16 v[62:65], v[164:167], v[214:217], v[62:65]
	v_mfma_f32_16x16x32_bf16 v[58:61], v[186:189], v[214:217], v[58:61]
	v_mfma_f32_16x16x32_bf16 v[54:57], v[164:167], v[222:225], v[54:57]
	v_mfma_f32_16x16x32_bf16 v[50:53], v[186:189], v[222:225], v[50:53]
	v_mfma_f32_16x16x32_bf16 v[38:41], v[164:167], v[230:233], v[38:41]
	v_mfma_f32_16x16x32_bf16 v[34:37], v[186:189], v[230:233], v[34:37]
	v_mfma_f32_16x16x32_bf16 v[22:25], v[164:167], v[238:241], v[22:25]
	v_mfma_f32_16x16x32_bf16 v[18:21], v[186:189], v[238:241], v[18:21]
	v_mfma_f32_16x16x32_bf16 v[62:65], v[168:171], v[218:221], v[62:65]
	v_mfma_f32_16x16x32_bf16 v[58:61], v[190:193], v[218:221], v[58:61]
	v_mfma_f32_16x16x32_bf16 v[54:57], v[168:171], v[226:229], v[54:57]
	v_mfma_f32_16x16x32_bf16 v[50:53], v[190:193], v[226:229], v[50:53]
	v_mfma_f32_16x16x32_bf16 v[38:41], v[168:171], v[234:237], v[38:41]
	v_mfma_f32_16x16x32_bf16 v[34:37], v[190:193], v[234:237], v[34:37]
	v_mfma_f32_16x16x32_bf16 v[22:25], v[168:171], v[242:245], v[22:25]
	v_mfma_f32_16x16x32_bf16 v[18:21], v[190:193], v[242:245], v[18:21]
	s_setprio 0
	s_setprio 1
	v_mfma_f32_16x16x32_bf16 v[46:49], v[198:201], v[214:217], v[46:49]
	v_mfma_f32_16x16x32_bf16 v[42:45], v[206:209], v[214:217], v[42:45]
	v_mfma_f32_16x16x32_bf16 v[30:33], v[198:201], v[222:225], v[30:33]
	v_mfma_f32_16x16x32_bf16 v[26:29], v[206:209], v[222:225], v[26:29]
	v_mfma_f32_16x16x32_bf16 v[14:17], v[198:201], v[230:233], v[14:17]
	v_mfma_f32_16x16x32_bf16 v[10:13], v[206:209], v[230:233], v[10:13]
	v_mfma_f32_16x16x32_bf16 v[6:9], v[198:201], v[238:241], v[6:9]
	v_mfma_f32_16x16x32_bf16 v[2:5], v[206:209], v[238:241], v[2:5]
	v_mfma_f32_16x16x32_bf16 v[46:49], v[202:205], v[218:221], v[46:49]
	v_mfma_f32_16x16x32_bf16 v[42:45], v[210:213], v[218:221], v[42:45]
	v_mfma_f32_16x16x32_bf16 v[30:33], v[202:205], v[226:229], v[30:33]
	v_mfma_f32_16x16x32_bf16 v[26:29], v[210:213], v[226:229], v[26:29]
	v_mfma_f32_16x16x32_bf16 v[14:17], v[202:205], v[234:237], v[14:17]
	v_mfma_f32_16x16x32_bf16 v[10:13], v[210:213], v[234:237], v[10:13]
	v_mfma_f32_16x16x32_bf16 v[6:9], v[202:205], v[242:245], v[6:9]
	v_mfma_f32_16x16x32_bf16 v[2:5], v[210:213], v[242:245], v[2:5]
	s_setprio 0
	s_barrier
	s_add_i32 s69, 0, 0x18000
	s_add_i32 s81, 0, 0x1c000
	v_add_u32_e32 v190, s69, v161
	v_add_u32_e32 v210, s81, v161
	ds_read_b128 v[164:167], v190
	ds_read_b128 v[168:171], v190 offset:1024
	ds_read_b128 v[186:189], v190 offset:2048
	ds_read_b128 v[190:193], v190 offset:3072
	ds_read_b128 v[198:201], v210
	ds_read_b128 v[202:205], v210 offset:1024
	ds_read_b128 v[206:209], v210 offset:2048
	ds_read_b128 v[210:213], v210 offset:3072
	s_add_u32 s10, s52, 0x40000
	s_addc_u32 s11, s53, 0
	s_mov_b32 m0, s31
	v_lshl_add_u64 v[248:249], s[10:11], 0, v[150:151]
	ds_read_b128 v[214:217], v163 offset:32768
	ds_read_b128 v[218:221], v163 offset:33792
	ds_read_b128 v[222:225], v163 offset:34816
	ds_read_b128 v[226:229], v163 offset:35840
	ds_read_b128 v[230:233], v163 offset:36864
	ds_read_b128 v[234:237], v163 offset:37888
	ds_read_b128 v[238:241], v163 offset:38912
	ds_read_b128 v[242:245], v163 offset:39936
	global_load_lds_dwordx4 v[248:249], off
	v_lshl_add_u64 v[248:249], s[10:11], 0, v[152:153]
	s_mov_b32 m0, s34
	s_nop 0
	global_load_lds_dwordx4 v[248:249], off
	s_waitcnt vmcnt(8)
	s_waitcnt lgkmcnt(0)
	s_barrier
	s_setprio 1
	v_mfma_f32_16x16x32_bf16 v[126:129], v[164:167], v[214:217], v[126:129]
	v_mfma_f32_16x16x32_bf16 v[122:125], v[186:189], v[214:217], v[122:125]
	v_mfma_f32_16x16x32_bf16 v[118:121], v[164:167], v[222:225], v[118:121]
	v_mfma_f32_16x16x32_bf16 v[114:117], v[186:189], v[222:225], v[114:117]
	v_mfma_f32_16x16x32_bf16 v[102:105], v[164:167], v[230:233], v[102:105]
	v_mfma_f32_16x16x32_bf16 v[98:101], v[186:189], v[230:233], v[98:101]
	v_mfma_f32_16x16x32_bf16 v[86:89], v[164:167], v[238:241], v[86:89]
	v_mfma_f32_16x16x32_bf16 v[82:85], v[186:189], v[238:241], v[82:85]
	v_mfma_f32_16x16x32_bf16 v[126:129], v[168:171], v[218:221], v[126:129]
	v_mfma_f32_16x16x32_bf16 v[122:125], v[190:193], v[218:221], v[122:125]
	v_mfma_f32_16x16x32_bf16 v[118:121], v[168:171], v[226:229], v[118:121]
	v_mfma_f32_16x16x32_bf16 v[114:117], v[190:193], v[226:229], v[114:117]
	v_mfma_f32_16x16x32_bf16 v[102:105], v[168:171], v[234:237], v[102:105]
	v_mfma_f32_16x16x32_bf16 v[98:101], v[190:193], v[234:237], v[98:101]
	v_mfma_f32_16x16x32_bf16 v[86:89], v[168:171], v[242:245], v[86:89]
	v_mfma_f32_16x16x32_bf16 v[82:85], v[190:193], v[242:245], v[82:85]
	s_setprio 0
	s_setprio 1
	v_mfma_f32_16x16x32_bf16 v[110:113], v[198:201], v[214:217], v[110:113]
	v_mfma_f32_16x16x32_bf16 v[106:109], v[206:209], v[214:217], v[106:109]
	v_mfma_f32_16x16x32_bf16 v[94:97], v[198:201], v[222:225], v[94:97]
	v_mfma_f32_16x16x32_bf16 v[90:93], v[206:209], v[222:225], v[90:93]
	v_mfma_f32_16x16x32_bf16 v[78:81], v[198:201], v[230:233], v[78:81]
	v_mfma_f32_16x16x32_bf16 v[74:77], v[206:209], v[230:233], v[74:77]
	v_mfma_f32_16x16x32_bf16 v[70:73], v[198:201], v[238:241], v[70:73]
	v_mfma_f32_16x16x32_bf16 v[66:69], v[206:209], v[238:241], v[66:69]
	v_mfma_f32_16x16x32_bf16 v[110:113], v[202:205], v[218:221], v[110:113]
	v_mfma_f32_16x16x32_bf16 v[106:109], v[210:213], v[218:221], v[106:109]
	v_mfma_f32_16x16x32_bf16 v[94:97], v[202:205], v[226:229], v[94:97]
	v_mfma_f32_16x16x32_bf16 v[90:93], v[210:213], v[226:229], v[90:93]
	v_mfma_f32_16x16x32_bf16 v[78:81], v[202:205], v[234:237], v[78:81]
	v_mfma_f32_16x16x32_bf16 v[74:77], v[210:213], v[234:237], v[74:77]
	v_mfma_f32_16x16x32_bf16 v[70:73], v[202:205], v[242:245], v[70:73]
	v_mfma_f32_16x16x32_bf16 v[66:69], v[210:213], v[242:245], v[66:69]
	s_setprio 0
	s_barrier
; #define PG8_STAGE(bufoff, gbase, voff) do { _Pragma("unroll") for (int _i = 0; _i < 2; ++_i) \
;         __builtin_amdgcn_global_load_lds((const unsigned*)((const char*)(gbase) + (voff)[_i]), (PG8_LAS unsigned*)(lds + (bufoff) + ldsw + _i * 8192), 16, 0, 0); } while (0)
; #define PG8_LDA(dst, b, h) do { _Pragma("unroll") for (int m = 0; m < 4; ++m) _Pragma("unroll") for (int k = 0; k < 2; ++k) dst[m][k] = *(const PG8_LAS bf16x8*)(lds + PG8_SA(b, h) + aoff + m * 2048 + k * 1024); } while (0)
; #define PG8_MMA(ai, bj, At, Bt) do { __builtin_amdgcn_s_setprio(1); _Pragma("unroll") for (int m = 0; m < 4; ++m) _Pragma("unroll") for (int n = 0; n < 2; ++n) _Pragma("unroll") for (int k = 0; k < 2; ++k) \
;         acc[ai][bj][m][n] = __builtin_amdgcn_mfma_f32_16x16x32_bf16(Bt[n][k], At[m][k], acc[ai][bj][m][n], 0, 0, 0); __builtin_amdgcn_s_setprio(0); } while (0)
; #define PG8_WAIT_V(n) asm volatile("s_waitcnt vmcnt(" #n ")" ::: "memory")
; #define PG8_WAIT_L(n) asm volatile("s_waitcnt lgkmcnt(" #n ")" ::: "memory")
; #define PG8_BAR __builtin_amdgcn_s_barrier()
; #define PG8_SCHED __builtin_amdgcn_sched_barrier(0)
; template <class Epi, class Sched, bool ALIGN_EPI = false, bool SP2 = false>
; __device__ __forceinline__ void gemm_phase(PG8_LAS unsigned char* lds, const Gemm g, const Sched& S, const Epi& E) {
;     ...
;             PG8_LDA(At, 1, 1); PG8_STAGE(PG8_SB(1, 0), b3, voffB); PG8_STAGE(PG8_SB(1, 1), b3 + hstepB, voffB); PG8_STAGE(PG8_SA(1, 0), a3, voffA);
;             PG8_WAIT_V(8); PG8_WAIT_L(0); PG8_BAR; PG8_MMA(1, 0, At, B0); PG8_MMA(1, 1, At, B1); PG8_BAR; PG8_SCHED;
;     ...
;         if constexpr (ALIGN_EPI) { if (wr == 0) PG8_BAR; }
	s_add_i32 s10, s69, s8
	v_lshl_add_u64 v[130:131], v[130:131], 0, s[2:3]
	s_mov_b32 m0, s10
	ds_read_b128 v[214:217], v163 offset:49152
	ds_read_b128 v[218:221], v163 offset:50176
	ds_read_b128 v[222:225], v163 offset:51200
	ds_read_b128 v[226:229], v163 offset:52224
	ds_read_b128 v[230:233], v163 offset:53248
	ds_read_b128 v[234:237], v163 offset:54272
	ds_read_b128 v[238:241], v163 offset:55296
	ds_read_b128 v[242:245], v163 offset:56320
	global_load_lds_dwordx4 v[130:131], off
	s_add_i32 m0, s10, 0x2000
	s_add_u32 s10, s50, 0x40080
	v_lshl_add_u64 v[130:131], v[132:133], 0, s[2:3]
	s_addc_u32 s11, s51, 0
	s_add_i32 s50, s81, s8
	global_load_lds_dwordx4 v[130:131], off
	v_lshl_add_u64 v[130:131], s[10:11], 0, v[0:1]
	s_mov_b32 m0, s50
	s_nop 0
	global_load_lds_dwordx4 v[130:131], off
	v_lshl_add_u64 v[130:131], s[10:11], 0, v[154:155]
	s_add_i32 m0, s50, 0x2000
	s_nop 0
	global_load_lds_dwordx4 v[130:131], off
	v_lshl_add_u64 v[130:131], v[172:173], 0, s[2:3]
	s_mov_b32 m0, s35
	s_nop 0
	global_load_lds_dwordx4 v[130:131], off
	v_lshl_add_u64 v[130:131], v[246:247], 0, s[2:3]
	s_mov_b32 m0, s39
	s_nop 0
	global_load_lds_dwordx4 v[130:131], off
	s_waitcnt vmcnt(8)
	s_waitcnt lgkmcnt(0)
	s_barrier
	s_setprio 1
	v_mfma_f32_16x16x32_bf16 v[62:65], v[164:167], v[214:217], v[62:65]
	v_mfma_f32_16x16x32_bf16 v[58:61], v[186:189], v[214:217], v[58:61]
	v_mfma_f32_16x16x32_bf16 v[54:57], v[164:167], v[222:225], v[54:57]
	v_mfma_f32_16x16x32_bf16 v[50:53], v[186:189], v[222:225], v[50:53]
	v_mfma_f32_16x16x32_bf16 v[38:41], v[164:167], v[230:233], v[38:41]
	v_mfma_f32_16x16x32_bf16 v[34:37], v[186:189], v[230:233], v[34:37]
	v_mfma_f32_16x16x32_bf16 v[22:25], v[164:167], v[238:241], v[22:25]
	v_mfma_f32_16x16x32_bf16 v[18:21], v[186:189], v[238:241], v[18:21]
	v_mfma_f32_16x16x32_bf16 v[62:65], v[168:171], v[218:221], v[62:65]
	v_mfma_f32_16x16x32_bf16 v[58:61], v[190:193], v[218:221], v[58:61]
	v_mfma_f32_16x16x32_bf16 v[54:57], v[168:171], v[226:229], v[54:57]
	v_mfma_f32_16x16x32_bf16 v[50:53], v[190:193], v[226:229], v[50:53]
	v_mfma_f32_16x16x32_bf16 v[38:41], v[168:171], v[234:237], v[38:41]
	v_mfma_f32_16x16x32_bf16 v[34:37], v[190:193], v[234:237], v[34:37]
	v_mfma_f32_16x16x32_bf16 v[22:25], v[168:171], v[242:245], v[22:25]
	v_mfma_f32_16x16x32_bf16 v[18:21], v[190:193], v[242:245], v[18:21]
	s_setprio 0
	s_setprio 1
	v_mfma_f32_16x16x32_bf16 v[46:49], v[198:201], v[214:217], v[46:49]
	v_mfma_f32_16x16x32_bf16 v[42:45], v[206:209], v[214:217], v[42:45]
	v_mfma_f32_16x16x32_bf16 v[30:33], v[198:201], v[222:225], v[30:33]
	v_mfma_f32_16x16x32_bf16 v[26:29], v[206:209], v[222:225], v[26:29]
	v_mfma_f32_16x16x32_bf16 v[14:17], v[198:201], v[230:233], v[14:17]
	v_mfma_f32_16x16x32_bf16 v[10:13], v[206:209], v[230:233], v[10:13]
	v_mfma_f32_16x16x32_bf16 v[6:9], v[198:201], v[238:241], v[6:9]
	v_mfma_f32_16x16x32_bf16 v[2:5], v[206:209], v[238:241], v[2:5]
	v_mfma_f32_16x16x32_bf16 v[46:49], v[202:205], v[218:221], v[46:49]
	v_mfma_f32_16x16x32_bf16 v[42:45], v[210:213], v[218:221], v[42:45]
	v_mfma_f32_16x16x32_bf16 v[30:33], v[202:205], v[226:229], v[30:33]
	v_mfma_f32_16x16x32_bf16 v[26:29], v[210:213], v[226:229], v[26:29]
	v_mfma_f32_16x16x32_bf16 v[14:17], v[202:205], v[234:237], v[14:17]
	v_mfma_f32_16x16x32_bf16 v[10:13], v[210:213], v[234:237], v[10:13]
	v_mfma_f32_16x16x32_bf16 v[6:9], v[202:205], v[242:245], v[6:9]
	v_mfma_f32_16x16x32_bf16 v[2:5], v[210:213], v[242:245], v[2:5]
	s_setprio 0
	s_barrier
	s_add_i32 s68, s68, 2
	s_add_u32 s48, s48, 0x100
	s_addc_u32 s49, s49, 0
	s_add_u32 s62, s62, 0x100
	s_addc_u32 s63, s63, 0
	s_cmp_gt_u32 s68, 13
	s_cbranch_scc0 .LBB0_168
	s_and_b64 vcc, exec, s[20:21]
	s_mov_b64 s[62:63], s[14:15]
	s_cbranch_vccz .LBB0_171
	s_barrier

; #define PG8_STAGE(bufoff, gbase, voff) do { _Pragma("unroll") for (int _i = 0; _i < 2; ++_i) \
;         __builtin_amdgcn_global_load_lds((const unsigned*)((const char*)(gbase) + (voff)[_i]), (PG8_LAS unsigned*)(lds + (bufoff) + ldsw + _i * 8192), 16, 0, 0); } while (0)
; #define PG8_LDA(dst, b, h) do { _Pragma("unroll") for (int m = 0; m < 4; ++m) _Pragma("unroll") for (int k = 0; k < 2; ++k) dst[m][k] = *(const PG8_LAS bf16x8*)(lds + PG8_SA(b, h) + aoff + m * 2048 + k * 1024); } while (0)
; #define PG8_LDB(dst, b, h) do { _Pragma("unroll") for (int n = 0; n < 2; ++n) _Pragma("unroll") for (int k = 0; k < 2; ++k) dst[n][k] = *(const PG8_LAS bf16x8*)(lds + PG8_SB(b, h) + boff + n * 2048 + k * 1024); } while (0)
; #define PG8_MMA(ai, bj, At, Bt) do { __builtin_amdgcn_s_setprio(1); _Pragma("unroll") for (int m = 0; m < 4; ++m) _Pragma("unroll") for (int n = 0; n < 2; ++n) _Pragma("unroll") for (int k = 0; k < 2; ++k) \
;         acc[ai][bj][m][n] = __builtin_amdgcn_mfma_f32_16x16x32_bf16(Bt[n][k], At[m][k], acc[ai][bj][m][n], 0, 0, 0); __builtin_amdgcn_s_setprio(0); } while (0)
; #define PG8_WAIT_V(n) asm volatile("s_waitcnt vmcnt(" #n ")" ::: "memory")
; #define PG8_WAIT_L(n) asm volatile("s_waitcnt lgkmcnt(" #n ")" ::: "memory")
; template <class Epi, class Sched, bool ALIGN_EPI = false, bool SP2 = false>
; __device__ __forceinline__ void gemm_phase(PG8_LAS unsigned char* lds, const Gemm g, const Sched& S, const Epi& E) {
;     ...
;             const bool last = (t == nt - 2);
;             const char* a1 = cA + (size_t)(t + 1) * kstep;
;             const char* a2 = last ? nA : cA + (size_t)(t + 2) * kstep; const char* b2 = last ? nB : cB + (size_t)(t + 2) * kstep;
;             const char* a3 = a2 + kstep; const char* b3 = b2 + kstep;
;             if (last && has_next) S.a_ready(nxt);
;             if constexpr (SP2) {
;             PG8_LDB(B0, 0, 0); PG8_LDB(B1, 0, 1); PG8_SCHED; PG8_LDA(At, 0, 0); PG8_STAGE(PG8_SA(1, 1), a1 + hstepA, voffA);
;             PG8_WAIT_V(8); PG8_WAIT_L(0); PG8_BAR; PG8_MMA(0, 0, At, B0); PG8_MMA(0, 1, At, B1); PG8_BAR; PG8_SCHED;
;             PG8_LDA(At, 0, 1); PG8_STAGE(PG8_SB(0, 0), b2, voffB); PG8_STAGE(PG8_SB(0, 1), b2 + hstepB, voffB); PG8_STAGE(PG8_SA(0, 0), a2, voffA);
;             PG8_WAIT_V(8); PG8_WAIT_L(0); PG8_BAR; PG8_MMA(1, 0, At, B0); PG8_MMA(1, 1, At, B1); PG8_BAR; PG8_SCHED;
.LBB0_380:
	s_add_u32 s36, s50, s4
	s_addc_u32 s37, s51, 0
	s_add_u32 s54, s36, 0x100
	s_addc_u32 s55, s37, 0
	s_and_b64 s[10:11], s[52:53], exec
	s_cselect_b32 s57, s45, s55
	s_cselect_b32 s56, s44, s54
	s_add_u32 s4, s48, s4
	s_addc_u32 s10, s49, 0
	s_add_u32 s4, s4, 0x100
	s_addc_u32 s54, s10, 0
	s_add_i32 s81, 0, 0x10000
	s_and_b64 s[10:11], s[52:53], exec
	s_cselect_b32 s63, s43, s54
	s_cselect_b32 s62, s94, s4
	s_add_i32 s10, 0, 0x14000
	s_add_u32 s36, s36, 0x90080
	s_addc_u32 s37, s37, 0
	s_add_i32 s86, s81, s8
	s_add_i32 m0, s9, 0xc000
	s_add_i32 s13, s9, 0xe000
	s_add_i32 s12, s86, 0x2000
	v_add_u32_e32 v130, s81, v157
	s_add_u32 vcc_lo, s62, 0x10000
	ds_read_b128 v[160:163], v130
	ds_read_b128 v[164:167], v130 offset:1024
	ds_read_b128 v[168:171], v130 offset:2048
	ds_read_b128 v[186:189], v130 offset:3072
	v_add_u32_e32 v130, s10, v157
	s_addc_u32 vcc_hi, s63, 0
	s_add_i32 s93, s10, s8
	ds_read_b128 v[190:193], v130
	ds_read_b128 v[198:201], v130 offset:1024
	ds_read_b128 v[202:205], v130 offset:2048
	ds_read_b128 v[206:209], v130 offset:3072
	s_add_i32 s92, s93, 0x2000
	s_add_i32 s95, 0, 0x18000
	s_add_i32 s85, 0, 0x1c000
	s_add_u32 s54, s56, 0x90000
	s_addc_u32 s55, s57, 0
	s_add_i32 s4, s95, s8
	s_add_i32 s87, s4, 0x2000
	s_add_u32 s52, s62, 0x10080
	s_addc_u32 s53, s63, 0
	s_add_i32 s11, s85, s8
	s_add_i32 s10, s11, 0x2000
	v_lshl_add_u64 v[130:131], s[36:37], 0, v[154:155]
	ds_read_b128 v[210:213], v159
	ds_read_b128 v[214:217], v159 offset:1024
	ds_read_b128 v[218:221], v159 offset:2048
	ds_read_b128 v[222:225], v159 offset:3072
	ds_read_b128 v[226:229], v159 offset:4096
	ds_read_b128 v[230:233], v159 offset:5120
	ds_read_b128 v[234:237], v159 offset:6144
	ds_read_b128 v[238:241], v159 offset:7168
	global_load_lds_dwordx4 v[130:131], off
	v_lshl_add_u64 v[130:131], s[36:37], 0, v[152:153]
	s_mov_b32 m0, s13
	s_nop 0
	global_load_lds_dwordx4 v[130:131], off
	s_waitcnt vmcnt(8)
	s_waitcnt lgkmcnt(0)
	s_barrier
	s_setprio 1
	v_mfma_f32_16x16x32_bf16 v[126:129], v[160:163], v[210:213], v[126:129]
	v_mfma_f32_16x16x32_bf16 v[122:125], v[168:171], v[210:213], v[122:125]
	v_mfma_f32_16x16x32_bf16 v[118:121], v[160:163], v[218:221], v[118:121]
	v_mfma_f32_16x16x32_bf16 v[114:117], v[168:171], v[218:221], v[114:117]
	v_mfma_f32_16x16x32_bf16 v[102:105], v[160:163], v[226:229], v[102:105]
	v_mfma_f32_16x16x32_bf16 v[98:101], v[168:171], v[226:229], v[98:101]
	v_mfma_f32_16x16x32_bf16 v[86:89], v[160:163], v[234:237], v[86:89]
	v_mfma_f32_16x16x32_bf16 v[82:85], v[168:171], v[234:237], v[82:85]
	v_mfma_f32_16x16x32_bf16 v[126:129], v[164:167], v[214:217], v[126:129]
	v_mfma_f32_16x16x32_bf16 v[122:125], v[186:189], v[214:217], v[122:125]
	v_mfma_f32_16x16x32_bf16 v[118:121], v[164:167], v[222:225], v[118:121]
	v_mfma_f32_16x16x32_bf16 v[114:117], v[186:189], v[222:225], v[114:117]
	v_mfma_f32_16x16x32_bf16 v[102:105], v[164:167], v[230:233], v[102:105]
	v_mfma_f32_16x16x32_bf16 v[98:101], v[186:189], v[230:233], v[98:101]
	v_mfma_f32_16x16x32_bf16 v[86:89], v[164:167], v[238:241], v[86:89]
	v_mfma_f32_16x16x32_bf16 v[82:85], v[186:189], v[238:241], v[82:85]
	s_setprio 0
	s_setprio 1
	v_mfma_f32_16x16x32_bf16 v[110:113], v[190:193], v[210:213], v[110:113]
	v_mfma_f32_16x16x32_bf16 v[106:109], v[202:205], v[210:213], v[106:109]
	v_mfma_f32_16x16x32_bf16 v[94:97], v[190:193], v[218:221], v[94:97]
	v_mfma_f32_16x16x32_bf16 v[90:93], v[202:205], v[218:221], v[90:93]
	v_mfma_f32_16x16x32_bf16 v[78:81], v[190:193], v[226:229], v[78:81]
	v_mfma_f32_16x16x32_bf16 v[74:77], v[202:205], v[226:229], v[74:77]
	v_mfma_f32_16x16x32_bf16 v[70:73], v[190:193], v[234:237], v[70:73]
	v_mfma_f32_16x16x32_bf16 v[66:69], v[202:205], v[234:237], v[66:69]
	v_mfma_f32_16x16x32_bf16 v[110:113], v[198:201], v[214:217], v[110:113]
	v_mfma_f32_16x16x32_bf16 v[106:109], v[206:209], v[214:217], v[106:109]
	v_mfma_f32_16x16x32_bf16 v[94:97], v[198:201], v[222:225], v[94:97]
	v_mfma_f32_16x16x32_bf16 v[90:93], v[206:209], v[222:225], v[90:93]
	v_mfma_f32_16x16x32_bf16 v[78:81], v[198:201], v[230:233], v[78:81]
	v_mfma_f32_16x16x32_bf16 v[74:77], v[206:209], v[230:233], v[74:77]
	v_mfma_f32_16x16x32_bf16 v[70:73], v[198:201], v[238:241], v[70:73]
	v_mfma_f32_16x16x32_bf16 v[66:69], v[206:209], v[238:241], v[66:69]
	s_setprio 0
	s_barrier
	s_mov_b32 m0, s86
	v_lshl_add_u64 v[130:131], s[62:63], 0, v[0:1]
	ds_read_b128 v[210:213], v159 offset:16384
	ds_read_b128 v[214:217], v159 offset:17408
	ds_read_b128 v[218:221], v159 offset:18432
	ds_read_b128 v[222:225], v159 offset:19456
	ds_read_b128 v[226:229], v159 offset:20480
	ds_read_b128 v[230:233], v159 offset:21504
	ds_read_b128 v[234:237], v159 offset:22528
	ds_read_b128 v[238:241], v159 offset:23552
	global_load_lds_dwordx4 v[130:131], off
	v_lshl_add_u64 v[132:133], s[62:63], 0, v[150:151]
	s_mov_b32 m0, s12
	v_lshl_add_u64 v[172:173], vcc, 0, v[0:1]
	global_load_lds_dwordx4 v[132:133], off
	s_mov_b32 m0, s93
	v_lshl_add_u64 v[242:243], s[56:57], 0, v[152:153]
	global_load_lds_dwordx4 v[172:173], off
	v_lshl_add_u64 v[172:173], vcc, 0, v[150:151]
	s_mov_b32 m0, s92
	s_nop 0
	global_load_lds_dwordx4 v[172:173], off
	v_lshl_add_u64 v[172:173], s[56:57], 0, v[154:155]
	s_mov_b32 m0, s9
	s_nop 0
	global_load_lds_dwordx4 v[172:173], off
	s_mov_b32 m0, s30
	s_nop 0
	global_load_lds_dwordx4 v[242:243], off
	s_waitcnt vmcnt(8)
	s_waitcnt lgkmcnt(0)
	s_barrier
; #define PG8_STAGE(bufoff, gbase, voff) do { _Pragma("unroll") for (int _i = 0; _i < 2; ++_i) \
;         __builtin_amdgcn_global_load_lds((const unsigned*)((const char*)(gbase) + (voff)[_i]), (PG8_LAS unsigned*)(lds + (bufoff) + ldsw + _i * 8192), 16, 0, 0); } while (0)
; #define PG8_LDA(dst, b, h) do { _Pragma("unroll") for (int m = 0; m < 4; ++m) _Pragma("unroll") for (int k = 0; k < 2; ++k) dst[m][k] = *(const PG8_LAS bf16x8*)(lds + PG8_SA(b, h) + aoff + m * 2048 + k * 1024); } while (0)
; #define PG8_LDB(dst, b, h) do { _Pragma("unroll") for (int n = 0; n < 2; ++n) _Pragma("unroll") for (int k = 0; k < 2; ++k) dst[n][k] = *(const PG8_LAS bf16x8*)(lds + PG8_SB(b, h) + boff + n * 2048 + k * 1024); } while (0)
; #define PG8_MMA(ai, bj, At, Bt) do { __builtin_amdgcn_s_setprio(1); _Pragma("unroll") for (int m = 0; m < 4; ++m) _Pragma("unroll") for (int n = 0; n < 2; ++n) _Pragma("unroll") for (int k = 0; k < 2; ++k) \
;         acc[ai][bj][m][n] = __builtin_amdgcn_mfma_f32_16x16x32_bf16(Bt[n][k], At[m][k], acc[ai][bj][m][n], 0, 0, 0); __builtin_amdgcn_s_setprio(0); } while (0)
; #define PG8_WAIT_V(n) asm volatile("s_waitcnt vmcnt(" #n ")" ::: "memory")
; #define PG8_WAIT_L(n) asm volatile("s_waitcnt lgkmcnt(" #n ")" ::: "memory")
; #define PG8_BAR __builtin_amdgcn_s_barrier()
; #define PG8_SCHED __builtin_amdgcn_sched_barrier(0)
; template <class Epi, class Sched, bool ALIGN_EPI = false, bool SP2 = false>
; __device__ __forceinline__ void gemm_phase(PG8_LAS unsigned char* lds, const Gemm g, const Sched& S, const Epi& E) {
;     ...
;             PG8_WAIT_V(8); PG8_WAIT_L(0); PG8_BAR; PG8_MMA(1, 0, At, B0); PG8_MMA(1, 1, At, B1); PG8_BAR; PG8_SCHED;
;             PG8_LDB(B0, 1, 0); PG8_LDB(B1, 1, 1); PG8_SCHED; PG8_LDA(At, 1, 0); PG8_STAGE(PG8_SA(0, 1), a2 + hstepA, voffA);
;             PG8_WAIT_V(8); PG8_WAIT_L(0); PG8_BAR; PG8_MMA(0, 0, At, B0); PG8_MMA(0, 1, At, B1); PG8_BAR; PG8_SCHED;
	s_setprio 1
	v_mfma_f32_16x16x32_bf16 v[62:65], v[160:163], v[210:213], v[62:65]
	v_mfma_f32_16x16x32_bf16 v[58:61], v[168:171], v[210:213], v[58:61]
	v_mfma_f32_16x16x32_bf16 v[54:57], v[160:163], v[218:221], v[54:57]
	v_mfma_f32_16x16x32_bf16 v[50:53], v[168:171], v[218:221], v[50:53]
	v_mfma_f32_16x16x32_bf16 v[38:41], v[160:163], v[226:229], v[38:41]
	v_mfma_f32_16x16x32_bf16 v[34:37], v[168:171], v[226:229], v[34:37]
	v_mfma_f32_16x16x32_bf16 v[22:25], v[160:163], v[234:237], v[22:25]
	v_mfma_f32_16x16x32_bf16 v[18:21], v[168:171], v[234:237], v[18:21]
	v_mfma_f32_16x16x32_bf16 v[62:65], v[164:167], v[214:217], v[62:65]
	v_mfma_f32_16x16x32_bf16 v[58:61], v[186:189], v[214:217], v[58:61]
	v_mfma_f32_16x16x32_bf16 v[54:57], v[164:167], v[222:225], v[54:57]
	v_mfma_f32_16x16x32_bf16 v[50:53], v[186:189], v[222:225], v[50:53]
	v_mfma_f32_16x16x32_bf16 v[38:41], v[164:167], v[230:233], v[38:41]
	v_mfma_f32_16x16x32_bf16 v[34:37], v[186:189], v[230:233], v[34:37]
	v_mfma_f32_16x16x32_bf16 v[22:25], v[164:167], v[238:241], v[22:25]
	v_mfma_f32_16x16x32_bf16 v[18:21], v[186:189], v[238:241], v[18:21]
	s_setprio 0
	s_setprio 1
	v_mfma_f32_16x16x32_bf16 v[46:49], v[190:193], v[210:213], v[46:49]
	v_mfma_f32_16x16x32_bf16 v[42:45], v[202:205], v[210:213], v[42:45]
	v_mfma_f32_16x16x32_bf16 v[30:33], v[190:193], v[218:221], v[30:33]
	v_mfma_f32_16x16x32_bf16 v[26:29], v[202:205], v[218:221], v[26:29]
	v_mfma_f32_16x16x32_bf16 v[14:17], v[190:193], v[226:229], v[14:17]
	v_mfma_f32_16x16x32_bf16 v[10:13], v[202:205], v[226:229], v[10:13]
	v_mfma_f32_16x16x32_bf16 v[6:9], v[190:193], v[234:237], v[6:9]
	v_mfma_f32_16x16x32_bf16 v[2:5], v[202:205], v[234:237], v[2:5]
	v_mfma_f32_16x16x32_bf16 v[46:49], v[198:201], v[214:217], v[46:49]
	v_mfma_f32_16x16x32_bf16 v[42:45], v[206:209], v[214:217], v[42:45]
	v_mfma_f32_16x16x32_bf16 v[30:33], v[198:201], v[222:225], v[30:33]
	v_mfma_f32_16x16x32_bf16 v[26:29], v[206:209], v[222:225], v[26:29]
	v_mfma_f32_16x16x32_bf16 v[14:17], v[198:201], v[230:233], v[14:17]
	v_mfma_f32_16x16x32_bf16 v[10:13], v[206:209], v[230:233], v[10:13]
	v_mfma_f32_16x16x32_bf16 v[6:9], v[198:201], v[238:241], v[6:9]
	v_mfma_f32_16x16x32_bf16 v[2:5], v[206:209], v[238:241], v[2:5]
	s_setprio 0
	s_barrier
	v_add_u32_e32 v186, s95, v157
	v_add_u32_e32 v206, s85, v157
	ds_read_b128 v[160:163], v186
	ds_read_b128 v[164:167], v186 offset:1024
	ds_read_b128 v[168:171], v186 offset:2048
	ds_read_b128 v[186:189], v186 offset:3072
	ds_read_b128 v[190:193], v206
	ds_read_b128 v[198:201], v206 offset:1024
	ds_read_b128 v[202:205], v206 offset:2048
	ds_read_b128 v[206:209], v206 offset:3072
	s_mov_b32 m0, s31
	v_lshl_add_u64 v[244:245], s[54:55], 0, v[154:155]
	ds_read_b128 v[210:213], v159 offset:32768
	ds_read_b128 v[214:217], v159 offset:33792
	ds_read_b128 v[218:221], v159 offset:34816
	ds_read_b128 v[222:225], v159 offset:35840
	ds_read_b128 v[226:229], v159 offset:36864
	ds_read_b128 v[230:233], v159 offset:37888
	ds_read_b128 v[234:237], v159 offset:38912
	ds_read_b128 v[238:241], v159 offset:39936
	global_load_lds_dwordx4 v[244:245], off
	v_lshl_add_u64 v[244:245], s[54:55], 0, v[152:153]
	s_mov_b32 m0, s34
	s_nop 0
	global_load_lds_dwordx4 v[244:245], off
	s_waitcnt vmcnt(8)
	s_waitcnt lgkmcnt(0)
	s_barrier
	s_setprio 1
	v_mfma_f32_16x16x32_bf16 v[126:129], v[160:163], v[210:213], v[126:129]
	v_mfma_f32_16x16x32_bf16 v[122:125], v[168:171], v[210:213], v[122:125]
	v_mfma_f32_16x16x32_bf16 v[118:121], v[160:163], v[218:221], v[118:121]
	v_mfma_f32_16x16x32_bf16 v[114:117], v[168:171], v[218:221], v[114:117]
	v_mfma_f32_16x16x32_bf16 v[102:105], v[160:163], v[226:229], v[102:105]
	v_mfma_f32_16x16x32_bf16 v[98:101], v[168:171], v[226:229], v[98:101]
	v_mfma_f32_16x16x32_bf16 v[86:89], v[160:163], v[234:237], v[86:89]
	v_mfma_f32_16x16x32_bf16 v[82:85], v[168:171], v[234:237], v[82:85]
	v_mfma_f32_16x16x32_bf16 v[126:129], v[164:167], v[214:217], v[126:129]
	v_mfma_f32_16x16x32_bf16 v[122:125], v[186:189], v[214:217], v[122:125]
	v_mfma_f32_16x16x32_bf16 v[118:121], v[164:167], v[222:225], v[118:121]
	v_mfma_f32_16x16x32_bf16 v[114:117], v[186:189], v[222:225], v[114:117]
	v_mfma_f32_16x16x32_bf16 v[102:105], v[164:167], v[230:233], v[102:105]
	v_mfma_f32_16x16x32_bf16 v[98:101], v[186:189], v[230:233], v[98:101]
	v_mfma_f32_16x16x32_bf16 v[86:89], v[164:167], v[238:241], v[86:89]
	v_mfma_f32_16x16x32_bf16 v[82:85], v[186:189], v[238:241], v[82:85]
	s_setprio 0
	s_setprio 1
	v_mfma_f32_16x16x32_bf16 v[110:113], v[190:193], v[210:213], v[110:113]
	v_mfma_f32_16x16x32_bf16 v[106:109], v[202:205], v[210:213], v[106:109]
	v_mfma_f32_16x16x32_bf16 v[94:97], v[190:193], v[218:221], v[94:97]
	v_mfma_f32_16x16x32_bf16 v[90:93], v[202:205], v[218:221], v[90:93]
	v_mfma_f32_16x16x32_bf16 v[78:81], v[190:193], v[226:229], v[78:81]
	v_mfma_f32_16x16x32_bf16 v[74:77], v[202:205], v[226:229], v[74:77]
	v_mfma_f32_16x16x32_bf16 v[70:73], v[190:193], v[234:237], v[70:73]
	v_mfma_f32_16x16x32_bf16 v[66:69], v[202:205], v[234:237], v[66:69]
	v_mfma_f32_16x16x32_bf16 v[110:113], v[198:201], v[214:217], v[110:113]
	v_mfma_f32_16x16x32_bf16 v[106:109], v[206:209], v[214:217], v[106:109]
	v_mfma_f32_16x16x32_bf16 v[94:97], v[198:201], v[222:225], v[94:97]
	v_mfma_f32_16x16x32_bf16 v[90:93], v[206:209], v[222:225], v[90:93]
	v_mfma_f32_16x16x32_bf16 v[78:81], v[198:201], v[230:233], v[78:81]
	v_mfma_f32_16x16x32_bf16 v[74:77], v[206:209], v[230:233], v[74:77]
	v_mfma_f32_16x16x32_bf16 v[70:73], v[198:201], v[238:241], v[70:73]
	v_mfma_f32_16x16x32_bf16 v[66:69], v[206:209], v[238:241], v[66:69]
	s_setprio 0
	s_barrier
; #define PG8_STAGE(bufoff, gbase, voff) do { _Pragma("unroll") for (int _i = 0; _i < 2; ++_i) \
;         __builtin_amdgcn_global_load_lds((const unsigned*)((const char*)(gbase) + (voff)[_i]), (PG8_LAS unsigned*)(lds + (bufoff) + ldsw + _i * 8192), 16, 0, 0); } while (0)
; #define PG8_LDA(dst, b, h) do { _Pragma("unroll") for (int m = 0; m < 4; ++m) _Pragma("unroll") for (int k = 0; k < 2; ++k) dst[m][k] = *(const PG8_LAS bf16x8*)(lds + PG8_SA(b, h) + aoff + m * 2048 + k * 1024); } while (0)
; #define PG8_MMA(ai, bj, At, Bt) do { __builtin_amdgcn_s_setprio(1); _Pragma("unroll") for (int m = 0; m < 4; ++m) _Pragma("unroll") for (int n = 0; n < 2; ++n) _Pragma("unroll") for (int k = 0; k < 2; ++k) \
;         acc[ai][bj][m][n] = __builtin_amdgcn_mfma_f32_16x16x32_bf16(Bt[n][k], At[m][k], acc[ai][bj][m][n], 0, 0, 0); __builtin_amdgcn_s_setprio(0); } while (0)
; #define PG8_WAIT_V(n) asm volatile("s_waitcnt vmcnt(" #n ")" ::: "memory")
; #define PG8_WAIT_L(n) asm volatile("s_waitcnt lgkmcnt(" #n ")" ::: "memory")
; #define PG8_BAR __builtin_amdgcn_s_barrier()
; #define PG8_SCHED __builtin_amdgcn_sched_barrier(0)
; template <class Epi, class Sched, bool ALIGN_EPI = false, bool SP2 = false>
; __device__ __forceinline__ void gemm_phase(PG8_LAS unsigned char* lds, const Gemm g, const Sched& S, const Epi& E) {
;     ...
;             PG8_LDA(At, 1, 1); PG8_STAGE(PG8_SB(1, 0), b3, voffB); PG8_STAGE(PG8_SB(1, 1), b3 + hstepB, voffB); PG8_STAGE(PG8_SA(1, 0), a3, voffA);
;             PG8_WAIT_V(8); PG8_WAIT_L(0); PG8_BAR; PG8_MMA(1, 0, At, B0); PG8_MMA(1, 1, At, B1); PG8_BAR; PG8_SCHED;
;     ...
;         if constexpr (ALIGN_EPI) { if (wr == 0) PG8_BAR; }
	s_mov_b32 m0, s4
	v_lshl_add_u64 v[130:131], v[130:131], 0, s[2:3]
	ds_read_b128 v[210:213], v159 offset:49152
	ds_read_b128 v[214:217], v159 offset:50176
	ds_read_b128 v[218:221], v159 offset:51200
	ds_read_b128 v[222:225], v159 offset:52224
	ds_read_b128 v[226:229], v159 offset:53248
	ds_read_b128 v[230:233], v159 offset:54272
	ds_read_b128 v[234:237], v159 offset:55296
	ds_read_b128 v[238:241], v159 offset:56320
	global_load_lds_dwordx4 v[130:131], off
	v_lshl_add_u64 v[130:131], v[132:133], 0, s[2:3]
	s_mov_b32 m0, s87
	s_nop 0
	global_load_lds_dwordx4 v[130:131], off
	v_lshl_add_u64 v[130:131], s[52:53], 0, v[0:1]
	s_mov_b32 m0, s11
	s_nop 0
	global_load_lds_dwordx4 v[130:131], off
	v_lshl_add_u64 v[130:131], s[52:53], 0, v[150:151]
	s_mov_b32 m0, s10
	s_nop 0
	global_load_lds_dwordx4 v[130:131], off
	v_lshl_add_u64 v[130:131], v[172:173], 0, s[2:3]
	s_mov_b32 m0, s35
	s_nop 0
	global_load_lds_dwordx4 v[130:131], off
	v_lshl_add_u64 v[130:131], v[242:243], 0, s[2:3]
	s_mov_b32 m0, s68
	s_nop 0
	global_load_lds_dwordx4 v[130:131], off
	s_waitcnt vmcnt(8)
	s_waitcnt lgkmcnt(0)
	s_barrier
	s_setprio 1
	v_mfma_f32_16x16x32_bf16 v[62:65], v[160:163], v[210:213], v[62:65]
	v_mfma_f32_16x16x32_bf16 v[58:61], v[168:171], v[210:213], v[58:61]
	v_mfma_f32_16x16x32_bf16 v[54:57], v[160:163], v[218:221], v[54:57]
	v_mfma_f32_16x16x32_bf16 v[50:53], v[168:171], v[218:221], v[50:53]
	v_mfma_f32_16x16x32_bf16 v[38:41], v[160:163], v[226:229], v[38:41]
	v_mfma_f32_16x16x32_bf16 v[34:37], v[168:171], v[226:229], v[34:37]
	v_mfma_f32_16x16x32_bf16 v[22:25], v[160:163], v[234:237], v[22:25]
	v_mfma_f32_16x16x32_bf16 v[18:21], v[168:171], v[234:237], v[18:21]
	v_mfma_f32_16x16x32_bf16 v[62:65], v[164:167], v[214:217], v[62:65]
	v_mfma_f32_16x16x32_bf16 v[58:61], v[186:189], v[214:217], v[58:61]
	v_mfma_f32_16x16x32_bf16 v[54:57], v[164:167], v[222:225], v[54:57]
	v_mfma_f32_16x16x32_bf16 v[50:53], v[186:189], v[222:225], v[50:53]
	v_mfma_f32_16x16x32_bf16 v[38:41], v[164:167], v[230:233], v[38:41]
	v_mfma_f32_16x16x32_bf16 v[34:37], v[186:189], v[230:233], v[34:37]
	v_mfma_f32_16x16x32_bf16 v[22:25], v[164:167], v[238:241], v[22:25]
	v_mfma_f32_16x16x32_bf16 v[18:21], v[186:189], v[238:241], v[18:21]
	s_setprio 0
	s_setprio 1
	v_mfma_f32_16x16x32_bf16 v[46:49], v[190:193], v[210:213], v[46:49]
	v_mfma_f32_16x16x32_bf16 v[42:45], v[202:205], v[210:213], v[42:45]
	v_mfma_f32_16x16x32_bf16 v[30:33], v[190:193], v[218:221], v[30:33]
	v_mfma_f32_16x16x32_bf16 v[26:29], v[202:205], v[218:221], v[26:29]
	v_mfma_f32_16x16x32_bf16 v[14:17], v[190:193], v[226:229], v[14:17]
	v_mfma_f32_16x16x32_bf16 v[10:13], v[202:205], v[226:229], v[10:13]
	v_mfma_f32_16x16x32_bf16 v[6:9], v[190:193], v[234:237], v[6:9]
	v_mfma_f32_16x16x32_bf16 v[2:5], v[202:205], v[234:237], v[2:5]
	v_mfma_f32_16x16x32_bf16 v[46:49], v[198:201], v[214:217], v[46:49]
	v_mfma_f32_16x16x32_bf16 v[42:45], v[206:209], v[214:217], v[42:45]
	v_mfma_f32_16x16x32_bf16 v[30:33], v[198:201], v[222:225], v[30:33]
	v_mfma_f32_16x16x32_bf16 v[26:29], v[206:209], v[222:225], v[26:29]
	v_mfma_f32_16x16x32_bf16 v[14:17], v[198:201], v[230:233], v[14:17]
	v_mfma_f32_16x16x32_bf16 v[10:13], v[206:209], v[230:233], v[10:13]
	v_mfma_f32_16x16x32_bf16 v[6:9], v[198:201], v[238:241], v[6:9]
	v_mfma_f32_16x16x32_bf16 v[2:5], v[206:209], v[238:241], v[2:5]
	s_setprio 0
	s_barrier
	s_movk_i32 s4, 0x100
	s_andn2_b64 vcc, exec, s[0:1]
	s_mov_b64 s[52:53], -1
	s_mov_b64 s[0:1], 0
	s_cbranch_vccz .LBB0_380
	s_and_b64 vcc, exec, s[40:41]
	s_cbranch_vccz .LBB0_383
	s_barrier

; #define PG8_STAGE(bufoff, gbase, voff) do { _Pragma("unroll") for (int _i = 0; _i < 2; ++_i) \
;         __builtin_amdgcn_global_load_lds((const unsigned*)((const char*)(gbase) + (voff)[_i]), (PG8_LAS unsigned*)(lds + (bufoff) + ldsw + _i * 8192), 16, 0, 0); } while (0)
; #define PG8_LDA(dst, b, h) do { _Pragma("unroll") for (int m = 0; m < 4; ++m) _Pragma("unroll") for (int k = 0; k < 2; ++k) dst[m][k] = *(const PG8_LAS bf16x8*)(lds + PG8_SA(b, h) + aoff + m * 2048 + k * 1024); } while (0)
; #define PG8_LDB(dst, b, h) do { _Pragma("unroll") for (int n = 0; n < 2; ++n) _Pragma("unroll") for (int k = 0; k < 2; ++k) dst[n][k] = *(const PG8_LAS bf16x8*)(lds + PG8_SB(b, h) + boff + n * 2048 + k * 1024); } while (0)
; #define PG8_MMA(ai, bj, At, Bt) do { __builtin_amdgcn_s_setprio(1); _Pragma("unroll") for (int m = 0; m < 4; ++m) _Pragma("unroll") for (int n = 0; n < 2; ++n) _Pragma("unroll") for (int k = 0; k < 2; ++k) \
;         acc[ai][bj][m][n] = __builtin_amdgcn_mfma_f32_16x16x32_bf16(Bt[n][k], At[m][k], acc[ai][bj][m][n], 0, 0, 0); __builtin_amdgcn_s_setprio(0); } while (0)
; #define PG8_WAIT_V(n) asm volatile("s_waitcnt vmcnt(" #n ")" ::: "memory")
; #define PG8_WAIT_L(n) asm volatile("s_waitcnt lgkmcnt(" #n ")" ::: "memory")
; template <class Epi, class Sched, bool ALIGN_EPI = false, bool SP2 = false>
; __device__ __forceinline__ void gemm_phase(PG8_LAS unsigned char* lds, const Gemm g, const Sched& S, const Epi& E) {
;     ...
;             const bool last = (t == nt - 2);
;             const char* a1 = cA + (size_t)(t + 1) * kstep;
;             const char* a2 = last ? nA : cA + (size_t)(t + 2) * kstep; const char* b2 = last ? nB : cB + (size_t)(t + 2) * kstep;
;             const char* a3 = a2 + kstep; const char* b3 = b2 + kstep;
;             if (last && has_next) S.a_ready(nxt);
;             if constexpr (SP2) {
;             PG8_LDB(B0, 0, 0); PG8_LDB(B1, 0, 1); PG8_SCHED; PG8_LDA(At, 0, 0); PG8_STAGE(PG8_SA(1, 1), a1 + hstepA, voffA);
;             PG8_WAIT_V(8); PG8_WAIT_L(0); PG8_BAR; PG8_MMA(0, 0, At, B0); PG8_MMA(0, 1, At, B1); PG8_BAR; PG8_SCHED;
;             PG8_LDA(At, 0, 1); PG8_STAGE(PG8_SB(0, 0), b2, voffB); PG8_STAGE(PG8_SB(0, 1), b2 + hstepB, voffB); PG8_STAGE(PG8_SA(0, 0), a2, voffA);
;             PG8_WAIT_V(8); PG8_WAIT_L(0); PG8_BAR; PG8_MMA(1, 0, At, B0); PG8_MMA(1, 1, At, B1); PG8_BAR; PG8_SCHED;
.LBB0_402:
	s_add_u32 s12, s52, s4
	s_addc_u32 s13, s53, 0
	s_add_u32 s36, s12, 0x100
	s_addc_u32 s37, s13, 0
	s_and_b64 s[10:11], s[54:55], exec
	s_cselect_b32 s63, s47, s37
	s_cselect_b32 s62, s46, s36
	s_add_u32 s4, s50, s4
	s_addc_u32 s10, s51, 0
	s_add_u32 s4, s4, 0x100
	s_addc_u32 s36, s10, 0
	s_add_i32 s86, 0, 0x10000
	s_and_b64 s[10:11], s[54:55], exec
	s_cselect_b32 vcc_hi, s45, s36
	s_cselect_b32 vcc_lo, s38, s4
	s_add_i32 s10, 0, 0x14000
	s_add_u32 s68, s12, 0x90080
	s_addc_u32 s69, s13, 0
	s_add_i32 s12, s86, s8
	s_add_i32 m0, s9, 0xc000
	s_add_i32 s13, s9, 0xe000
	s_add_i32 s81, s12, 0x2000
	v_add_u32_e32 v130, s86, v157
	s_add_u32 s36, vcc_lo, 0x10000
	ds_read_b128 v[160:163], v130
	ds_read_b128 v[164:167], v130 offset:1024
	ds_read_b128 v[168:171], v130 offset:2048
	ds_read_b128 v[186:189], v130 offset:3072
	v_add_u32_e32 v130, s10, v157
	s_addc_u32 s37, vcc_hi, 0
	s_add_i32 s93, s10, s8
	ds_read_b128 v[190:193], v130
	ds_read_b128 v[198:201], v130 offset:1024
	ds_read_b128 v[202:205], v130 offset:2048
	ds_read_b128 v[206:209], v130 offset:3072
	s_add_i32 s92, s93, 0x2000
	s_add_i32 s87, 0, 0x18000
	s_add_i32 s85, 0, 0x1c000
	s_add_u32 s56, s62, 0x90000
	s_addc_u32 s57, s63, 0
	s_add_i32 s39, s87, s8
	s_add_i32 s4, s39, 0x2000
	s_add_u32 s54, vcc_lo, 0x10080
	s_addc_u32 s55, vcc_hi, 0
	s_add_i32 s11, s85, s8
	s_add_i32 s10, s11, 0x2000
	v_lshl_add_u64 v[130:131], s[68:69], 0, v[154:155]
	ds_read_b128 v[210:213], v159
	ds_read_b128 v[214:217], v159 offset:1024
	ds_read_b128 v[218:221], v159 offset:2048
	ds_read_b128 v[222:225], v159 offset:3072
	ds_read_b128 v[226:229], v159 offset:4096
	ds_read_b128 v[230:233], v159 offset:5120
	ds_read_b128 v[234:237], v159 offset:6144
	ds_read_b128 v[238:241], v159 offset:7168
	global_load_lds_dwordx4 v[130:131], off
	v_lshl_add_u64 v[130:131], s[68:69], 0, v[152:153]
	s_mov_b32 m0, s13
	s_nop 0
	global_load_lds_dwordx4 v[130:131], off
	s_waitcnt vmcnt(8)
	s_waitcnt lgkmcnt(0)
	s_barrier
	s_setprio 1
	v_mfma_f32_16x16x32_bf16 v[126:129], v[160:163], v[210:213], v[126:129]
	v_mfma_f32_16x16x32_bf16 v[122:125], v[168:171], v[210:213], v[122:125]
	v_mfma_f32_16x16x32_bf16 v[118:121], v[160:163], v[218:221], v[118:121]
	v_mfma_f32_16x16x32_bf16 v[114:117], v[168:171], v[218:221], v[114:117]
	v_mfma_f32_16x16x32_bf16 v[102:105], v[160:163], v[226:229], v[102:105]
	v_mfma_f32_16x16x32_bf16 v[98:101], v[168:171], v[226:229], v[98:101]
	v_mfma_f32_16x16x32_bf16 v[86:89], v[160:163], v[234:237], v[86:89]
	v_mfma_f32_16x16x32_bf16 v[82:85], v[168:171], v[234:237], v[82:85]
	v_mfma_f32_16x16x32_bf16 v[126:129], v[164:167], v[214:217], v[126:129]
	v_mfma_f32_16x16x32_bf16 v[122:125], v[186:189], v[214:217], v[122:125]
	v_mfma_f32_16x16x32_bf16 v[118:121], v[164:167], v[222:225], v[118:121]
	v_mfma_f32_16x16x32_bf16 v[114:117], v[186:189], v[222:225], v[114:117]
	v_mfma_f32_16x16x32_bf16 v[102:105], v[164:167], v[230:233], v[102:105]
	v_mfma_f32_16x16x32_bf16 v[98:101], v[186:189], v[230:233], v[98:101]
	v_mfma_f32_16x16x32_bf16 v[86:89], v[164:167], v[238:241], v[86:89]
	v_mfma_f32_16x16x32_bf16 v[82:85], v[186:189], v[238:241], v[82:85]
	s_setprio 0
	s_setprio 1
	v_mfma_f32_16x16x32_bf16 v[110:113], v[190:193], v[210:213], v[110:113]
	v_mfma_f32_16x16x32_bf16 v[106:109], v[202:205], v[210:213], v[106:109]
	v_mfma_f32_16x16x32_bf16 v[94:97], v[190:193], v[218:221], v[94:97]
	v_mfma_f32_16x16x32_bf16 v[90:93], v[202:205], v[218:221], v[90:93]
	v_mfma_f32_16x16x32_bf16 v[78:81], v[190:193], v[226:229], v[78:81]
	v_mfma_f32_16x16x32_bf16 v[74:77], v[202:205], v[226:229], v[74:77]
	v_mfma_f32_16x16x32_bf16 v[70:73], v[190:193], v[234:237], v[70:73]
	v_mfma_f32_16x16x32_bf16 v[66:69], v[202:205], v[234:237], v[66:69]
	v_mfma_f32_16x16x32_bf16 v[110:113], v[198:201], v[214:217], v[110:113]
	v_mfma_f32_16x16x32_bf16 v[106:109], v[206:209], v[214:217], v[106:109]
	v_mfma_f32_16x16x32_bf16 v[94:97], v[198:201], v[222:225], v[94:97]
	v_mfma_f32_16x16x32_bf16 v[90:93], v[206:209], v[222:225], v[90:93]
	v_mfma_f32_16x16x32_bf16 v[78:81], v[198:201], v[230:233], v[78:81]
	v_mfma_f32_16x16x32_bf16 v[74:77], v[206:209], v[230:233], v[74:77]
	v_mfma_f32_16x16x32_bf16 v[70:73], v[198:201], v[238:241], v[70:73]
	v_mfma_f32_16x16x32_bf16 v[66:69], v[206:209], v[238:241], v[66:69]
	s_setprio 0
	s_barrier
	s_mov_b32 m0, s12
	v_lshl_add_u64 v[130:131], vcc, 0, v[0:1]
	ds_read_b128 v[210:213], v159 offset:16384
	ds_read_b128 v[214:217], v159 offset:17408
	ds_read_b128 v[218:221], v159 offset:18432
	ds_read_b128 v[222:225], v159 offset:19456
	ds_read_b128 v[226:229], v159 offset:20480
	ds_read_b128 v[230:233], v159 offset:21504
	ds_read_b128 v[234:237], v159 offset:22528
	ds_read_b128 v[238:241], v159 offset:23552
	global_load_lds_dwordx4 v[130:131], off
	v_lshl_add_u64 v[132:133], vcc, 0, v[150:151]
	s_mov_b32 m0, s81
	v_lshl_add_u64 v[172:173], s[36:37], 0, v[0:1]
	global_load_lds_dwordx4 v[132:133], off
	s_mov_b32 m0, s93
	v_lshl_add_u64 v[242:243], s[62:63], 0, v[152:153]
	global_load_lds_dwordx4 v[172:173], off
	v_lshl_add_u64 v[172:173], s[36:37], 0, v[150:151]
	s_mov_b32 m0, s92
	s_nop 0
	global_load_lds_dwordx4 v[172:173], off
	v_lshl_add_u64 v[172:173], s[62:63], 0, v[154:155]
	s_mov_b32 m0, s9
	s_nop 0
	global_load_lds_dwordx4 v[172:173], off
	s_mov_b32 m0, s30
	s_nop 0
	global_load_lds_dwordx4 v[242:243], off
	s_waitcnt vmcnt(8)
	s_waitcnt lgkmcnt(0)
	s_barrier
; #define PG8_STAGE(bufoff, gbase, voff) do { _Pragma("unroll") for (int _i = 0; _i < 2; ++_i) \
;         __builtin_amdgcn_global_load_lds((const unsigned*)((const char*)(gbase) + (voff)[_i]), (PG8_LAS unsigned*)(lds + (bufoff) + ldsw + _i * 8192), 16, 0, 0); } while (0)
; #define PG8_LDA(dst, b, h) do { _Pragma("unroll") for (int m = 0; m < 4; ++m) _Pragma("unroll") for (int k = 0; k < 2; ++k) dst[m][k] = *(const PG8_LAS bf16x8*)(lds + PG8_SA(b, h) + aoff + m * 2048 + k * 1024); } while (0)
; #define PG8_LDB(dst, b, h) do { _Pragma("unroll") for (int n = 0; n < 2; ++n) _Pragma("unroll") for (int k = 0; k < 2; ++k) dst[n][k] = *(const PG8_LAS bf16x8*)(lds + PG8_SB(b, h) + boff + n * 2048 + k * 1024); } while (0)
; #define PG8_MMA(ai, bj, At, Bt) do { __builtin_amdgcn_s_setprio(1); _Pragma("unroll") for (int m = 0; m < 4; ++m) _Pragma("unroll") for (int n = 0; n < 2; ++n) _Pragma("unroll") for (int k = 0; k < 2; ++k) \
;         acc[ai][bj][m][n] = __builtin_amdgcn_mfma_f32_16x16x32_bf16(Bt[n][k], At[m][k], acc[ai][bj][m][n], 0, 0, 0); __builtin_amdgcn_s_setprio(0); } while (0)
; #define PG8_WAIT_V(n) asm volatile("s_waitcnt vmcnt(" #n ")" ::: "memory")
; #define PG8_WAIT_L(n) asm volatile("s_waitcnt lgkmcnt(" #n ")" ::: "memory")
; #define PG8_BAR __builtin_amdgcn_s_barrier()
; #define PG8_SCHED __builtin_amdgcn_sched_barrier(0)
; template <class Epi, class Sched, bool ALIGN_EPI = false, bool SP2 = false>
; __device__ __forceinline__ void gemm_phase(PG8_LAS unsigned char* lds, const Gemm g, const Sched& S, const Epi& E) {
;     ...
;             PG8_WAIT_V(8); PG8_WAIT_L(0); PG8_BAR; PG8_MMA(1, 0, At, B0); PG8_MMA(1, 1, At, B1); PG8_BAR; PG8_SCHED;
;             PG8_LDB(B0, 1, 0); PG8_LDB(B1, 1, 1); PG8_SCHED; PG8_LDA(At, 1, 0); PG8_STAGE(PG8_SA(0, 1), a2 + hstepA, voffA);
;             PG8_WAIT_V(8); PG8_WAIT_L(0); PG8_BAR; PG8_MMA(0, 0, At, B0); PG8_MMA(0, 1, At, B1); PG8_BAR; PG8_SCHED;
	s_setprio 1
	v_mfma_f32_16x16x32_bf16 v[62:65], v[160:163], v[210:213], v[62:65]
	v_mfma_f32_16x16x32_bf16 v[58:61], v[168:171], v[210:213], v[58:61]
	v_mfma_f32_16x16x32_bf16 v[54:57], v[160:163], v[218:221], v[54:57]
	v_mfma_f32_16x16x32_bf16 v[50:53], v[168:171], v[218:221], v[50:53]
	v_mfma_f32_16x16x32_bf16 v[38:41], v[160:163], v[226:229], v[38:41]
	v_mfma_f32_16x16x32_bf16 v[34:37], v[168:171], v[226:229], v[34:37]
	v_mfma_f32_16x16x32_bf16 v[22:25], v[160:163], v[234:237], v[22:25]
	v_mfma_f32_16x16x32_bf16 v[18:21], v[168:171], v[234:237], v[18:21]
	v_mfma_f32_16x16x32_bf16 v[62:65], v[164:167], v[214:217], v[62:65]
	v_mfma_f32_16x16x32_bf16 v[58:61], v[186:189], v[214:217], v[58:61]
	v_mfma_f32_16x16x32_bf16 v[54:57], v[164:167], v[222:225], v[54:57]
	v_mfma_f32_16x16x32_bf16 v[50:53], v[186:189], v[222:225], v[50:53]
	v_mfma_f32_16x16x32_bf16 v[38:41], v[164:167], v[230:233], v[38:41]
	v_mfma_f32_16x16x32_bf16 v[34:37], v[186:189], v[230:233], v[34:37]
	v_mfma_f32_16x16x32_bf16 v[22:25], v[164:167], v[238:241], v[22:25]
	v_mfma_f32_16x16x32_bf16 v[18:21], v[186:189], v[238:241], v[18:21]
	s_setprio 0
	s_setprio 1
	v_mfma_f32_16x16x32_bf16 v[46:49], v[190:193], v[210:213], v[46:49]
	v_mfma_f32_16x16x32_bf16 v[42:45], v[202:205], v[210:213], v[42:45]
	v_mfma_f32_16x16x32_bf16 v[30:33], v[190:193], v[218:221], v[30:33]
	v_mfma_f32_16x16x32_bf16 v[26:29], v[202:205], v[218:221], v[26:29]
	v_mfma_f32_16x16x32_bf16 v[14:17], v[190:193], v[226:229], v[14:17]
	v_mfma_f32_16x16x32_bf16 v[10:13], v[202:205], v[226:229], v[10:13]
	v_mfma_f32_16x16x32_bf16 v[6:9], v[190:193], v[234:237], v[6:9]
	v_mfma_f32_16x16x32_bf16 v[2:5], v[202:205], v[234:237], v[2:5]
	v_mfma_f32_16x16x32_bf16 v[46:49], v[198:201], v[214:217], v[46:49]
	v_mfma_f32_16x16x32_bf16 v[42:45], v[206:209], v[214:217], v[42:45]
	v_mfma_f32_16x16x32_bf16 v[30:33], v[198:201], v[222:225], v[30:33]
	v_mfma_f32_16x16x32_bf16 v[26:29], v[206:209], v[222:225], v[26:29]
	v_mfma_f32_16x16x32_bf16 v[14:17], v[198:201], v[230:233], v[14:17]
	v_mfma_f32_16x16x32_bf16 v[10:13], v[206:209], v[230:233], v[10:13]
	v_mfma_f32_16x16x32_bf16 v[6:9], v[198:201], v[238:241], v[6:9]
	v_mfma_f32_16x16x32_bf16 v[2:5], v[206:209], v[238:241], v[2:5]
	s_setprio 0
	s_barrier
	v_add_u32_e32 v186, s87, v157
	v_add_u32_e32 v206, s85, v157
	ds_read_b128 v[160:163], v186
	ds_read_b128 v[164:167], v186 offset:1024
	ds_read_b128 v[168:171], v186 offset:2048
	ds_read_b128 v[186:189], v186 offset:3072
	ds_read_b128 v[190:193], v206
	ds_read_b128 v[198:201], v206 offset:1024
	ds_read_b128 v[202:205], v206 offset:2048
	ds_read_b128 v[206:209], v206 offset:3072
	s_mov_b32 m0, s31
	v_lshl_add_u64 v[244:245], s[56:57], 0, v[154:155]
	ds_read_b128 v[210:213], v159 offset:32768
	ds_read_b128 v[214:217], v159 offset:33792
	ds_read_b128 v[218:221], v159 offset:34816
	ds_read_b128 v[222:225], v159 offset:35840
	ds_read_b128 v[226:229], v159 offset:36864
	ds_read_b128 v[230:233], v159 offset:37888
	ds_read_b128 v[234:237], v159 offset:38912
	ds_read_b128 v[238:241], v159 offset:39936
	global_load_lds_dwordx4 v[244:245], off
	v_lshl_add_u64 v[244:245], s[56:57], 0, v[152:153]
	s_mov_b32 m0, s34
	s_nop 0
	global_load_lds_dwordx4 v[244:245], off
	s_waitcnt vmcnt(8)
	s_waitcnt lgkmcnt(0)
	s_barrier
	s_setprio 1
	v_mfma_f32_16x16x32_bf16 v[126:129], v[160:163], v[210:213], v[126:129]
	v_mfma_f32_16x16x32_bf16 v[122:125], v[168:171], v[210:213], v[122:125]
	v_mfma_f32_16x16x32_bf16 v[118:121], v[160:163], v[218:221], v[118:121]
	v_mfma_f32_16x16x32_bf16 v[114:117], v[168:171], v[218:221], v[114:117]
	v_mfma_f32_16x16x32_bf16 v[102:105], v[160:163], v[226:229], v[102:105]
	v_mfma_f32_16x16x32_bf16 v[98:101], v[168:171], v[226:229], v[98:101]
	v_mfma_f32_16x16x32_bf16 v[86:89], v[160:163], v[234:237], v[86:89]
	v_mfma_f32_16x16x32_bf16 v[82:85], v[168:171], v[234:237], v[82:85]
	v_mfma_f32_16x16x32_bf16 v[126:129], v[164:167], v[214:217], v[126:129]
	v_mfma_f32_16x16x32_bf16 v[122:125], v[186:189], v[214:217], v[122:125]
	v_mfma_f32_16x16x32_bf16 v[118:121], v[164:167], v[222:225], v[118:121]
	v_mfma_f32_16x16x32_bf16 v[114:117], v[186:189], v[222:225], v[114:117]
	v_mfma_f32_16x16x32_bf16 v[102:105], v[164:167], v[230:233], v[102:105]
	v_mfma_f32_16x16x32_bf16 v[98:101], v[186:189], v[230:233], v[98:101]
	v_mfma_f32_16x16x32_bf16 v[86:89], v[164:167], v[238:241], v[86:89]
	v_mfma_f32_16x16x32_bf16 v[82:85], v[186:189], v[238:241], v[82:85]
	s_setprio 0
	s_setprio 1
	v_mfma_f32_16x16x32_bf16 v[110:113], v[190:193], v[210:213], v[110:113]
	v_mfma_f32_16x16x32_bf16 v[106:109], v[202:205], v[210:213], v[106:109]
	v_mfma_f32_16x16x32_bf16 v[94:97], v[190:193], v[218:221], v[94:97]
	v_mfma_f32_16x16x32_bf16 v[90:93], v[202:205], v[218:221], v[90:93]
	v_mfma_f32_16x16x32_bf16 v[78:81], v[190:193], v[226:229], v[78:81]
	v_mfma_f32_16x16x32_bf16 v[74:77], v[202:205], v[226:229], v[74:77]
	v_mfma_f32_16x16x32_bf16 v[70:73], v[190:193], v[234:237], v[70:73]
	v_mfma_f32_16x16x32_bf16 v[66:69], v[202:205], v[234:237], v[66:69]
	v_mfma_f32_16x16x32_bf16 v[110:113], v[198:201], v[214:217], v[110:113]
	v_mfma_f32_16x16x32_bf16 v[106:109], v[206:209], v[214:217], v[106:109]
	v_mfma_f32_16x16x32_bf16 v[94:97], v[198:201], v[222:225], v[94:97]
	v_mfma_f32_16x16x32_bf16 v[90:93], v[206:209], v[222:225], v[90:93]
	v_mfma_f32_16x16x32_bf16 v[78:81], v[198:201], v[230:233], v[78:81]
	v_mfma_f32_16x16x32_bf16 v[74:77], v[206:209], v[230:233], v[74:77]
	v_mfma_f32_16x16x32_bf16 v[70:73], v[198:201], v[238:241], v[70:73]
	v_mfma_f32_16x16x32_bf16 v[66:69], v[206:209], v[238:241], v[66:69]
	s_setprio 0
	s_barrier
; #define PG8_STAGE(bufoff, gbase, voff) do { _Pragma("unroll") for (int _i = 0; _i < 2; ++_i) \
;         __builtin_amdgcn_global_load_lds((const unsigned*)((const char*)(gbase) + (voff)[_i]), (PG8_LAS unsigned*)(lds + (bufoff) + ldsw + _i * 8192), 16, 0, 0); } while (0)
; #define PG8_LDA(dst, b, h) do { _Pragma("unroll") for (int m = 0; m < 4; ++m) _Pragma("unroll") for (int k = 0; k < 2; ++k) dst[m][k] = *(const PG8_LAS bf16x8*)(lds + PG8_SA(b, h) + aoff + m * 2048 + k * 1024); } while (0)
; #define PG8_MMA(ai, bj, At, Bt) do { __builtin_amdgcn_s_setprio(1); _Pragma("unroll") for (int m = 0; m < 4; ++m) _Pragma("unroll") for (int n = 0; n < 2; ++n) _Pragma("unroll") for (int k = 0; k < 2; ++k) \
;         acc[ai][bj][m][n] = __builtin_amdgcn_mfma_f32_16x16x32_bf16(Bt[n][k], At[m][k], acc[ai][bj][m][n], 0, 0, 0); __builtin_amdgcn_s_setprio(0); } while (0)
; #define PG8_WAIT_V(n) asm volatile("s_waitcnt vmcnt(" #n ")" ::: "memory")
; #define PG8_WAIT_L(n) asm volatile("s_waitcnt lgkmcnt(" #n ")" ::: "memory")
; #define PG8_BAR __builtin_amdgcn_s_barrier()
; #define PG8_SCHED __builtin_amdgcn_sched_barrier(0)
; template <class Epi, class Sched, bool ALIGN_EPI = false, bool SP2 = false>
; __device__ __forceinline__ void gemm_phase(PG8_LAS unsigned char* lds, const Gemm g, const Sched& S, const Epi& E) {
;     ...
;             PG8_LDA(At, 1, 1); PG8_STAGE(PG8_SB(1, 0), b3, voffB); PG8_STAGE(PG8_SB(1, 1), b3 + hstepB, voffB); PG8_STAGE(PG8_SA(1, 0), a3, voffA);
;             PG8_WAIT_V(8); PG8_WAIT_L(0); PG8_BAR; PG8_MMA(1, 0, At, B0); PG8_MMA(1, 1, At, B1); PG8_BAR; PG8_SCHED;
;     ...
;         if constexpr (ALIGN_EPI) { if (wr == 0) PG8_BAR; }
	s_mov_b32 m0, s39
	v_lshl_add_u64 v[130:131], v[130:131], 0, s[2:3]
	ds_read_b128 v[210:213], v159 offset:49152
	ds_read_b128 v[214:217], v159 offset:50176
	ds_read_b128 v[218:221], v159 offset:51200
	ds_read_b128 v[222:225], v159 offset:52224
	ds_read_b128 v[226:229], v159 offset:53248
	ds_read_b128 v[230:233], v159 offset:54272
	ds_read_b128 v[234:237], v159 offset:55296
	ds_read_b128 v[238:241], v159 offset:56320
	global_load_lds_dwordx4 v[130:131], off
	v_lshl_add_u64 v[130:131], v[132:133], 0, s[2:3]
	s_mov_b32 m0, s4
	s_nop 0
	global_load_lds_dwordx4 v[130:131], off
	v_lshl_add_u64 v[130:131], s[54:55], 0, v[0:1]
	s_mov_b32 m0, s11
	s_nop 0
	global_load_lds_dwordx4 v[130:131], off
	v_lshl_add_u64 v[130:131], s[54:55], 0, v[150:151]
	s_mov_b32 m0, s10
	s_nop 0
	global_load_lds_dwordx4 v[130:131], off
	v_lshl_add_u64 v[130:131], v[172:173], 0, s[2:3]
	s_mov_b32 m0, s35
	s_nop 0
	global_load_lds_dwordx4 v[130:131], off
	v_lshl_add_u64 v[130:131], v[242:243], 0, s[2:3]
	s_mov_b32 m0, s88
	s_nop 0
	global_load_lds_dwordx4 v[130:131], off
	s_waitcnt vmcnt(8)
	s_waitcnt lgkmcnt(0)
	s_barrier
	s_setprio 1
	v_mfma_f32_16x16x32_bf16 v[62:65], v[160:163], v[210:213], v[62:65]
	v_mfma_f32_16x16x32_bf16 v[58:61], v[168:171], v[210:213], v[58:61]
	v_mfma_f32_16x16x32_bf16 v[54:57], v[160:163], v[218:221], v[54:57]
	v_mfma_f32_16x16x32_bf16 v[50:53], v[168:171], v[218:221], v[50:53]
	v_mfma_f32_16x16x32_bf16 v[38:41], v[160:163], v[226:229], v[38:41]
	v_mfma_f32_16x16x32_bf16 v[34:37], v[168:171], v[226:229], v[34:37]
	v_mfma_f32_16x16x32_bf16 v[22:25], v[160:163], v[234:237], v[22:25]
	v_mfma_f32_16x16x32_bf16 v[18:21], v[168:171], v[234:237], v[18:21]
	v_mfma_f32_16x16x32_bf16 v[62:65], v[164:167], v[214:217], v[62:65]
	v_mfma_f32_16x16x32_bf16 v[58:61], v[186:189], v[214:217], v[58:61]
	v_mfma_f32_16x16x32_bf16 v[54:57], v[164:167], v[222:225], v[54:57]
	v_mfma_f32_16x16x32_bf16 v[50:53], v[186:189], v[222:225], v[50:53]
	v_mfma_f32_16x16x32_bf16 v[38:41], v[164:167], v[230:233], v[38:41]
	v_mfma_f32_16x16x32_bf16 v[34:37], v[186:189], v[230:233], v[34:37]
	v_mfma_f32_16x16x32_bf16 v[22:25], v[164:167], v[238:241], v[22:25]
	v_mfma_f32_16x16x32_bf16 v[18:21], v[186:189], v[238:241], v[18:21]
	s_setprio 0
	s_setprio 1
	v_mfma_f32_16x16x32_bf16 v[46:49], v[190:193], v[210:213], v[46:49]
	v_mfma_f32_16x16x32_bf16 v[42:45], v[202:205], v[210:213], v[42:45]
	v_mfma_f32_16x16x32_bf16 v[30:33], v[190:193], v[218:221], v[30:33]
	v_mfma_f32_16x16x32_bf16 v[26:29], v[202:205], v[218:221], v[26:29]
	v_mfma_f32_16x16x32_bf16 v[14:17], v[190:193], v[226:229], v[14:17]
	v_mfma_f32_16x16x32_bf16 v[10:13], v[202:205], v[226:229], v[10:13]
	v_mfma_f32_16x16x32_bf16 v[6:9], v[190:193], v[234:237], v[6:9]
	v_mfma_f32_16x16x32_bf16 v[2:5], v[202:205], v[234:237], v[2:5]
	v_mfma_f32_16x16x32_bf16 v[46:49], v[198:201], v[214:217], v[46:49]
	v_mfma_f32_16x16x32_bf16 v[42:45], v[206:209], v[214:217], v[42:45]
	v_mfma_f32_16x16x32_bf16 v[30:33], v[198:201], v[222:225], v[30:33]
	v_mfma_f32_16x16x32_bf16 v[26:29], v[206:209], v[222:225], v[26:29]
	v_mfma_f32_16x16x32_bf16 v[14:17], v[198:201], v[230:233], v[14:17]
	v_mfma_f32_16x16x32_bf16 v[10:13], v[206:209], v[230:233], v[10:13]
	v_mfma_f32_16x16x32_bf16 v[6:9], v[198:201], v[238:241], v[6:9]
	v_mfma_f32_16x16x32_bf16 v[2:5], v[206:209], v[238:241], v[2:5]
	s_setprio 0
	s_barrier
	s_movk_i32 s4, 0x100
	s_andn2_b64 vcc, exec, s[0:1]
	s_mov_b64 s[54:55], -1
	s_mov_b64 s[0:1], 0
	s_cbranch_vccz .LBB0_402
	s_and_b64 vcc, exec, s[42:43]
	s_cbranch_vccz .LBB0_405
	s_barrier

; #define PG8_STAGE(bufoff, gbase, voff) do { _Pragma("unroll") for (int _i = 0; _i < 2; ++_i) \
;         __builtin_amdgcn_global_load_lds((const unsigned*)((const char*)(gbase) + (voff)[_i]), (PG8_LAS unsigned*)(lds + (bufoff) + ldsw + _i * 8192), 16, 0, 0); } while (0)
; #define PG8_LDA(dst, b, h) do { _Pragma("unroll") for (int m = 0; m < 4; ++m) _Pragma("unroll") for (int k = 0; k < 2; ++k) dst[m][k] = *(const PG8_LAS bf16x8*)(lds + PG8_SA(b, h) + aoff + m * 2048 + k * 1024); } while (0)
; #define PG8_LDB(dst, b, h) do { _Pragma("unroll") for (int n = 0; n < 2; ++n) _Pragma("unroll") for (int k = 0; k < 2; ++k) dst[n][k] = *(const PG8_LAS bf16x8*)(lds + PG8_SB(b, h) + boff + n * 2048 + k * 1024); } while (0)
; #define PG8_MMA(ai, bj, At, Bt) do { __builtin_amdgcn_s_setprio(1); _Pragma("unroll") for (int m = 0; m < 4; ++m) _Pragma("unroll") for (int n = 0; n < 2; ++n) _Pragma("unroll") for (int k = 0; k < 2; ++k) \
;         acc[ai][bj][m][n] = __builtin_amdgcn_mfma_f32_16x16x32_bf16(Bt[n][k], At[m][k], acc[ai][bj][m][n], 0, 0, 0); __builtin_amdgcn_s_setprio(0); } while (0)
; #define PG8_WAIT_V(n) asm volatile("s_waitcnt vmcnt(" #n ")" ::: "memory")
; #define PG8_WAIT_L(n) asm volatile("s_waitcnt lgkmcnt(" #n ")" ::: "memory")
; template <class Epi, class Sched, bool ALIGN_EPI = false, bool SP2 = false>
; __device__ __forceinline__ void gemm_phase(PG8_LAS unsigned char* lds, const Gemm g, const Sched& S, const Epi& E) {
;     ...
;             const bool last = (t == nt - 2);
;             const char* a1 = cA + (size_t)(t + 1) * kstep;
;             const char* a2 = last ? nA : cA + (size_t)(t + 2) * kstep; const char* b2 = last ? nB : cB + (size_t)(t + 2) * kstep;
;             const char* a3 = a2 + kstep; const char* b3 = b2 + kstep;
;             if (last && has_next) S.a_ready(nxt);
;             if constexpr (SP2) {
;             PG8_LDB(B0, 0, 0); PG8_LDB(B1, 0, 1); PG8_SCHED; PG8_LDA(At, 0, 0); PG8_STAGE(PG8_SA(1, 1), a1 + hstepA, voffA);
;             PG8_WAIT_V(8); PG8_WAIT_L(0); PG8_BAR; PG8_MMA(0, 0, At, B0); PG8_MMA(0, 1, At, B1); PG8_BAR; PG8_SCHED;
;             PG8_LDA(At, 0, 1); PG8_STAGE(PG8_SB(0, 0), b2, voffB); PG8_STAGE(PG8_SB(0, 1), b2 + hstepB, voffB); PG8_STAGE(PG8_SA(0, 0), a2, voffA);
;             PG8_WAIT_V(8); PG8_WAIT_L(0); PG8_BAR; PG8_MMA(1, 0, At, B0); PG8_MMA(1, 1, At, B1); PG8_BAR; PG8_SCHED;
.LBB0_424:
	s_add_u32 s12, s50, s36
	s_addc_u32 s13, s51, 0
	s_add_u32 s37, s12, 0x100
	s_addc_u32 s54, s13, 0
	s_and_b64 s[10:11], s[52:53], exec
	s_cselect_b32 s57, s43, s54
	s_cselect_b32 s56, s4, s37
	s_add_u32 s10, s48, s36
	s_addc_u32 s11, s49, 0
	s_add_u32 s36, s10, 0x100
	s_addc_u32 s37, s11, 0
	s_add_i32 s86, 0, 0x10000
	s_and_b64 s[10:11], s[52:53], exec
	s_cselect_b32 s63, s45, s37
	s_cselect_b32 s62, s44, s36
	s_add_i32 s10, 0, 0x14000
	s_add_u32 s68, s12, 0x10080
	s_addc_u32 s69, s13, 0
	s_add_i32 s12, s86, s8
	s_add_i32 m0, s9, 0xc000
	s_add_i32 s13, s9, 0xe000
	s_add_i32 s81, s12, 0x2000
	v_add_u32_e32 v130, s86, v157
	s_add_u32 s36, s62, 0x90000
	ds_read_b128 v[160:163], v130
	ds_read_b128 v[164:167], v130 offset:1024
	ds_read_b128 v[168:171], v130 offset:2048
	ds_read_b128 v[186:189], v130 offset:3072
	v_add_u32_e32 v130, s10, v157
	s_addc_u32 s37, s63, 0
	s_add_i32 s93, s10, s8
	ds_read_b128 v[190:193], v130
	ds_read_b128 v[198:201], v130 offset:1024
	ds_read_b128 v[202:205], v130 offset:2048
	ds_read_b128 v[206:209], v130 offset:3072
	s_add_i32 s92, s93, 0x2000
	s_add_i32 s87, 0, 0x18000
	s_add_i32 s85, 0, 0x1c000
	s_add_u32 s54, s56, 0x10000
	s_addc_u32 s55, s57, 0
	s_add_i32 vcc_hi, s87, s8
	s_add_i32 vcc_lo, vcc_hi, 0x2000
	s_add_u32 s52, s62, 0x90080
	s_addc_u32 s53, s63, 0
	s_add_i32 s11, s85, s8
	s_add_i32 s10, s11, 0x2000
	v_lshl_add_u64 v[130:131], s[68:69], 0, v[154:155]
	ds_read_b128 v[210:213], v159
	ds_read_b128 v[214:217], v159 offset:1024
	ds_read_b128 v[218:221], v159 offset:2048
	ds_read_b128 v[222:225], v159 offset:3072
	ds_read_b128 v[226:229], v159 offset:4096
	ds_read_b128 v[230:233], v159 offset:5120
	ds_read_b128 v[234:237], v159 offset:6144
	ds_read_b128 v[238:241], v159 offset:7168
	global_load_lds_dwordx4 v[130:131], off
	v_lshl_add_u64 v[130:131], s[68:69], 0, v[152:153]
	s_mov_b32 m0, s13
	s_nop 0
	global_load_lds_dwordx4 v[130:131], off
	s_waitcnt vmcnt(8)
	s_waitcnt lgkmcnt(0)
	s_barrier
	s_setprio 1
	v_mfma_f32_16x16x32_bf16 v[126:129], v[160:163], v[210:213], v[126:129]
	v_mfma_f32_16x16x32_bf16 v[122:125], v[168:171], v[210:213], v[122:125]
	v_mfma_f32_16x16x32_bf16 v[118:121], v[160:163], v[218:221], v[118:121]
	v_mfma_f32_16x16x32_bf16 v[114:117], v[168:171], v[218:221], v[114:117]
	v_mfma_f32_16x16x32_bf16 v[102:105], v[160:163], v[226:229], v[102:105]
	v_mfma_f32_16x16x32_bf16 v[98:101], v[168:171], v[226:229], v[98:101]
	v_mfma_f32_16x16x32_bf16 v[86:89], v[160:163], v[234:237], v[86:89]
	v_mfma_f32_16x16x32_bf16 v[82:85], v[168:171], v[234:237], v[82:85]
	v_mfma_f32_16x16x32_bf16 v[126:129], v[164:167], v[214:217], v[126:129]
	v_mfma_f32_16x16x32_bf16 v[122:125], v[186:189], v[214:217], v[122:125]
	v_mfma_f32_16x16x32_bf16 v[118:121], v[164:167], v[222:225], v[118:121]
	v_mfma_f32_16x16x32_bf16 v[114:117], v[186:189], v[222:225], v[114:117]
	v_mfma_f32_16x16x32_bf16 v[102:105], v[164:167], v[230:233], v[102:105]
	v_mfma_f32_16x16x32_bf16 v[98:101], v[186:189], v[230:233], v[98:101]
	v_mfma_f32_16x16x32_bf16 v[86:89], v[164:167], v[238:241], v[86:89]
	v_mfma_f32_16x16x32_bf16 v[82:85], v[186:189], v[238:241], v[82:85]
	s_setprio 0
	s_setprio 1
	v_mfma_f32_16x16x32_bf16 v[110:113], v[190:193], v[210:213], v[110:113]
	v_mfma_f32_16x16x32_bf16 v[106:109], v[202:205], v[210:213], v[106:109]
	v_mfma_f32_16x16x32_bf16 v[94:97], v[190:193], v[218:221], v[94:97]
	v_mfma_f32_16x16x32_bf16 v[90:93], v[202:205], v[218:221], v[90:93]
	v_mfma_f32_16x16x32_bf16 v[78:81], v[190:193], v[226:229], v[78:81]
	v_mfma_f32_16x16x32_bf16 v[74:77], v[202:205], v[226:229], v[74:77]
	v_mfma_f32_16x16x32_bf16 v[70:73], v[190:193], v[234:237], v[70:73]
	v_mfma_f32_16x16x32_bf16 v[66:69], v[202:205], v[234:237], v[66:69]
	v_mfma_f32_16x16x32_bf16 v[110:113], v[198:201], v[214:217], v[110:113]
	v_mfma_f32_16x16x32_bf16 v[106:109], v[206:209], v[214:217], v[106:109]
	v_mfma_f32_16x16x32_bf16 v[94:97], v[198:201], v[222:225], v[94:97]
	v_mfma_f32_16x16x32_bf16 v[90:93], v[206:209], v[222:225], v[90:93]
	v_mfma_f32_16x16x32_bf16 v[78:81], v[198:201], v[230:233], v[78:81]
	v_mfma_f32_16x16x32_bf16 v[74:77], v[206:209], v[230:233], v[74:77]
	v_mfma_f32_16x16x32_bf16 v[70:73], v[198:201], v[238:241], v[70:73]
	v_mfma_f32_16x16x32_bf16 v[66:69], v[206:209], v[238:241], v[66:69]
	s_setprio 0
	s_barrier
	s_mov_b32 m0, s12
	v_lshl_add_u64 v[130:131], s[62:63], 0, v[0:1]
	ds_read_b128 v[210:213], v159 offset:16384
	ds_read_b128 v[214:217], v159 offset:17408
	ds_read_b128 v[218:221], v159 offset:18432
	ds_read_b128 v[222:225], v159 offset:19456
	ds_read_b128 v[226:229], v159 offset:20480
	ds_read_b128 v[230:233], v159 offset:21504
	ds_read_b128 v[234:237], v159 offset:22528
	ds_read_b128 v[238:241], v159 offset:23552
	global_load_lds_dwordx4 v[130:131], off
	v_lshl_add_u64 v[132:133], s[62:63], 0, v[150:151]
	s_mov_b32 m0, s81
	v_lshl_add_u64 v[172:173], s[36:37], 0, v[0:1]
	global_load_lds_dwordx4 v[132:133], off
	s_mov_b32 m0, s93
	v_lshl_add_u64 v[242:243], s[56:57], 0, v[152:153]
	global_load_lds_dwordx4 v[172:173], off
	v_lshl_add_u64 v[172:173], s[36:37], 0, v[150:151]
	s_mov_b32 m0, s92
	s_nop 0
	global_load_lds_dwordx4 v[172:173], off
	v_lshl_add_u64 v[172:173], s[56:57], 0, v[154:155]
	s_mov_b32 m0, s9
	s_nop 0
	global_load_lds_dwordx4 v[172:173], off
	s_mov_b32 m0, s30
	s_nop 0
	global_load_lds_dwordx4 v[242:243], off
	s_waitcnt vmcnt(8)
	s_waitcnt lgkmcnt(0)
	s_barrier
; #define PG8_STAGE(bufoff, gbase, voff) do { _Pragma("unroll") for (int _i = 0; _i < 2; ++_i) \
;         __builtin_amdgcn_global_load_lds((const unsigned*)((const char*)(gbase) + (voff)[_i]), (PG8_LAS unsigned*)(lds + (bufoff) + ldsw + _i * 8192), 16, 0, 0); } while (0)
; #define PG8_LDA(dst, b, h) do { _Pragma("unroll") for (int m = 0; m < 4; ++m) _Pragma("unroll") for (int k = 0; k < 2; ++k) dst[m][k] = *(const PG8_LAS bf16x8*)(lds + PG8_SA(b, h) + aoff + m * 2048 + k * 1024); } while (0)
; #define PG8_LDB(dst, b, h) do { _Pragma("unroll") for (int n = 0; n < 2; ++n) _Pragma("unroll") for (int k = 0; k < 2; ++k) dst[n][k] = *(const PG8_LAS bf16x8*)(lds + PG8_SB(b, h) + boff + n * 2048 + k * 1024); } while (0)
; #define PG8_MMA(ai, bj, At, Bt) do { __builtin_amdgcn_s_setprio(1); _Pragma("unroll") for (int m = 0; m < 4; ++m) _Pragma("unroll") for (int n = 0; n < 2; ++n) _Pragma("unroll") for (int k = 0; k < 2; ++k) \
;         acc[ai][bj][m][n] = __builtin_amdgcn_mfma_f32_16x16x32_bf16(Bt[n][k], At[m][k], acc[ai][bj][m][n], 0, 0, 0); __builtin_amdgcn_s_setprio(0); } while (0)
; #define PG8_WAIT_V(n) asm volatile("s_waitcnt vmcnt(" #n ")" ::: "memory")
; #define PG8_WAIT_L(n) asm volatile("s_waitcnt lgkmcnt(" #n ")" ::: "memory")
; #define PG8_BAR __builtin_amdgcn_s_barrier()
; #define PG8_SCHED __builtin_amdgcn_sched_barrier(0)
; template <class Epi, class Sched, bool ALIGN_EPI = false, bool SP2 = false>
; __device__ __forceinline__ void gemm_phase(PG8_LAS unsigned char* lds, const Gemm g, const Sched& S, const Epi& E) {
;     ...
;             PG8_WAIT_V(8); PG8_WAIT_L(0); PG8_BAR; PG8_MMA(1, 0, At, B0); PG8_MMA(1, 1, At, B1); PG8_BAR; PG8_SCHED;
;             PG8_LDB(B0, 1, 0); PG8_LDB(B1, 1, 1); PG8_SCHED; PG8_LDA(At, 1, 0); PG8_STAGE(PG8_SA(0, 1), a2 + hstepA, voffA);
;             PG8_WAIT_V(8); PG8_WAIT_L(0); PG8_BAR; PG8_MMA(0, 0, At, B0); PG8_MMA(0, 1, At, B1); PG8_BAR; PG8_SCHED;
	s_setprio 1
	v_mfma_f32_16x16x32_bf16 v[62:65], v[160:163], v[210:213], v[62:65]
	v_mfma_f32_16x16x32_bf16 v[58:61], v[168:171], v[210:213], v[58:61]
	v_mfma_f32_16x16x32_bf16 v[54:57], v[160:163], v[218:221], v[54:57]
	v_mfma_f32_16x16x32_bf16 v[50:53], v[168:171], v[218:221], v[50:53]
	v_mfma_f32_16x16x32_bf16 v[38:41], v[160:163], v[226:229], v[38:41]
	v_mfma_f32_16x16x32_bf16 v[34:37], v[168:171], v[226:229], v[34:37]
	v_mfma_f32_16x16x32_bf16 v[22:25], v[160:163], v[234:237], v[22:25]
	v_mfma_f32_16x16x32_bf16 v[18:21], v[168:171], v[234:237], v[18:21]
	v_mfma_f32_16x16x32_bf16 v[62:65], v[164:167], v[214:217], v[62:65]
	v_mfma_f32_16x16x32_bf16 v[58:61], v[186:189], v[214:217], v[58:61]
	v_mfma_f32_16x16x32_bf16 v[54:57], v[164:167], v[222:225], v[54:57]
	v_mfma_f32_16x16x32_bf16 v[50:53], v[186:189], v[222:225], v[50:53]
	v_mfma_f32_16x16x32_bf16 v[38:41], v[164:167], v[230:233], v[38:41]
	v_mfma_f32_16x16x32_bf16 v[34:37], v[186:189], v[230:233], v[34:37]
	v_mfma_f32_16x16x32_bf16 v[22:25], v[164:167], v[238:241], v[22:25]
	v_mfma_f32_16x16x32_bf16 v[18:21], v[186:189], v[238:241], v[18:21]
	s_setprio 0
	s_setprio 1
	v_mfma_f32_16x16x32_bf16 v[46:49], v[190:193], v[210:213], v[46:49]
	v_mfma_f32_16x16x32_bf16 v[42:45], v[202:205], v[210:213], v[42:45]
	v_mfma_f32_16x16x32_bf16 v[30:33], v[190:193], v[218:221], v[30:33]
	v_mfma_f32_16x16x32_bf16 v[26:29], v[202:205], v[218:221], v[26:29]
	v_mfma_f32_16x16x32_bf16 v[14:17], v[190:193], v[226:229], v[14:17]
	v_mfma_f32_16x16x32_bf16 v[10:13], v[202:205], v[226:229], v[10:13]
	v_mfma_f32_16x16x32_bf16 v[6:9], v[190:193], v[234:237], v[6:9]
	v_mfma_f32_16x16x32_bf16 v[2:5], v[202:205], v[234:237], v[2:5]
	v_mfma_f32_16x16x32_bf16 v[46:49], v[198:201], v[214:217], v[46:49]
	v_mfma_f32_16x16x32_bf16 v[42:45], v[206:209], v[214:217], v[42:45]
	v_mfma_f32_16x16x32_bf16 v[30:33], v[198:201], v[222:225], v[30:33]
	v_mfma_f32_16x16x32_bf16 v[26:29], v[206:209], v[222:225], v[26:29]
	v_mfma_f32_16x16x32_bf16 v[14:17], v[198:201], v[230:233], v[14:17]
	v_mfma_f32_16x16x32_bf16 v[10:13], v[206:209], v[230:233], v[10:13]
	v_mfma_f32_16x16x32_bf16 v[6:9], v[198:201], v[238:241], v[6:9]
	v_mfma_f32_16x16x32_bf16 v[2:5], v[206:209], v[238:241], v[2:5]
	s_setprio 0
	s_barrier
	v_add_u32_e32 v186, s87, v157
	v_add_u32_e32 v206, s85, v157
	ds_read_b128 v[160:163], v186
	ds_read_b128 v[164:167], v186 offset:1024
	ds_read_b128 v[168:171], v186 offset:2048
	ds_read_b128 v[186:189], v186 offset:3072
	ds_read_b128 v[190:193], v206
	ds_read_b128 v[198:201], v206 offset:1024
	ds_read_b128 v[202:205], v206 offset:2048
	ds_read_b128 v[206:209], v206 offset:3072
	s_mov_b32 m0, s31
	v_lshl_add_u64 v[244:245], s[54:55], 0, v[154:155]
	ds_read_b128 v[210:213], v159 offset:32768
	ds_read_b128 v[214:217], v159 offset:33792
	ds_read_b128 v[218:221], v159 offset:34816
	ds_read_b128 v[222:225], v159 offset:35840
	ds_read_b128 v[226:229], v159 offset:36864
	ds_read_b128 v[230:233], v159 offset:37888
	ds_read_b128 v[234:237], v159 offset:38912
	ds_read_b128 v[238:241], v159 offset:39936
	global_load_lds_dwordx4 v[244:245], off
	v_lshl_add_u64 v[244:245], s[54:55], 0, v[152:153]
	s_mov_b32 m0, s34
	s_nop 0
	global_load_lds_dwordx4 v[244:245], off
	s_waitcnt vmcnt(8)
	s_waitcnt lgkmcnt(0)
	s_barrier
	s_setprio 1
	v_mfma_f32_16x16x32_bf16 v[126:129], v[160:163], v[210:213], v[126:129]
	v_mfma_f32_16x16x32_bf16 v[122:125], v[168:171], v[210:213], v[122:125]
	v_mfma_f32_16x16x32_bf16 v[118:121], v[160:163], v[218:221], v[118:121]
	v_mfma_f32_16x16x32_bf16 v[114:117], v[168:171], v[218:221], v[114:117]
	v_mfma_f32_16x16x32_bf16 v[102:105], v[160:163], v[226:229], v[102:105]
	v_mfma_f32_16x16x32_bf16 v[98:101], v[168:171], v[226:229], v[98:101]
	v_mfma_f32_16x16x32_bf16 v[86:89], v[160:163], v[234:237], v[86:89]
	v_mfma_f32_16x16x32_bf16 v[82:85], v[168:171], v[234:237], v[82:85]
	v_mfma_f32_16x16x32_bf16 v[126:129], v[164:167], v[214:217], v[126:129]
	v_mfma_f32_16x16x32_bf16 v[122:125], v[186:189], v[214:217], v[122:125]
	v_mfma_f32_16x16x32_bf16 v[118:121], v[164:167], v[222:225], v[118:121]
	v_mfma_f32_16x16x32_bf16 v[114:117], v[186:189], v[222:225], v[114:117]
	v_mfma_f32_16x16x32_bf16 v[102:105], v[164:167], v[230:233], v[102:105]
	v_mfma_f32_16x16x32_bf16 v[98:101], v[186:189], v[230:233], v[98:101]
	v_mfma_f32_16x16x32_bf16 v[86:89], v[164:167], v[238:241], v[86:89]
	v_mfma_f32_16x16x32_bf16 v[82:85], v[186:189], v[238:241], v[82:85]
	s_setprio 0
	s_setprio 1
	v_mfma_f32_16x16x32_bf16 v[110:113], v[190:193], v[210:213], v[110:113]
	v_mfma_f32_16x16x32_bf16 v[106:109], v[202:205], v[210:213], v[106:109]
	v_mfma_f32_16x16x32_bf16 v[94:97], v[190:193], v[218:221], v[94:97]
	v_mfma_f32_16x16x32_bf16 v[90:93], v[202:205], v[218:221], v[90:93]
	v_mfma_f32_16x16x32_bf16 v[78:81], v[190:193], v[226:229], v[78:81]
	v_mfma_f32_16x16x32_bf16 v[74:77], v[202:205], v[226:229], v[74:77]
	v_mfma_f32_16x16x32_bf16 v[70:73], v[190:193], v[234:237], v[70:73]
	v_mfma_f32_16x16x32_bf16 v[66:69], v[202:205], v[234:237], v[66:69]
	v_mfma_f32_16x16x32_bf16 v[110:113], v[198:201], v[214:217], v[110:113]
	v_mfma_f32_16x16x32_bf16 v[106:109], v[206:209], v[214:217], v[106:109]
	v_mfma_f32_16x16x32_bf16 v[94:97], v[198:201], v[222:225], v[94:97]
	v_mfma_f32_16x16x32_bf16 v[90:93], v[206:209], v[222:225], v[90:93]
	v_mfma_f32_16x16x32_bf16 v[78:81], v[198:201], v[230:233], v[78:81]
	v_mfma_f32_16x16x32_bf16 v[74:77], v[206:209], v[230:233], v[74:77]
	v_mfma_f32_16x16x32_bf16 v[70:73], v[198:201], v[238:241], v[70:73]
	v_mfma_f32_16x16x32_bf16 v[66:69], v[206:209], v[238:241], v[66:69]
	s_setprio 0
	s_barrier
; #define PG8_STAGE(bufoff, gbase, voff) do { _Pragma("unroll") for (int _i = 0; _i < 2; ++_i) \
;         __builtin_amdgcn_global_load_lds((const unsigned*)((const char*)(gbase) + (voff)[_i]), (PG8_LAS unsigned*)(lds + (bufoff) + ldsw + _i * 8192), 16, 0, 0); } while (0)
; #define PG8_LDA(dst, b, h) do { _Pragma("unroll") for (int m = 0; m < 4; ++m) _Pragma("unroll") for (int k = 0; k < 2; ++k) dst[m][k] = *(const PG8_LAS bf16x8*)(lds + PG8_SA(b, h) + aoff + m * 2048 + k * 1024); } while (0)
; #define PG8_MMA(ai, bj, At, Bt) do { __builtin_amdgcn_s_setprio(1); _Pragma("unroll") for (int m = 0; m < 4; ++m) _Pragma("unroll") for (int n = 0; n < 2; ++n) _Pragma("unroll") for (int k = 0; k < 2; ++k) \
;         acc[ai][bj][m][n] = __builtin_amdgcn_mfma_f32_16x16x32_bf16(Bt[n][k], At[m][k], acc[ai][bj][m][n], 0, 0, 0); __builtin_amdgcn_s_setprio(0); } while (0)
; #define PG8_WAIT_V(n) asm volatile("s_waitcnt vmcnt(" #n ")" ::: "memory")
; #define PG8_WAIT_L(n) asm volatile("s_waitcnt lgkmcnt(" #n ")" ::: "memory")
; #define PG8_BAR __builtin_amdgcn_s_barrier()
; #define PG8_SCHED __builtin_amdgcn_sched_barrier(0)
; template <class Epi, class Sched, bool ALIGN_EPI = false, bool SP2 = false>
; __device__ __forceinline__ void gemm_phase(PG8_LAS unsigned char* lds, const Gemm g, const Sched& S, const Epi& E) {
;     ...
;             PG8_LDA(At, 1, 1); PG8_STAGE(PG8_SB(1, 0), b3, voffB); PG8_STAGE(PG8_SB(1, 1), b3 + hstepB, voffB); PG8_STAGE(PG8_SA(1, 0), a3, voffA);
;             PG8_WAIT_V(8); PG8_WAIT_L(0); PG8_BAR; PG8_MMA(1, 0, At, B0); PG8_MMA(1, 1, At, B1); PG8_BAR; PG8_SCHED;
;     ...
;         if constexpr (ALIGN_EPI) { if (wr == 0) PG8_BAR; }
	s_mov_b32 m0, vcc_hi
	v_lshl_add_u64 v[130:131], v[130:131], 0, s[2:3]
	ds_read_b128 v[210:213], v159 offset:49152
	ds_read_b128 v[214:217], v159 offset:50176
	ds_read_b128 v[218:221], v159 offset:51200
	ds_read_b128 v[222:225], v159 offset:52224
	ds_read_b128 v[226:229], v159 offset:53248
	ds_read_b128 v[230:233], v159 offset:54272
	ds_read_b128 v[234:237], v159 offset:55296
	ds_read_b128 v[238:241], v159 offset:56320
	global_load_lds_dwordx4 v[130:131], off
	v_lshl_add_u64 v[130:131], v[132:133], 0, s[2:3]
	s_mov_b32 m0, vcc_lo
	s_nop 0
	global_load_lds_dwordx4 v[130:131], off
	v_lshl_add_u64 v[130:131], s[52:53], 0, v[0:1]
	s_mov_b32 m0, s11
	s_nop 0
	global_load_lds_dwordx4 v[130:131], off
	v_lshl_add_u64 v[130:131], s[52:53], 0, v[150:151]
	s_mov_b32 m0, s10
	s_nop 0
	global_load_lds_dwordx4 v[130:131], off
	v_lshl_add_u64 v[130:131], v[172:173], 0, s[2:3]
	s_mov_b32 m0, s35
	s_nop 0
	global_load_lds_dwordx4 v[130:131], off
	v_lshl_add_u64 v[130:131], v[242:243], 0, s[2:3]
	s_mov_b32 m0, s88
	s_nop 0
	global_load_lds_dwordx4 v[130:131], off
	s_waitcnt vmcnt(8)
	s_waitcnt lgkmcnt(0)
	s_barrier
	s_setprio 1
	v_mfma_f32_16x16x32_bf16 v[62:65], v[160:163], v[210:213], v[62:65]
	v_mfma_f32_16x16x32_bf16 v[58:61], v[168:171], v[210:213], v[58:61]
	v_mfma_f32_16x16x32_bf16 v[54:57], v[160:163], v[218:221], v[54:57]
	v_mfma_f32_16x16x32_bf16 v[50:53], v[168:171], v[218:221], v[50:53]
	v_mfma_f32_16x16x32_bf16 v[38:41], v[160:163], v[226:229], v[38:41]
	v_mfma_f32_16x16x32_bf16 v[34:37], v[168:171], v[226:229], v[34:37]
	v_mfma_f32_16x16x32_bf16 v[22:25], v[160:163], v[234:237], v[22:25]
	v_mfma_f32_16x16x32_bf16 v[18:21], v[168:171], v[234:237], v[18:21]
	v_mfma_f32_16x16x32_bf16 v[62:65], v[164:167], v[214:217], v[62:65]
	v_mfma_f32_16x16x32_bf16 v[58:61], v[186:189], v[214:217], v[58:61]
	v_mfma_f32_16x16x32_bf16 v[54:57], v[164:167], v[222:225], v[54:57]
	v_mfma_f32_16x16x32_bf16 v[50:53], v[186:189], v[222:225], v[50:53]
	v_mfma_f32_16x16x32_bf16 v[38:41], v[164:167], v[230:233], v[38:41]
	v_mfma_f32_16x16x32_bf16 v[34:37], v[186:189], v[230:233], v[34:37]
	v_mfma_f32_16x16x32_bf16 v[22:25], v[164:167], v[238:241], v[22:25]
	v_mfma_f32_16x16x32_bf16 v[18:21], v[186:189], v[238:241], v[18:21]
	s_setprio 0
	s_setprio 1
	v_mfma_f32_16x16x32_bf16 v[46:49], v[190:193], v[210:213], v[46:49]
	v_mfma_f32_16x16x32_bf16 v[42:45], v[202:205], v[210:213], v[42:45]
	v_mfma_f32_16x16x32_bf16 v[30:33], v[190:193], v[218:221], v[30:33]
	v_mfma_f32_16x16x32_bf16 v[26:29], v[202:205], v[218:221], v[26:29]
	v_mfma_f32_16x16x32_bf16 v[14:17], v[190:193], v[226:229], v[14:17]
	v_mfma_f32_16x16x32_bf16 v[10:13], v[202:205], v[226:229], v[10:13]
	v_mfma_f32_16x16x32_bf16 v[6:9], v[190:193], v[234:237], v[6:9]
	v_mfma_f32_16x16x32_bf16 v[2:5], v[202:205], v[234:237], v[2:5]
	v_mfma_f32_16x16x32_bf16 v[46:49], v[198:201], v[214:217], v[46:49]
	v_mfma_f32_16x16x32_bf16 v[42:45], v[206:209], v[214:217], v[42:45]
	v_mfma_f32_16x16x32_bf16 v[30:33], v[198:201], v[222:225], v[30:33]
	v_mfma_f32_16x16x32_bf16 v[26:29], v[206:209], v[222:225], v[26:29]
	v_mfma_f32_16x16x32_bf16 v[14:17], v[198:201], v[230:233], v[14:17]
	v_mfma_f32_16x16x32_bf16 v[10:13], v[206:209], v[230:233], v[10:13]
	v_mfma_f32_16x16x32_bf16 v[6:9], v[198:201], v[238:241], v[6:9]
	v_mfma_f32_16x16x32_bf16 v[2:5], v[206:209], v[238:241], v[2:5]
	s_setprio 0
	s_barrier
	s_movk_i32 s36, 0x100
	s_andn2_b64 vcc, exec, s[0:1]
	s_mov_b64 s[52:53], -1
	s_mov_b64 s[0:1], 0
	s_cbranch_vccz .LBB0_424
	s_and_b64 vcc, exec, s[40:41]
	s_cbranch_vccz .LBB0_427
	s_barrier

; #define PG8_STAGE(bufoff, gbase, voff) do { _Pragma("unroll") for (int _i = 0; _i < 2; ++_i) \
;         __builtin_amdgcn_global_load_lds((const unsigned*)((const char*)(gbase) + (voff)[_i]), (PG8_LAS unsigned*)(lds + (bufoff) + ldsw + _i * 8192), 16, 0, 0); } while (0)
; #define PG8_LDA(dst, b, h) do { _Pragma("unroll") for (int m = 0; m < 4; ++m) _Pragma("unroll") for (int k = 0; k < 2; ++k) dst[m][k] = *(const PG8_LAS bf16x8*)(lds + PG8_SA(b, h) + aoff + m * 2048 + k * 1024); } while (0)
; #define PG8_LDB(dst, b, h) do { _Pragma("unroll") for (int n = 0; n < 2; ++n) _Pragma("unroll") for (int k = 0; k < 2; ++k) dst[n][k] = *(const PG8_LAS bf16x8*)(lds + PG8_SB(b, h) + boff + n * 2048 + k * 1024); } while (0)
; #define PG8_MMA(ai, bj, At, Bt) do { __builtin_amdgcn_s_setprio(1); _Pragma("unroll") for (int m = 0; m < 4; ++m) _Pragma("unroll") for (int n = 0; n < 2; ++n) _Pragma("unroll") for (int k = 0; k < 2; ++k) \
;         acc[ai][bj][m][n] = __builtin_amdgcn_mfma_f32_16x16x32_bf16(Bt[n][k], At[m][k], acc[ai][bj][m][n], 0, 0, 0); __builtin_amdgcn_s_setprio(0); } while (0)
; #define PG8_WAIT_V(n) asm volatile("s_waitcnt vmcnt(" #n ")" ::: "memory")
; #define PG8_WAIT_L(n) asm volatile("s_waitcnt lgkmcnt(" #n ")" ::: "memory")
; template <class Epi, class Sched, bool ALIGN_EPI = false, bool SP2 = false>
; __device__ __forceinline__ void gemm_phase(PG8_LAS unsigned char* lds, const Gemm g, const Sched& S, const Epi& E) {
;     ...
;             const bool last = (t == nt - 2);
;             const char* a1 = cA + (size_t)(t + 1) * kstep;
;             const char* a2 = last ? nA : cA + (size_t)(t + 2) * kstep; const char* b2 = last ? nB : cB + (size_t)(t + 2) * kstep;
;             const char* a3 = a2 + kstep; const char* b3 = b2 + kstep;
;             if (last && has_next) S.a_ready(nxt);
;             if constexpr (SP2) {
;             PG8_LDB(B0, 0, 0); PG8_LDB(B1, 0, 1); PG8_SCHED; PG8_LDA(At, 0, 0); PG8_STAGE(PG8_SA(1, 1), a1 + hstepA, voffA);
;             PG8_WAIT_V(8); PG8_WAIT_L(0); PG8_BAR; PG8_MMA(0, 0, At, B0); PG8_MMA(0, 1, At, B1); PG8_BAR; PG8_SCHED;
;             PG8_LDA(At, 0, 1); PG8_STAGE(PG8_SB(0, 0), b2, voffB); PG8_STAGE(PG8_SB(0, 1), b2 + hstepB, voffB); PG8_STAGE(PG8_SA(0, 0), a2, voffA);
;             PG8_WAIT_V(8); PG8_WAIT_L(0); PG8_BAR; PG8_MMA(1, 0, At, B0); PG8_MMA(1, 1, At, B1); PG8_BAR; PG8_SCHED;
.LBB0_603:
	s_add_u32 s10, s50, 0xfffc0080
	s_addc_u32 s11, s51, -1
	s_add_i32 s12, 0, 0x10000
	s_cmp_eq_u32 s95, 12
	s_cselect_b32 s55, s45, s11
	s_cselect_b32 s54, s90, s10
	v_add_u32_e32 v130, s12, v163
	s_cselect_b32 s53, s4, s94
	s_cselect_b32 s52, s43, s91
	s_add_i32 s13, 0, 0x14000
	ds_read_b128 v[166:169], v130
	ds_read_b128 v[170:173], v130 offset:1024
	ds_read_b128 v[186:189], v130 offset:2048
	ds_read_b128 v[190:193], v130 offset:3072
	v_add_u32_e32 v130, s13, v163
	ds_read_b128 v[198:201], v130
	ds_read_b128 v[202:205], v130 offset:1024
	ds_read_b128 v[206:209], v130 offset:2048
	ds_read_b128 v[210:213], v130 offset:3072
	v_lshl_add_u64 v[130:131], s[50:51], 0, v[156:157]
	s_add_i32 m0, s31, 0xc000
	ds_read_b128 v[214:217], v165
	ds_read_b128 v[218:221], v165 offset:1024
	ds_read_b128 v[222:225], v165 offset:2048
	ds_read_b128 v[226:229], v165 offset:3072
	ds_read_b128 v[230:233], v165 offset:4096
	ds_read_b128 v[234:237], v165 offset:5120
	ds_read_b128 v[238:241], v165 offset:6144
	ds_read_b128 v[242:245], v165 offset:7168
	global_load_lds_dwordx4 v[130:131], off
	v_lshl_add_u64 v[130:131], s[50:51], 0, v[158:159]
	s_add_i32 m0, s31, 0xe000
	s_nop 0
	global_load_lds_dwordx4 v[130:131], off
	s_waitcnt vmcnt(8)
	s_waitcnt lgkmcnt(0)
	s_barrier
	s_setprio 1
	v_mfma_f32_16x16x32_bf16 v[126:129], v[166:169], v[214:217], v[126:129]
	v_mfma_f32_16x16x32_bf16 v[122:125], v[186:189], v[214:217], v[122:125]
	v_mfma_f32_16x16x32_bf16 v[110:113], v[166:169], v[222:225], v[110:113]
	v_mfma_f32_16x16x32_bf16 v[106:109], v[186:189], v[222:225], v[106:109]
	v_mfma_f32_16x16x32_bf16 v[94:97], v[166:169], v[230:233], v[94:97]
	v_mfma_f32_16x16x32_bf16 v[90:93], v[186:189], v[230:233], v[90:93]
	v_mfma_f32_16x16x32_bf16 v[78:81], v[166:169], v[238:241], v[78:81]
	v_mfma_f32_16x16x32_bf16 v[74:77], v[186:189], v[238:241], v[74:77]
	v_mfma_f32_16x16x32_bf16 v[126:129], v[170:173], v[218:221], v[126:129]
	v_mfma_f32_16x16x32_bf16 v[122:125], v[190:193], v[218:221], v[122:125]
	v_mfma_f32_16x16x32_bf16 v[110:113], v[170:173], v[226:229], v[110:113]
	v_mfma_f32_16x16x32_bf16 v[106:109], v[190:193], v[226:229], v[106:109]
	v_mfma_f32_16x16x32_bf16 v[94:97], v[170:173], v[234:237], v[94:97]
	v_mfma_f32_16x16x32_bf16 v[90:93], v[190:193], v[234:237], v[90:93]
	v_mfma_f32_16x16x32_bf16 v[78:81], v[170:173], v[242:245], v[78:81]
	v_mfma_f32_16x16x32_bf16 v[74:77], v[190:193], v[242:245], v[74:77]
	s_setprio 0
	s_setprio 1
	v_mfma_f32_16x16x32_bf16 v[118:121], v[198:201], v[214:217], v[118:121]
	v_mfma_f32_16x16x32_bf16 v[114:117], v[206:209], v[214:217], v[114:117]
	v_mfma_f32_16x16x32_bf16 v[102:105], v[198:201], v[222:225], v[102:105]
	v_mfma_f32_16x16x32_bf16 v[98:101], v[206:209], v[222:225], v[98:101]
	v_mfma_f32_16x16x32_bf16 v[86:89], v[198:201], v[230:233], v[86:89]
	v_mfma_f32_16x16x32_bf16 v[82:85], v[206:209], v[230:233], v[82:85]
	v_mfma_f32_16x16x32_bf16 v[70:73], v[198:201], v[238:241], v[70:73]
	v_mfma_f32_16x16x32_bf16 v[66:69], v[206:209], v[238:241], v[66:69]
	v_mfma_f32_16x16x32_bf16 v[118:121], v[202:205], v[218:221], v[118:121]
	v_mfma_f32_16x16x32_bf16 v[114:117], v[210:213], v[218:221], v[114:117]
	v_mfma_f32_16x16x32_bf16 v[102:105], v[202:205], v[226:229], v[102:105]
	v_mfma_f32_16x16x32_bf16 v[98:101], v[210:213], v[226:229], v[98:101]
	v_mfma_f32_16x16x32_bf16 v[86:89], v[202:205], v[234:237], v[86:89]
	v_mfma_f32_16x16x32_bf16 v[82:85], v[210:213], v[234:237], v[82:85]
	v_mfma_f32_16x16x32_bf16 v[70:73], v[202:205], v[242:245], v[70:73]
	v_mfma_f32_16x16x32_bf16 v[66:69], v[210:213], v[242:245], v[66:69]
	s_setprio 0
	s_barrier
	s_add_i32 s10, s12, s30
	v_lshl_add_u64 v[130:131], s[52:53], 0, v[0:1]
	s_mov_b32 m0, s10
	ds_read_b128 v[214:217], v165 offset:16384
	ds_read_b128 v[218:221], v165 offset:17408
	ds_read_b128 v[222:225], v165 offset:18432
	ds_read_b128 v[226:229], v165 offset:19456
	ds_read_b128 v[230:233], v165 offset:20480
	ds_read_b128 v[234:237], v165 offset:21504
	ds_read_b128 v[238:241], v165 offset:22528
	ds_read_b128 v[242:245], v165 offset:23552
	global_load_lds_dwordx4 v[130:131], off
	s_add_i32 m0, s10, 0x2000
	s_add_u32 s10, s52, 0x40000
	v_lshl_add_u64 v[132:133], s[52:53], 0, v[150:151]
	s_addc_u32 s11, s53, 0
	s_add_i32 s12, s13, s30
	global_load_lds_dwordx4 v[132:133], off
	v_lshl_add_u64 v[160:161], s[10:11], 0, v[0:1]
	s_mov_b32 m0, s12
	v_lshl_add_u64 v[246:247], s[54:55], 0, v[152:153]
	global_load_lds_dwordx4 v[160:161], off
	v_lshl_add_u64 v[160:161], s[10:11], 0, v[150:151]
	s_add_i32 m0, s12, 0x2000
	s_nop 0
	global_load_lds_dwordx4 v[160:161], off
	v_lshl_add_u64 v[160:161], s[54:55], 0, v[154:155]
	s_mov_b32 m0, s31
	s_nop 0
	global_load_lds_dwordx4 v[160:161], off
	s_mov_b32 m0, s34
	s_nop 0
	global_load_lds_dwordx4 v[246:247], off
	s_waitcnt vmcnt(8)
	s_waitcnt lgkmcnt(0)
	s_barrier
; #define PG8_STAGE(bufoff, gbase, voff) do { _Pragma("unroll") for (int _i = 0; _i < 2; ++_i) \
;         __builtin_amdgcn_global_load_lds((const unsigned*)((const char*)(gbase) + (voff)[_i]), (PG8_LAS unsigned*)(lds + (bufoff) + ldsw + _i * 8192), 16, 0, 0); } while (0)
; #define PG8_LDA(dst, b, h) do { _Pragma("unroll") for (int m = 0; m < 4; ++m) _Pragma("unroll") for (int k = 0; k < 2; ++k) dst[m][k] = *(const PG8_LAS bf16x8*)(lds + PG8_SA(b, h) + aoff + m * 2048 + k * 1024); } while (0)
; #define PG8_LDB(dst, b, h) do { _Pragma("unroll") for (int n = 0; n < 2; ++n) _Pragma("unroll") for (int k = 0; k < 2; ++k) dst[n][k] = *(const PG8_LAS bf16x8*)(lds + PG8_SB(b, h) + boff + n * 2048 + k * 1024); } while (0)
; #define PG8_MMA(ai, bj, At, Bt) do { __builtin_amdgcn_s_setprio(1); _Pragma("unroll") for (int m = 0; m < 4; ++m) _Pragma("unroll") for (int n = 0; n < 2; ++n) _Pragma("unroll") for (int k = 0; k < 2; ++k) \
;         acc[ai][bj][m][n] = __builtin_amdgcn_mfma_f32_16x16x32_bf16(Bt[n][k], At[m][k], acc[ai][bj][m][n], 0, 0, 0); __builtin_amdgcn_s_setprio(0); } while (0)
; #define PG8_WAIT_V(n) asm volatile("s_waitcnt vmcnt(" #n ")" ::: "memory")
; #define PG8_WAIT_L(n) asm volatile("s_waitcnt lgkmcnt(" #n ")" ::: "memory")
; #define PG8_BAR __builtin_amdgcn_s_barrier()
; #define PG8_SCHED __builtin_amdgcn_sched_barrier(0)
; template <class Epi, class Sched, bool ALIGN_EPI = false, bool SP2 = false>
; __device__ __forceinline__ void gemm_phase(PG8_LAS unsigned char* lds, const Gemm g, const Sched& S, const Epi& E) {
;     ...
;             PG8_WAIT_V(8); PG8_WAIT_L(0); PG8_BAR; PG8_MMA(1, 0, At, B0); PG8_MMA(1, 1, At, B1); PG8_BAR; PG8_SCHED;
;             PG8_LDB(B0, 1, 0); PG8_LDB(B1, 1, 1); PG8_SCHED; PG8_LDA(At, 1, 0); PG8_STAGE(PG8_SA(0, 1), a2 + hstepA, voffA);
;             PG8_WAIT_V(8); PG8_WAIT_L(0); PG8_BAR; PG8_MMA(0, 0, At, B0); PG8_MMA(0, 1, At, B1); PG8_BAR; PG8_SCHED;
	s_setprio 1
	v_mfma_f32_16x16x32_bf16 v[62:65], v[166:169], v[214:217], v[62:65]
	v_mfma_f32_16x16x32_bf16 v[58:61], v[186:189], v[214:217], v[58:61]
	v_mfma_f32_16x16x32_bf16 v[46:49], v[166:169], v[222:225], v[46:49]
	v_mfma_f32_16x16x32_bf16 v[42:45], v[186:189], v[222:225], v[42:45]
	v_mfma_f32_16x16x32_bf16 v[30:33], v[166:169], v[230:233], v[30:33]
	v_mfma_f32_16x16x32_bf16 v[26:29], v[186:189], v[230:233], v[26:29]
	v_mfma_f32_16x16x32_bf16 v[14:17], v[166:169], v[238:241], v[14:17]
	v_mfma_f32_16x16x32_bf16 v[10:13], v[186:189], v[238:241], v[10:13]
	v_mfma_f32_16x16x32_bf16 v[62:65], v[170:173], v[218:221], v[62:65]
	v_mfma_f32_16x16x32_bf16 v[58:61], v[190:193], v[218:221], v[58:61]
	v_mfma_f32_16x16x32_bf16 v[46:49], v[170:173], v[226:229], v[46:49]
	v_mfma_f32_16x16x32_bf16 v[42:45], v[190:193], v[226:229], v[42:45]
	v_mfma_f32_16x16x32_bf16 v[30:33], v[170:173], v[234:237], v[30:33]
	v_mfma_f32_16x16x32_bf16 v[26:29], v[190:193], v[234:237], v[26:29]
	v_mfma_f32_16x16x32_bf16 v[14:17], v[170:173], v[242:245], v[14:17]
	v_mfma_f32_16x16x32_bf16 v[10:13], v[190:193], v[242:245], v[10:13]
	s_setprio 0
	s_setprio 1
	v_mfma_f32_16x16x32_bf16 v[54:57], v[198:201], v[214:217], v[54:57]
	v_mfma_f32_16x16x32_bf16 v[50:53], v[206:209], v[214:217], v[50:53]
	v_mfma_f32_16x16x32_bf16 v[38:41], v[198:201], v[222:225], v[38:41]
	v_mfma_f32_16x16x32_bf16 v[34:37], v[206:209], v[222:225], v[34:37]
	v_mfma_f32_16x16x32_bf16 v[22:25], v[198:201], v[230:233], v[22:25]
	v_mfma_f32_16x16x32_bf16 v[18:21], v[206:209], v[230:233], v[18:21]
	v_mfma_f32_16x16x32_bf16 v[6:9], v[198:201], v[238:241], v[6:9]
	v_mfma_f32_16x16x32_bf16 v[2:5], v[206:209], v[238:241], v[2:5]
	v_mfma_f32_16x16x32_bf16 v[54:57], v[202:205], v[218:221], v[54:57]
	v_mfma_f32_16x16x32_bf16 v[50:53], v[210:213], v[218:221], v[50:53]
	v_mfma_f32_16x16x32_bf16 v[38:41], v[202:205], v[226:229], v[38:41]
	v_mfma_f32_16x16x32_bf16 v[34:37], v[210:213], v[226:229], v[34:37]
	v_mfma_f32_16x16x32_bf16 v[22:25], v[202:205], v[234:237], v[22:25]
	v_mfma_f32_16x16x32_bf16 v[18:21], v[210:213], v[234:237], v[18:21]
	v_mfma_f32_16x16x32_bf16 v[6:9], v[202:205], v[242:245], v[6:9]
	v_mfma_f32_16x16x32_bf16 v[2:5], v[210:213], v[242:245], v[2:5]
	s_setprio 0
	s_barrier
	s_add_i32 s12, 0, 0x18000
	s_add_i32 s13, 0, 0x1c000
	v_add_u32_e32 v190, s12, v163
	v_add_u32_e32 v210, s13, v163
	ds_read_b128 v[166:169], v190
	ds_read_b128 v[170:173], v190 offset:1024
	ds_read_b128 v[186:189], v190 offset:2048
	ds_read_b128 v[190:193], v190 offset:3072
	ds_read_b128 v[198:201], v210
	ds_read_b128 v[202:205], v210 offset:1024
	ds_read_b128 v[206:209], v210 offset:2048
	ds_read_b128 v[210:213], v210 offset:3072
	s_add_u32 s10, s54, 0x40000
	s_addc_u32 s11, s55, 0
	s_mov_b32 m0, s35
	v_lshl_add_u64 v[248:249], s[10:11], 0, v[154:155]
	ds_read_b128 v[214:217], v165 offset:32768
	ds_read_b128 v[218:221], v165 offset:33792
	ds_read_b128 v[222:225], v165 offset:34816
	ds_read_b128 v[226:229], v165 offset:35840
	ds_read_b128 v[230:233], v165 offset:36864
	ds_read_b128 v[234:237], v165 offset:37888
	ds_read_b128 v[238:241], v165 offset:38912
	ds_read_b128 v[242:245], v165 offset:39936
	global_load_lds_dwordx4 v[248:249], off
	v_lshl_add_u64 v[248:249], s[10:11], 0, v[152:153]
	s_mov_b32 m0, s56
	s_nop 0
	global_load_lds_dwordx4 v[248:249], off
	s_waitcnt vmcnt(8)
	s_waitcnt lgkmcnt(0)
	s_barrier
	s_setprio 1
	v_mfma_f32_16x16x32_bf16 v[126:129], v[166:169], v[214:217], v[126:129]
	v_mfma_f32_16x16x32_bf16 v[122:125], v[186:189], v[214:217], v[122:125]
	v_mfma_f32_16x16x32_bf16 v[110:113], v[166:169], v[222:225], v[110:113]
	v_mfma_f32_16x16x32_bf16 v[106:109], v[186:189], v[222:225], v[106:109]
	v_mfma_f32_16x16x32_bf16 v[94:97], v[166:169], v[230:233], v[94:97]
	v_mfma_f32_16x16x32_bf16 v[90:93], v[186:189], v[230:233], v[90:93]
	v_mfma_f32_16x16x32_bf16 v[78:81], v[166:169], v[238:241], v[78:81]
	v_mfma_f32_16x16x32_bf16 v[74:77], v[186:189], v[238:241], v[74:77]
	v_mfma_f32_16x16x32_bf16 v[126:129], v[170:173], v[218:221], v[126:129]
	v_mfma_f32_16x16x32_bf16 v[122:125], v[190:193], v[218:221], v[122:125]
	v_mfma_f32_16x16x32_bf16 v[110:113], v[170:173], v[226:229], v[110:113]
	v_mfma_f32_16x16x32_bf16 v[106:109], v[190:193], v[226:229], v[106:109]
	v_mfma_f32_16x16x32_bf16 v[94:97], v[170:173], v[234:237], v[94:97]
	v_mfma_f32_16x16x32_bf16 v[90:93], v[190:193], v[234:237], v[90:93]
	v_mfma_f32_16x16x32_bf16 v[78:81], v[170:173], v[242:245], v[78:81]
	v_mfma_f32_16x16x32_bf16 v[74:77], v[190:193], v[242:245], v[74:77]
	s_setprio 0
	s_setprio 1
	v_mfma_f32_16x16x32_bf16 v[118:121], v[198:201], v[214:217], v[118:121]
	v_mfma_f32_16x16x32_bf16 v[114:117], v[206:209], v[214:217], v[114:117]
	v_mfma_f32_16x16x32_bf16 v[102:105], v[198:201], v[222:225], v[102:105]
	v_mfma_f32_16x16x32_bf16 v[98:101], v[206:209], v[222:225], v[98:101]
	v_mfma_f32_16x16x32_bf16 v[86:89], v[198:201], v[230:233], v[86:89]
	v_mfma_f32_16x16x32_bf16 v[82:85], v[206:209], v[230:233], v[82:85]
	v_mfma_f32_16x16x32_bf16 v[70:73], v[198:201], v[238:241], v[70:73]
	v_mfma_f32_16x16x32_bf16 v[66:69], v[206:209], v[238:241], v[66:69]
	v_mfma_f32_16x16x32_bf16 v[118:121], v[202:205], v[218:221], v[118:121]
	v_mfma_f32_16x16x32_bf16 v[114:117], v[210:213], v[218:221], v[114:117]
	v_mfma_f32_16x16x32_bf16 v[102:105], v[202:205], v[226:229], v[102:105]
	v_mfma_f32_16x16x32_bf16 v[98:101], v[210:213], v[226:229], v[98:101]
	v_mfma_f32_16x16x32_bf16 v[86:89], v[202:205], v[234:237], v[86:89]
	v_mfma_f32_16x16x32_bf16 v[82:85], v[210:213], v[234:237], v[82:85]
	v_mfma_f32_16x16x32_bf16 v[70:73], v[202:205], v[242:245], v[70:73]
	v_mfma_f32_16x16x32_bf16 v[66:69], v[210:213], v[242:245], v[66:69]
	s_setprio 0
	s_barrier
; #define PG8_STAGE(bufoff, gbase, voff) do { _Pragma("unroll") for (int _i = 0; _i < 2; ++_i) \
;         __builtin_amdgcn_global_load_lds((const unsigned*)((const char*)(gbase) + (voff)[_i]), (PG8_LAS unsigned*)(lds + (bufoff) + ldsw + _i * 8192), 16, 0, 0); } while (0)
; #define PG8_LDA(dst, b, h) do { _Pragma("unroll") for (int m = 0; m < 4; ++m) _Pragma("unroll") for (int k = 0; k < 2; ++k) dst[m][k] = *(const PG8_LAS bf16x8*)(lds + PG8_SA(b, h) + aoff + m * 2048 + k * 1024); } while (0)
; #define PG8_MMA(ai, bj, At, Bt) do { __builtin_amdgcn_s_setprio(1); _Pragma("unroll") for (int m = 0; m < 4; ++m) _Pragma("unroll") for (int n = 0; n < 2; ++n) _Pragma("unroll") for (int k = 0; k < 2; ++k) \
;         acc[ai][bj][m][n] = __builtin_amdgcn_mfma_f32_16x16x32_bf16(Bt[n][k], At[m][k], acc[ai][bj][m][n], 0, 0, 0); __builtin_amdgcn_s_setprio(0); } while (0)
; #define PG8_WAIT_V(n) asm volatile("s_waitcnt vmcnt(" #n ")" ::: "memory")
; #define PG8_WAIT_L(n) asm volatile("s_waitcnt lgkmcnt(" #n ")" ::: "memory")
; #define PG8_BAR __builtin_amdgcn_s_barrier()
; #define PG8_SCHED __builtin_amdgcn_sched_barrier(0)
; template <class Epi, class Sched, bool ALIGN_EPI = false, bool SP2 = false>
; __device__ __forceinline__ void gemm_phase(PG8_LAS unsigned char* lds, const Gemm g, const Sched& S, const Epi& E) {
;     ...
;             PG8_LDA(At, 1, 1); PG8_STAGE(PG8_SB(1, 0), b3, voffB); PG8_STAGE(PG8_SB(1, 1), b3 + hstepB, voffB); PG8_STAGE(PG8_SA(1, 0), a3, voffA);
;             PG8_WAIT_V(8); PG8_WAIT_L(0); PG8_BAR; PG8_MMA(1, 0, At, B0); PG8_MMA(1, 1, At, B1); PG8_BAR; PG8_SCHED;
;     ...
;         if constexpr (ALIGN_EPI) { if (wr == 0) PG8_BAR; }
	s_add_i32 s10, s12, s30
	v_lshl_add_u64 v[130:131], v[130:131], 0, s[2:3]
	s_mov_b32 m0, s10
	ds_read_b128 v[214:217], v165 offset:49152
	ds_read_b128 v[218:221], v165 offset:50176
	ds_read_b128 v[222:225], v165 offset:51200
	ds_read_b128 v[226:229], v165 offset:52224
	ds_read_b128 v[230:233], v165 offset:53248
	ds_read_b128 v[234:237], v165 offset:54272
	ds_read_b128 v[238:241], v165 offset:55296
	ds_read_b128 v[242:245], v165 offset:56320
	global_load_lds_dwordx4 v[130:131], off
	s_add_i32 m0, s10, 0x2000
	s_add_u32 s10, s52, 0x40080
	v_lshl_add_u64 v[130:131], v[132:133], 0, s[2:3]
	s_addc_u32 s11, s53, 0
	s_add_i32 s12, s13, s30
	global_load_lds_dwordx4 v[130:131], off
	v_lshl_add_u64 v[130:131], s[10:11], 0, v[0:1]
	s_mov_b32 m0, s12
	s_nop 0
	global_load_lds_dwordx4 v[130:131], off
	v_lshl_add_u64 v[130:131], s[10:11], 0, v[150:151]
	s_add_i32 m0, s12, 0x2000
	s_nop 0
	global_load_lds_dwordx4 v[130:131], off
	v_lshl_add_u64 v[130:131], v[160:161], 0, s[2:3]
	s_mov_b32 m0, s57
	s_nop 0
	global_load_lds_dwordx4 v[130:131], off
	v_lshl_add_u64 v[130:131], v[246:247], 0, s[2:3]
	s_mov_b32 m0, s62
	s_nop 0
	global_load_lds_dwordx4 v[130:131], off
	s_waitcnt vmcnt(8)
	s_waitcnt lgkmcnt(0)
	s_barrier
	s_setprio 1
	v_mfma_f32_16x16x32_bf16 v[62:65], v[166:169], v[214:217], v[62:65]
	v_mfma_f32_16x16x32_bf16 v[58:61], v[186:189], v[214:217], v[58:61]
	v_mfma_f32_16x16x32_bf16 v[46:49], v[166:169], v[222:225], v[46:49]
	v_mfma_f32_16x16x32_bf16 v[42:45], v[186:189], v[222:225], v[42:45]
	v_mfma_f32_16x16x32_bf16 v[30:33], v[166:169], v[230:233], v[30:33]
	v_mfma_f32_16x16x32_bf16 v[26:29], v[186:189], v[230:233], v[26:29]
	v_mfma_f32_16x16x32_bf16 v[14:17], v[166:169], v[238:241], v[14:17]
	v_mfma_f32_16x16x32_bf16 v[10:13], v[186:189], v[238:241], v[10:13]
	v_mfma_f32_16x16x32_bf16 v[62:65], v[170:173], v[218:221], v[62:65]
	v_mfma_f32_16x16x32_bf16 v[58:61], v[190:193], v[218:221], v[58:61]
	v_mfma_f32_16x16x32_bf16 v[46:49], v[170:173], v[226:229], v[46:49]
	v_mfma_f32_16x16x32_bf16 v[42:45], v[190:193], v[226:229], v[42:45]
	v_mfma_f32_16x16x32_bf16 v[30:33], v[170:173], v[234:237], v[30:33]
	v_mfma_f32_16x16x32_bf16 v[26:29], v[190:193], v[234:237], v[26:29]
	v_mfma_f32_16x16x32_bf16 v[14:17], v[170:173], v[242:245], v[14:17]
	v_mfma_f32_16x16x32_bf16 v[10:13], v[190:193], v[242:245], v[10:13]
	s_setprio 0
	s_setprio 1
	v_mfma_f32_16x16x32_bf16 v[54:57], v[198:201], v[214:217], v[54:57]
	v_mfma_f32_16x16x32_bf16 v[50:53], v[206:209], v[214:217], v[50:53]
	v_mfma_f32_16x16x32_bf16 v[38:41], v[198:201], v[222:225], v[38:41]
	v_mfma_f32_16x16x32_bf16 v[34:37], v[206:209], v[222:225], v[34:37]
	v_mfma_f32_16x16x32_bf16 v[22:25], v[198:201], v[230:233], v[22:25]
	v_mfma_f32_16x16x32_bf16 v[18:21], v[206:209], v[230:233], v[18:21]
	v_mfma_f32_16x16x32_bf16 v[6:9], v[198:201], v[238:241], v[6:9]
	v_mfma_f32_16x16x32_bf16 v[2:5], v[206:209], v[238:241], v[2:5]
	v_mfma_f32_16x16x32_bf16 v[54:57], v[202:205], v[218:221], v[54:57]
	v_mfma_f32_16x16x32_bf16 v[50:53], v[210:213], v[218:221], v[50:53]
	v_mfma_f32_16x16x32_bf16 v[38:41], v[202:205], v[226:229], v[38:41]
	v_mfma_f32_16x16x32_bf16 v[34:37], v[210:213], v[226:229], v[34:37]
	v_mfma_f32_16x16x32_bf16 v[22:25], v[202:205], v[234:237], v[22:25]
	v_mfma_f32_16x16x32_bf16 v[18:21], v[210:213], v[234:237], v[18:21]
	v_mfma_f32_16x16x32_bf16 v[6:9], v[202:205], v[242:245], v[6:9]
	v_mfma_f32_16x16x32_bf16 v[2:5], v[210:213], v[242:245], v[2:5]
	s_setprio 0
	s_barrier
	s_add_i32 s95, s95, 2
	s_add_u32 s50, s50, 0x100
	s_addc_u32 s51, s51, 0
	s_add_u32 s91, s91, 0x100
	s_addc_u32 s94, s94, 0
	s_cmp_gt_u32 s95, 13
	s_cbranch_scc0 .LBB0_603
	s_and_b64 vcc, exec, s[40:41]
	s_cbranch_vccz .LBB0_606
	s_barrier

; #define PG8_STAGE(bufoff, gbase, voff) do { _Pragma("unroll") for (int _i = 0; _i < 2; ++_i) \
;         __builtin_amdgcn_global_load_lds((const unsigned*)((const char*)(gbase) + (voff)[_i]), (PG8_LAS unsigned*)(lds + (bufoff) + ldsw + _i * 8192), 16, 0, 0); } while (0)
; #define PG8_LDA(dst, b, h) do { _Pragma("unroll") for (int m = 0; m < 4; ++m) _Pragma("unroll") for (int k = 0; k < 2; ++k) dst[m][k] = *(const PG8_LAS bf16x8*)(lds + PG8_SA(b, h) + aoff + m * 2048 + k * 1024); } while (0)
; #define PG8_LDB(dst, b, h) do { _Pragma("unroll") for (int n = 0; n < 2; ++n) _Pragma("unroll") for (int k = 0; k < 2; ++k) dst[n][k] = *(const PG8_LAS bf16x8*)(lds + PG8_SB(b, h) + boff + n * 2048 + k * 1024); } while (0)
; #define PG8_MMA(ai, bj, At, Bt) do { __builtin_amdgcn_s_setprio(1); _Pragma("unroll") for (int m = 0; m < 4; ++m) _Pragma("unroll") for (int n = 0; n < 2; ++n) _Pragma("unroll") for (int k = 0; k < 2; ++k) \
;         acc[ai][bj][m][n] = __builtin_amdgcn_mfma_f32_16x16x32_bf16(Bt[n][k], At[m][k], acc[ai][bj][m][n], 0, 0, 0); __builtin_amdgcn_s_setprio(0); } while (0)
; #define PG8_WAIT_V(n) asm volatile("s_waitcnt vmcnt(" #n ")" ::: "memory")
; #define PG8_WAIT_L(n) asm volatile("s_waitcnt lgkmcnt(" #n ")" ::: "memory")
; template <class Epi, class Sched, bool ALIGN_EPI = false, bool SP2 = false>
; __device__ __forceinline__ void gemm_phase(PG8_LAS unsigned char* lds, const Gemm g, const Sched& S, const Epi& E) {
;     ...
;             const bool last = (t == nt - 2);
;             const char* a1 = cA + (size_t)(t + 1) * kstep;
;             const char* a2 = last ? nA : cA + (size_t)(t + 2) * kstep; const char* b2 = last ? nB : cB + (size_t)(t + 2) * kstep;
;             const char* a3 = a2 + kstep; const char* b3 = b2 + kstep;
;             if (last && has_next) S.a_ready(nxt);
;             if constexpr (SP2) {
;             PG8_LDB(B0, 0, 0); PG8_LDB(B1, 0, 1); PG8_SCHED; PG8_LDA(At, 0, 0); PG8_STAGE(PG8_SA(1, 1), a1 + hstepA, voffA);
;             PG8_WAIT_V(8); PG8_WAIT_L(0); PG8_BAR; PG8_MMA(0, 0, At, B0); PG8_MMA(0, 1, At, B1); PG8_BAR; PG8_SCHED;
;             PG8_LDA(At, 0, 1); PG8_STAGE(PG8_SB(0, 0), b2, voffB); PG8_STAGE(PG8_SB(0, 1), b2 + hstepB, voffB); PG8_STAGE(PG8_SA(0, 0), a2, voffA);
;             PG8_WAIT_V(8); PG8_WAIT_L(0); PG8_BAR; PG8_MMA(1, 0, At, B0); PG8_MMA(1, 1, At, B1); PG8_BAR; PG8_SCHED;
.LBB0_623:
	s_add_u32 s10, s54, 0xfffe0080
	s_addc_u32 s11, s55, -1
	s_add_i32 s12, 0, 0x10000
	s_cmp_eq_u32 vcc_hi, 4
	s_cselect_b32 s63, s41, s11
	s_cselect_b32 s62, s47, s10
	v_add_u32_e32 v130, s12, v169
	s_cselect_b32 s57, s4, vcc_lo
	s_cselect_b32 s56, s45, s91
	s_add_i32 s13, 0, 0x14000
	ds_read_b128 v[160:163], v130
	ds_read_b128 v[164:167], v130 offset:1024
	ds_read_b128 v[186:189], v130 offset:2048
	ds_read_b128 v[190:193], v130 offset:3072
	v_add_u32_e32 v130, s13, v169
	ds_read_b128 v[198:201], v130
	ds_read_b128 v[202:205], v130 offset:1024
	ds_read_b128 v[206:209], v130 offset:2048
	ds_read_b128 v[210:213], v130 offset:3072
	v_lshl_add_u64 v[130:131], s[54:55], 0, v[156:157]
	s_add_i32 m0, s53, 0xc000
	ds_read_b128 v[214:217], v171
	ds_read_b128 v[218:221], v171 offset:1024
	ds_read_b128 v[222:225], v171 offset:2048
	ds_read_b128 v[226:229], v171 offset:3072
	ds_read_b128 v[230:233], v171 offset:4096
	ds_read_b128 v[234:237], v171 offset:5120
	ds_read_b128 v[238:241], v171 offset:6144
	ds_read_b128 v[242:245], v171 offset:7168
	global_load_lds_dwordx4 v[130:131], off
	v_lshl_add_u64 v[130:131], s[54:55], 0, v[158:159]
	s_add_i32 m0, s53, 0xe000
	s_nop 0
	global_load_lds_dwordx4 v[130:131], off
	s_waitcnt vmcnt(8)
	s_waitcnt lgkmcnt(0)
	s_barrier
	s_setprio 1
	v_mfma_f32_16x16x32_bf16 v[126:129], v[160:163], v[214:217], v[126:129]
	v_mfma_f32_16x16x32_bf16 v[122:125], v[186:189], v[214:217], v[122:125]
	v_mfma_f32_16x16x32_bf16 v[110:113], v[160:163], v[222:225], v[110:113]
	v_mfma_f32_16x16x32_bf16 v[106:109], v[186:189], v[222:225], v[106:109]
	v_mfma_f32_16x16x32_bf16 v[94:97], v[160:163], v[230:233], v[94:97]
	v_mfma_f32_16x16x32_bf16 v[90:93], v[186:189], v[230:233], v[90:93]
	v_mfma_f32_16x16x32_bf16 v[78:81], v[160:163], v[238:241], v[78:81]
	v_mfma_f32_16x16x32_bf16 v[74:77], v[186:189], v[238:241], v[74:77]
	v_mfma_f32_16x16x32_bf16 v[126:129], v[164:167], v[218:221], v[126:129]
	v_mfma_f32_16x16x32_bf16 v[122:125], v[190:193], v[218:221], v[122:125]
	v_mfma_f32_16x16x32_bf16 v[110:113], v[164:167], v[226:229], v[110:113]
	v_mfma_f32_16x16x32_bf16 v[106:109], v[190:193], v[226:229], v[106:109]
	v_mfma_f32_16x16x32_bf16 v[94:97], v[164:167], v[234:237], v[94:97]
	v_mfma_f32_16x16x32_bf16 v[90:93], v[190:193], v[234:237], v[90:93]
	v_mfma_f32_16x16x32_bf16 v[78:81], v[164:167], v[242:245], v[78:81]
	v_mfma_f32_16x16x32_bf16 v[74:77], v[190:193], v[242:245], v[74:77]
	s_setprio 0
	s_setprio 1
	v_mfma_f32_16x16x32_bf16 v[118:121], v[198:201], v[214:217], v[118:121]
	v_mfma_f32_16x16x32_bf16 v[114:117], v[206:209], v[214:217], v[114:117]
	v_mfma_f32_16x16x32_bf16 v[102:105], v[198:201], v[222:225], v[102:105]
	v_mfma_f32_16x16x32_bf16 v[98:101], v[206:209], v[222:225], v[98:101]
	v_mfma_f32_16x16x32_bf16 v[86:89], v[198:201], v[230:233], v[86:89]
	v_mfma_f32_16x16x32_bf16 v[82:85], v[206:209], v[230:233], v[82:85]
	v_mfma_f32_16x16x32_bf16 v[70:73], v[198:201], v[238:241], v[70:73]
	v_mfma_f32_16x16x32_bf16 v[66:69], v[206:209], v[238:241], v[66:69]
	v_mfma_f32_16x16x32_bf16 v[118:121], v[202:205], v[218:221], v[118:121]
	v_mfma_f32_16x16x32_bf16 v[114:117], v[210:213], v[218:221], v[114:117]
	v_mfma_f32_16x16x32_bf16 v[102:105], v[202:205], v[226:229], v[102:105]
	v_mfma_f32_16x16x32_bf16 v[98:101], v[210:213], v[226:229], v[98:101]
	v_mfma_f32_16x16x32_bf16 v[86:89], v[202:205], v[234:237], v[86:89]
	v_mfma_f32_16x16x32_bf16 v[82:85], v[210:213], v[234:237], v[82:85]
	v_mfma_f32_16x16x32_bf16 v[70:73], v[202:205], v[242:245], v[70:73]
	v_mfma_f32_16x16x32_bf16 v[66:69], v[210:213], v[242:245], v[66:69]
	s_setprio 0
	s_barrier
	s_add_i32 s10, s12, s68
	v_lshl_add_u64 v[130:131], s[56:57], 0, v[0:1]
	s_mov_b32 m0, s10
	ds_read_b128 v[214:217], v171 offset:16384
	ds_read_b128 v[218:221], v171 offset:17408
	ds_read_b128 v[222:225], v171 offset:18432
	ds_read_b128 v[226:229], v171 offset:19456
	ds_read_b128 v[230:233], v171 offset:20480
	ds_read_b128 v[234:237], v171 offset:21504
	ds_read_b128 v[238:241], v171 offset:22528
	ds_read_b128 v[242:245], v171 offset:23552
	global_load_lds_dwordx4 v[130:131], off
	s_add_i32 m0, s10, 0x2000
	s_add_u32 s10, s56, 0x20000
	v_lshl_add_u64 v[132:133], s[56:57], 0, v[150:151]
	s_addc_u32 s11, s57, 0
	s_add_i32 s12, s13, s68
	global_load_lds_dwordx4 v[132:133], off
	v_lshl_add_u64 v[172:173], s[10:11], 0, v[0:1]
	s_mov_b32 m0, s12
	v_lshl_add_u64 v[246:247], s[62:63], 0, v[152:153]
	global_load_lds_dwordx4 v[172:173], off
	v_lshl_add_u64 v[172:173], s[10:11], 0, v[150:151]
	s_add_i32 m0, s12, 0x2000
	s_nop 0
	global_load_lds_dwordx4 v[172:173], off
	v_lshl_add_u64 v[172:173], s[62:63], 0, v[154:155]
	s_mov_b32 m0, s53
	s_nop 0
	global_load_lds_dwordx4 v[172:173], off
	s_mov_b32 m0, s69
	s_nop 0
	global_load_lds_dwordx4 v[246:247], off
	s_waitcnt vmcnt(8)
	s_waitcnt lgkmcnt(0)
	s_barrier
; #define PG8_STAGE(bufoff, gbase, voff) do { _Pragma("unroll") for (int _i = 0; _i < 2; ++_i) \
;         __builtin_amdgcn_global_load_lds((const unsigned*)((const char*)(gbase) + (voff)[_i]), (PG8_LAS unsigned*)(lds + (bufoff) + ldsw + _i * 8192), 16, 0, 0); } while (0)
; #define PG8_LDA(dst, b, h) do { _Pragma("unroll") for (int m = 0; m < 4; ++m) _Pragma("unroll") for (int k = 0; k < 2; ++k) dst[m][k] = *(const PG8_LAS bf16x8*)(lds + PG8_SA(b, h) + aoff + m * 2048 + k * 1024); } while (0)
; #define PG8_LDB(dst, b, h) do { _Pragma("unroll") for (int n = 0; n < 2; ++n) _Pragma("unroll") for (int k = 0; k < 2; ++k) dst[n][k] = *(const PG8_LAS bf16x8*)(lds + PG8_SB(b, h) + boff + n * 2048 + k * 1024); } while (0)
; #define PG8_MMA(ai, bj, At, Bt) do { __builtin_amdgcn_s_setprio(1); _Pragma("unroll") for (int m = 0; m < 4; ++m) _Pragma("unroll") for (int n = 0; n < 2; ++n) _Pragma("unroll") for (int k = 0; k < 2; ++k) \
;         acc[ai][bj][m][n] = __builtin_amdgcn_mfma_f32_16x16x32_bf16(Bt[n][k], At[m][k], acc[ai][bj][m][n], 0, 0, 0); __builtin_amdgcn_s_setprio(0); } while (0)
; #define PG8_WAIT_V(n) asm volatile("s_waitcnt vmcnt(" #n ")" ::: "memory")
; #define PG8_WAIT_L(n) asm volatile("s_waitcnt lgkmcnt(" #n ")" ::: "memory")
; #define PG8_BAR __builtin_amdgcn_s_barrier()
; #define PG8_SCHED __builtin_amdgcn_sched_barrier(0)
; template <class Epi, class Sched, bool ALIGN_EPI = false, bool SP2 = false>
; __device__ __forceinline__ void gemm_phase(PG8_LAS unsigned char* lds, const Gemm g, const Sched& S, const Epi& E) {
;     ...
;             PG8_WAIT_V(8); PG8_WAIT_L(0); PG8_BAR; PG8_MMA(1, 0, At, B0); PG8_MMA(1, 1, At, B1); PG8_BAR; PG8_SCHED;
;             PG8_LDB(B0, 1, 0); PG8_LDB(B1, 1, 1); PG8_SCHED; PG8_LDA(At, 1, 0); PG8_STAGE(PG8_SA(0, 1), a2 + hstepA, voffA);
;             PG8_WAIT_V(8); PG8_WAIT_L(0); PG8_BAR; PG8_MMA(0, 0, At, B0); PG8_MMA(0, 1, At, B1); PG8_BAR; PG8_SCHED;
	s_setprio 1
	v_mfma_f32_16x16x32_bf16 v[62:65], v[160:163], v[214:217], v[62:65]
	v_mfma_f32_16x16x32_bf16 v[58:61], v[186:189], v[214:217], v[58:61]
	v_mfma_f32_16x16x32_bf16 v[46:49], v[160:163], v[222:225], v[46:49]
	v_mfma_f32_16x16x32_bf16 v[42:45], v[186:189], v[222:225], v[42:45]
	v_mfma_f32_16x16x32_bf16 v[30:33], v[160:163], v[230:233], v[30:33]
	v_mfma_f32_16x16x32_bf16 v[26:29], v[186:189], v[230:233], v[26:29]
	v_mfma_f32_16x16x32_bf16 v[14:17], v[160:163], v[238:241], v[14:17]
	v_mfma_f32_16x16x32_bf16 v[10:13], v[186:189], v[238:241], v[10:13]
	v_mfma_f32_16x16x32_bf16 v[62:65], v[164:167], v[218:221], v[62:65]
	v_mfma_f32_16x16x32_bf16 v[58:61], v[190:193], v[218:221], v[58:61]
	v_mfma_f32_16x16x32_bf16 v[46:49], v[164:167], v[226:229], v[46:49]
	v_mfma_f32_16x16x32_bf16 v[42:45], v[190:193], v[226:229], v[42:45]
	v_mfma_f32_16x16x32_bf16 v[30:33], v[164:167], v[234:237], v[30:33]
	v_mfma_f32_16x16x32_bf16 v[26:29], v[190:193], v[234:237], v[26:29]
	v_mfma_f32_16x16x32_bf16 v[14:17], v[164:167], v[242:245], v[14:17]
	v_mfma_f32_16x16x32_bf16 v[10:13], v[190:193], v[242:245], v[10:13]
	s_setprio 0
	s_setprio 1
	v_mfma_f32_16x16x32_bf16 v[54:57], v[198:201], v[214:217], v[54:57]
	v_mfma_f32_16x16x32_bf16 v[50:53], v[206:209], v[214:217], v[50:53]
	v_mfma_f32_16x16x32_bf16 v[38:41], v[198:201], v[222:225], v[38:41]
	v_mfma_f32_16x16x32_bf16 v[34:37], v[206:209], v[222:225], v[34:37]
	v_mfma_f32_16x16x32_bf16 v[22:25], v[198:201], v[230:233], v[22:25]
	v_mfma_f32_16x16x32_bf16 v[18:21], v[206:209], v[230:233], v[18:21]
	v_mfma_f32_16x16x32_bf16 v[6:9], v[198:201], v[238:241], v[6:9]
	v_mfma_f32_16x16x32_bf16 v[2:5], v[206:209], v[238:241], v[2:5]
	v_mfma_f32_16x16x32_bf16 v[54:57], v[202:205], v[218:221], v[54:57]
	v_mfma_f32_16x16x32_bf16 v[50:53], v[210:213], v[218:221], v[50:53]
	v_mfma_f32_16x16x32_bf16 v[38:41], v[202:205], v[226:229], v[38:41]
	v_mfma_f32_16x16x32_bf16 v[34:37], v[210:213], v[226:229], v[34:37]
	v_mfma_f32_16x16x32_bf16 v[22:25], v[202:205], v[234:237], v[22:25]
	v_mfma_f32_16x16x32_bf16 v[18:21], v[210:213], v[234:237], v[18:21]
	v_mfma_f32_16x16x32_bf16 v[6:9], v[202:205], v[242:245], v[6:9]
	v_mfma_f32_16x16x32_bf16 v[2:5], v[210:213], v[242:245], v[2:5]
	s_setprio 0
	s_barrier
	s_add_i32 s12, 0, 0x18000
	s_add_i32 s13, 0, 0x1c000
	v_add_u32_e32 v190, s12, v169
	v_add_u32_e32 v210, s13, v169
	ds_read_b128 v[160:163], v190
	ds_read_b128 v[164:167], v190 offset:1024
	ds_read_b128 v[186:189], v190 offset:2048
	ds_read_b128 v[190:193], v190 offset:3072
	ds_read_b128 v[198:201], v210
	ds_read_b128 v[202:205], v210 offset:1024
	ds_read_b128 v[206:209], v210 offset:2048
	ds_read_b128 v[210:213], v210 offset:3072
	s_add_u32 s10, s62, 0x20000
	s_addc_u32 s11, s63, 0
	s_mov_b32 m0, s94
	v_lshl_add_u64 v[248:249], s[10:11], 0, v[154:155]
	ds_read_b128 v[214:217], v171 offset:32768
	ds_read_b128 v[218:221], v171 offset:33792
	ds_read_b128 v[222:225], v171 offset:34816
	ds_read_b128 v[226:229], v171 offset:35840
	ds_read_b128 v[230:233], v171 offset:36864
	ds_read_b128 v[234:237], v171 offset:37888
	ds_read_b128 v[238:241], v171 offset:38912
	ds_read_b128 v[242:245], v171 offset:39936
	global_load_lds_dwordx4 v[248:249], off
	v_lshl_add_u64 v[248:249], s[10:11], 0, v[152:153]
	s_mov_b32 m0, s95
	s_nop 0
	global_load_lds_dwordx4 v[248:249], off
	s_waitcnt vmcnt(8)
	s_waitcnt lgkmcnt(0)
	s_barrier
	s_setprio 1
	v_mfma_f32_16x16x32_bf16 v[126:129], v[160:163], v[214:217], v[126:129]
	v_mfma_f32_16x16x32_bf16 v[122:125], v[186:189], v[214:217], v[122:125]
	v_mfma_f32_16x16x32_bf16 v[110:113], v[160:163], v[222:225], v[110:113]
	v_mfma_f32_16x16x32_bf16 v[106:109], v[186:189], v[222:225], v[106:109]
	v_mfma_f32_16x16x32_bf16 v[94:97], v[160:163], v[230:233], v[94:97]
	v_mfma_f32_16x16x32_bf16 v[90:93], v[186:189], v[230:233], v[90:93]
	v_mfma_f32_16x16x32_bf16 v[78:81], v[160:163], v[238:241], v[78:81]
	v_mfma_f32_16x16x32_bf16 v[74:77], v[186:189], v[238:241], v[74:77]
	v_mfma_f32_16x16x32_bf16 v[126:129], v[164:167], v[218:221], v[126:129]
	v_mfma_f32_16x16x32_bf16 v[122:125], v[190:193], v[218:221], v[122:125]
	v_mfma_f32_16x16x32_bf16 v[110:113], v[164:167], v[226:229], v[110:113]
	v_mfma_f32_16x16x32_bf16 v[106:109], v[190:193], v[226:229], v[106:109]
	v_mfma_f32_16x16x32_bf16 v[94:97], v[164:167], v[234:237], v[94:97]
	v_mfma_f32_16x16x32_bf16 v[90:93], v[190:193], v[234:237], v[90:93]
	v_mfma_f32_16x16x32_bf16 v[78:81], v[164:167], v[242:245], v[78:81]
	v_mfma_f32_16x16x32_bf16 v[74:77], v[190:193], v[242:245], v[74:77]
	s_setprio 0
	s_setprio 1
	v_mfma_f32_16x16x32_bf16 v[118:121], v[198:201], v[214:217], v[118:121]
	v_mfma_f32_16x16x32_bf16 v[114:117], v[206:209], v[214:217], v[114:117]
	v_mfma_f32_16x16x32_bf16 v[102:105], v[198:201], v[222:225], v[102:105]
	v_mfma_f32_16x16x32_bf16 v[98:101], v[206:209], v[222:225], v[98:101]
	v_mfma_f32_16x16x32_bf16 v[86:89], v[198:201], v[230:233], v[86:89]
	v_mfma_f32_16x16x32_bf16 v[82:85], v[206:209], v[230:233], v[82:85]
	v_mfma_f32_16x16x32_bf16 v[70:73], v[198:201], v[238:241], v[70:73]
	v_mfma_f32_16x16x32_bf16 v[66:69], v[206:209], v[238:241], v[66:69]
	v_mfma_f32_16x16x32_bf16 v[118:121], v[202:205], v[218:221], v[118:121]
	v_mfma_f32_16x16x32_bf16 v[114:117], v[210:213], v[218:221], v[114:117]
	v_mfma_f32_16x16x32_bf16 v[102:105], v[202:205], v[226:229], v[102:105]
	v_mfma_f32_16x16x32_bf16 v[98:101], v[210:213], v[226:229], v[98:101]
	v_mfma_f32_16x16x32_bf16 v[86:89], v[202:205], v[234:237], v[86:89]
	v_mfma_f32_16x16x32_bf16 v[82:85], v[210:213], v[234:237], v[82:85]
	v_mfma_f32_16x16x32_bf16 v[70:73], v[202:205], v[242:245], v[70:73]
	v_mfma_f32_16x16x32_bf16 v[66:69], v[210:213], v[242:245], v[66:69]
	s_setprio 0
	s_barrier
; #define PG8_STAGE(bufoff, gbase, voff) do { _Pragma("unroll") for (int _i = 0; _i < 2; ++_i) \
;         __builtin_amdgcn_global_load_lds((const unsigned*)((const char*)(gbase) + (voff)[_i]), (PG8_LAS unsigned*)(lds + (bufoff) + ldsw + _i * 8192), 16, 0, 0); } while (0)
; #define PG8_LDA(dst, b, h) do { _Pragma("unroll") for (int m = 0; m < 4; ++m) _Pragma("unroll") for (int k = 0; k < 2; ++k) dst[m][k] = *(const PG8_LAS bf16x8*)(lds + PG8_SA(b, h) + aoff + m * 2048 + k * 1024); } while (0)
; #define PG8_MMA(ai, bj, At, Bt) do { __builtin_amdgcn_s_setprio(1); _Pragma("unroll") for (int m = 0; m < 4; ++m) _Pragma("unroll") for (int n = 0; n < 2; ++n) _Pragma("unroll") for (int k = 0; k < 2; ++k) \
;         acc[ai][bj][m][n] = __builtin_amdgcn_mfma_f32_16x16x32_bf16(Bt[n][k], At[m][k], acc[ai][bj][m][n], 0, 0, 0); __builtin_amdgcn_s_setprio(0); } while (0)
; #define PG8_WAIT_V(n) asm volatile("s_waitcnt vmcnt(" #n ")" ::: "memory")
; #define PG8_WAIT_L(n) asm volatile("s_waitcnt lgkmcnt(" #n ")" ::: "memory")
; #define PG8_BAR __builtin_amdgcn_s_barrier()
; #define PG8_SCHED __builtin_amdgcn_sched_barrier(0)
; template <class Epi, class Sched, bool ALIGN_EPI = false, bool SP2 = false>
; __device__ __forceinline__ void gemm_phase(PG8_LAS unsigned char* lds, const Gemm g, const Sched& S, const Epi& E) {
;     ...
;             PG8_LDA(At, 1, 1); PG8_STAGE(PG8_SB(1, 0), b3, voffB); PG8_STAGE(PG8_SB(1, 1), b3 + hstepB, voffB); PG8_STAGE(PG8_SA(1, 0), a3, voffA);
;             PG8_WAIT_V(8); PG8_WAIT_L(0); PG8_BAR; PG8_MMA(1, 0, At, B0); PG8_MMA(1, 1, At, B1); PG8_BAR; PG8_SCHED;
;     ...
;         if constexpr (ALIGN_EPI) { if (wr == 0) PG8_BAR; }
	s_add_i32 s10, s12, s68
	v_lshl_add_u64 v[130:131], v[130:131], 0, s[2:3]
	s_mov_b32 m0, s10
	ds_read_b128 v[214:217], v171 offset:49152
	ds_read_b128 v[218:221], v171 offset:50176
	ds_read_b128 v[222:225], v171 offset:51200
	ds_read_b128 v[226:229], v171 offset:52224
	ds_read_b128 v[230:233], v171 offset:53248
	ds_read_b128 v[234:237], v171 offset:54272
	ds_read_b128 v[238:241], v171 offset:55296
	ds_read_b128 v[242:245], v171 offset:56320
	global_load_lds_dwordx4 v[130:131], off
	s_add_i32 m0, s10, 0x2000
	s_add_u32 s10, s56, 0x20080
	v_lshl_add_u64 v[130:131], v[132:133], 0, s[2:3]
	s_addc_u32 s11, s57, 0
	s_add_i32 s12, s13, s68
	global_load_lds_dwordx4 v[130:131], off
	v_lshl_add_u64 v[130:131], s[10:11], 0, v[0:1]
	s_mov_b32 m0, s12
	s_nop 0
	global_load_lds_dwordx4 v[130:131], off
	v_lshl_add_u64 v[130:131], s[10:11], 0, v[150:151]
	s_add_i32 m0, s12, 0x2000
	s_nop 0
	global_load_lds_dwordx4 v[130:131], off
	v_lshl_add_u64 v[130:131], v[172:173], 0, s[2:3]
	s_mov_b32 m0, s8
	s_nop 0
	global_load_lds_dwordx4 v[130:131], off
	v_lshl_add_u64 v[130:131], v[246:247], 0, s[2:3]
	s_mov_b32 m0, s9
	s_nop 0
	global_load_lds_dwordx4 v[130:131], off
	s_waitcnt vmcnt(8)
	s_waitcnt lgkmcnt(0)
	s_barrier
	s_setprio 1
	v_mfma_f32_16x16x32_bf16 v[62:65], v[160:163], v[214:217], v[62:65]
	v_mfma_f32_16x16x32_bf16 v[58:61], v[186:189], v[214:217], v[58:61]
	v_mfma_f32_16x16x32_bf16 v[46:49], v[160:163], v[222:225], v[46:49]
	v_mfma_f32_16x16x32_bf16 v[42:45], v[186:189], v[222:225], v[42:45]
	v_mfma_f32_16x16x32_bf16 v[30:33], v[160:163], v[230:233], v[30:33]
	v_mfma_f32_16x16x32_bf16 v[26:29], v[186:189], v[230:233], v[26:29]
	v_mfma_f32_16x16x32_bf16 v[14:17], v[160:163], v[238:241], v[14:17]
	v_mfma_f32_16x16x32_bf16 v[10:13], v[186:189], v[238:241], v[10:13]
	v_mfma_f32_16x16x32_bf16 v[62:65], v[164:167], v[218:221], v[62:65]
	v_mfma_f32_16x16x32_bf16 v[58:61], v[190:193], v[218:221], v[58:61]
	v_mfma_f32_16x16x32_bf16 v[46:49], v[164:167], v[226:229], v[46:49]
	v_mfma_f32_16x16x32_bf16 v[42:45], v[190:193], v[226:229], v[42:45]
	v_mfma_f32_16x16x32_bf16 v[30:33], v[164:167], v[234:237], v[30:33]
	v_mfma_f32_16x16x32_bf16 v[26:29], v[190:193], v[234:237], v[26:29]
	v_mfma_f32_16x16x32_bf16 v[14:17], v[164:167], v[242:245], v[14:17]
	v_mfma_f32_16x16x32_bf16 v[10:13], v[190:193], v[242:245], v[10:13]
	s_setprio 0
	s_setprio 1
	v_mfma_f32_16x16x32_bf16 v[54:57], v[198:201], v[214:217], v[54:57]
	v_mfma_f32_16x16x32_bf16 v[50:53], v[206:209], v[214:217], v[50:53]
	v_mfma_f32_16x16x32_bf16 v[38:41], v[198:201], v[222:225], v[38:41]
	v_mfma_f32_16x16x32_bf16 v[34:37], v[206:209], v[222:225], v[34:37]
	v_mfma_f32_16x16x32_bf16 v[22:25], v[198:201], v[230:233], v[22:25]
	v_mfma_f32_16x16x32_bf16 v[18:21], v[206:209], v[230:233], v[18:21]
	v_mfma_f32_16x16x32_bf16 v[6:9], v[198:201], v[238:241], v[6:9]
	v_mfma_f32_16x16x32_bf16 v[2:5], v[206:209], v[238:241], v[2:5]
	v_mfma_f32_16x16x32_bf16 v[54:57], v[202:205], v[218:221], v[54:57]
	v_mfma_f32_16x16x32_bf16 v[50:53], v[210:213], v[218:221], v[50:53]
	v_mfma_f32_16x16x32_bf16 v[38:41], v[202:205], v[226:229], v[38:41]
	v_mfma_f32_16x16x32_bf16 v[34:37], v[210:213], v[226:229], v[34:37]
	v_mfma_f32_16x16x32_bf16 v[22:25], v[202:205], v[234:237], v[22:25]
	v_mfma_f32_16x16x32_bf16 v[18:21], v[210:213], v[234:237], v[18:21]
	v_mfma_f32_16x16x32_bf16 v[6:9], v[202:205], v[242:245], v[6:9]
	v_mfma_f32_16x16x32_bf16 v[2:5], v[210:213], v[242:245], v[2:5]
	s_setprio 0
	s_barrier
	s_add_i32 vcc_hi, vcc_hi, 2
	s_add_u32 s54, s54, 0x100
	s_addc_u32 s55, s55, 0
	s_add_u32 s91, s91, 0x100
	s_addc_u32 vcc_lo, vcc_lo, 0
	s_cmp_gt_u32 vcc_hi, 5
	s_cbranch_scc0 .LBB0_623
	s_and_b64 vcc, exec, s[42:43]
	s_cbranch_vccz .LBB0_626
	s_barrier

; #define PG8_STAGE(bufoff, gbase, voff) do { _Pragma("unroll") for (int _i = 0; _i < 2; ++_i) \
;         __builtin_amdgcn_global_load_lds((const unsigned*)((const char*)(gbase) + (voff)[_i]), (PG8_LAS unsigned*)(lds + (bufoff) + ldsw + _i * 8192), 16, 0, 0); } while (0)
; #define PG8_LDA(dst, b, h) do { _Pragma("unroll") for (int m = 0; m < 4; ++m) _Pragma("unroll") for (int k = 0; k < 2; ++k) dst[m][k] = *(const PG8_LAS bf16x8*)(lds + PG8_SA(b, h) + aoff + m * 2048 + k * 1024); } while (0)
; #define PG8_LDB(dst, b, h) do { _Pragma("unroll") for (int n = 0; n < 2; ++n) _Pragma("unroll") for (int k = 0; k < 2; ++k) dst[n][k] = *(const PG8_LAS bf16x8*)(lds + PG8_SB(b, h) + boff + n * 2048 + k * 1024); } while (0)
; #define PG8_MMA(ai, bj, At, Bt) do { __builtin_amdgcn_s_setprio(1); _Pragma("unroll") for (int m = 0; m < 4; ++m) _Pragma("unroll") for (int n = 0; n < 2; ++n) _Pragma("unroll") for (int k = 0; k < 2; ++k) \
;         acc[ai][bj][m][n] = __builtin_amdgcn_mfma_f32_16x16x32_bf16(Bt[n][k], At[m][k], acc[ai][bj][m][n], 0, 0, 0); __builtin_amdgcn_s_setprio(0); } while (0)
; #define PG8_WAIT_V(n) asm volatile("s_waitcnt vmcnt(" #n ")" ::: "memory")
; #define PG8_WAIT_L(n) asm volatile("s_waitcnt lgkmcnt(" #n ")" ::: "memory")
; template <class Epi, class Sched, bool ALIGN_EPI = false, bool SP2 = false>
; __device__ __forceinline__ void gemm_phase(PG8_LAS unsigned char* lds, const Gemm g, const Sched& S, const Epi& E) {
;     ...
;             const bool last = (t == nt - 2);
;             const char* a1 = cA + (size_t)(t + 1) * kstep;
;             const char* a2 = last ? nA : cA + (size_t)(t + 2) * kstep; const char* b2 = last ? nB : cB + (size_t)(t + 2) * kstep;
;             const char* a3 = a2 + kstep; const char* b3 = b2 + kstep;
;             if (last && has_next) S.a_ready(nxt);
;             if constexpr (SP2) {
;             PG8_LDB(B0, 0, 0); PG8_LDB(B1, 0, 1); PG8_SCHED; PG8_LDA(At, 0, 0); PG8_STAGE(PG8_SA(1, 1), a1 + hstepA, voffA);
;             PG8_WAIT_V(8); PG8_WAIT_L(0); PG8_BAR; PG8_MMA(0, 0, At, B0); PG8_MMA(0, 1, At, B1); PG8_BAR; PG8_SCHED;
;             PG8_LDA(At, 0, 1); PG8_STAGE(PG8_SB(0, 0), b2, voffB); PG8_STAGE(PG8_SB(0, 1), b2 + hstepB, voffB); PG8_STAGE(PG8_SA(0, 0), a2, voffA);
;             PG8_WAIT_V(8); PG8_WAIT_L(0); PG8_BAR; PG8_MMA(1, 0, At, B0); PG8_MMA(1, 1, At, B1); PG8_BAR; PG8_SCHED;
.LBB0_726:
	s_add_u32 s10, s48, 0xfffc0080
	s_addc_u32 s11, s49, -1
	s_add_i32 s12, 0, 0x10000
	s_cmp_eq_u32 s69, 12
	s_cselect_b32 s53, s43, s11
	s_cselect_b32 s52, s62, s10
	v_add_u32_e32 v130, s12, v167
	s_cselect_b32 s51, s4, s68
	s_cselect_b32 s50, s41, s63
	s_add_i32 s13, 0, 0x14000
	ds_read_b128 v[160:163], v130
	ds_read_b128 v[170:173], v130 offset:1024
	ds_read_b128 v[186:189], v130 offset:2048
	ds_read_b128 v[190:193], v130 offset:3072
	v_add_u32_e32 v130, s13, v167
	ds_read_b128 v[198:201], v130
	ds_read_b128 v[202:205], v130 offset:1024
	ds_read_b128 v[206:209], v130 offset:2048
	ds_read_b128 v[210:213], v130 offset:3072
	v_lshl_add_u64 v[130:131], s[48:49], 0, v[156:157]
	s_add_i32 m0, s9, 0xc000
	ds_read_b128 v[214:217], v169
	ds_read_b128 v[218:221], v169 offset:1024
	ds_read_b128 v[222:225], v169 offset:2048
	ds_read_b128 v[226:229], v169 offset:3072
	ds_read_b128 v[230:233], v169 offset:4096
	ds_read_b128 v[234:237], v169 offset:5120
	ds_read_b128 v[238:241], v169 offset:6144
	ds_read_b128 v[242:245], v169 offset:7168
	global_load_lds_dwordx4 v[130:131], off
	v_lshl_add_u64 v[130:131], s[48:49], 0, v[158:159]
	s_add_i32 m0, s9, 0xe000
	s_nop 0
	global_load_lds_dwordx4 v[130:131], off
	s_waitcnt vmcnt(8)
	s_waitcnt lgkmcnt(0)
	s_barrier
	s_setprio 1
	v_mfma_f32_16x16x32_bf16 v[126:129], v[160:163], v[214:217], v[126:129]
	v_mfma_f32_16x16x32_bf16 v[122:125], v[186:189], v[214:217], v[122:125]
	v_mfma_f32_16x16x32_bf16 v[110:113], v[160:163], v[222:225], v[110:113]
	v_mfma_f32_16x16x32_bf16 v[106:109], v[186:189], v[222:225], v[106:109]
	v_mfma_f32_16x16x32_bf16 v[94:97], v[160:163], v[230:233], v[94:97]
	v_mfma_f32_16x16x32_bf16 v[90:93], v[186:189], v[230:233], v[90:93]
	v_mfma_f32_16x16x32_bf16 v[78:81], v[160:163], v[238:241], v[78:81]
	v_mfma_f32_16x16x32_bf16 v[74:77], v[186:189], v[238:241], v[74:77]
	v_mfma_f32_16x16x32_bf16 v[126:129], v[170:173], v[218:221], v[126:129]
	v_mfma_f32_16x16x32_bf16 v[122:125], v[190:193], v[218:221], v[122:125]
	v_mfma_f32_16x16x32_bf16 v[110:113], v[170:173], v[226:229], v[110:113]
	v_mfma_f32_16x16x32_bf16 v[106:109], v[190:193], v[226:229], v[106:109]
	v_mfma_f32_16x16x32_bf16 v[94:97], v[170:173], v[234:237], v[94:97]
	v_mfma_f32_16x16x32_bf16 v[90:93], v[190:193], v[234:237], v[90:93]
	v_mfma_f32_16x16x32_bf16 v[78:81], v[170:173], v[242:245], v[78:81]
	v_mfma_f32_16x16x32_bf16 v[74:77], v[190:193], v[242:245], v[74:77]
	s_setprio 0
	s_setprio 1
	v_mfma_f32_16x16x32_bf16 v[118:121], v[198:201], v[214:217], v[118:121]
	v_mfma_f32_16x16x32_bf16 v[114:117], v[206:209], v[214:217], v[114:117]
	v_mfma_f32_16x16x32_bf16 v[102:105], v[198:201], v[222:225], v[102:105]
	v_mfma_f32_16x16x32_bf16 v[98:101], v[206:209], v[222:225], v[98:101]
	v_mfma_f32_16x16x32_bf16 v[86:89], v[198:201], v[230:233], v[86:89]
	v_mfma_f32_16x16x32_bf16 v[82:85], v[206:209], v[230:233], v[82:85]
	v_mfma_f32_16x16x32_bf16 v[70:73], v[198:201], v[238:241], v[70:73]
	v_mfma_f32_16x16x32_bf16 v[66:69], v[206:209], v[238:241], v[66:69]
	v_mfma_f32_16x16x32_bf16 v[118:121], v[202:205], v[218:221], v[118:121]
	v_mfma_f32_16x16x32_bf16 v[114:117], v[210:213], v[218:221], v[114:117]
	v_mfma_f32_16x16x32_bf16 v[102:105], v[202:205], v[226:229], v[102:105]
	v_mfma_f32_16x16x32_bf16 v[98:101], v[210:213], v[226:229], v[98:101]
	v_mfma_f32_16x16x32_bf16 v[86:89], v[202:205], v[234:237], v[86:89]
	v_mfma_f32_16x16x32_bf16 v[82:85], v[210:213], v[234:237], v[82:85]
	v_mfma_f32_16x16x32_bf16 v[70:73], v[202:205], v[242:245], v[70:73]
	v_mfma_f32_16x16x32_bf16 v[66:69], v[210:213], v[242:245], v[66:69]
	s_setprio 0
	s_barrier
	s_add_i32 s10, s12, s8
	v_lshl_add_u64 v[130:131], s[50:51], 0, v[0:1]
	s_mov_b32 m0, s10
	ds_read_b128 v[214:217], v169 offset:16384
	ds_read_b128 v[218:221], v169 offset:17408
	ds_read_b128 v[222:225], v169 offset:18432
	ds_read_b128 v[226:229], v169 offset:19456
	ds_read_b128 v[230:233], v169 offset:20480
	ds_read_b128 v[234:237], v169 offset:21504
	ds_read_b128 v[238:241], v169 offset:22528
	ds_read_b128 v[242:245], v169 offset:23552
	global_load_lds_dwordx4 v[130:131], off
	s_add_i32 m0, s10, 0x2000
	s_add_u32 s10, s50, 0x40000
	v_lshl_add_u64 v[132:133], s[50:51], 0, v[150:151]
	s_addc_u32 s11, s51, 0
	s_add_i32 s12, s13, s8
	global_load_lds_dwordx4 v[132:133], off
	v_lshl_add_u64 v[164:165], s[10:11], 0, v[0:1]
	s_mov_b32 m0, s12
	v_lshl_add_u64 v[246:247], s[52:53], 0, v[152:153]
	global_load_lds_dwordx4 v[164:165], off
	v_lshl_add_u64 v[164:165], s[10:11], 0, v[150:151]
	s_add_i32 m0, s12, 0x2000
	s_nop 0
	global_load_lds_dwordx4 v[164:165], off
	v_lshl_add_u64 v[164:165], s[52:53], 0, v[154:155]
	s_mov_b32 m0, s9
	s_nop 0
	global_load_lds_dwordx4 v[164:165], off
	s_mov_b32 m0, s30
	s_nop 0
	global_load_lds_dwordx4 v[246:247], off
	s_waitcnt vmcnt(8)
	s_waitcnt lgkmcnt(0)
	s_barrier
; #define PG8_STAGE(bufoff, gbase, voff) do { _Pragma("unroll") for (int _i = 0; _i < 2; ++_i) \
;         __builtin_amdgcn_global_load_lds((const unsigned*)((const char*)(gbase) + (voff)[_i]), (PG8_LAS unsigned*)(lds + (bufoff) + ldsw + _i * 8192), 16, 0, 0); } while (0)
; #define PG8_LDA(dst, b, h) do { _Pragma("unroll") for (int m = 0; m < 4; ++m) _Pragma("unroll") for (int k = 0; k < 2; ++k) dst[m][k] = *(const PG8_LAS bf16x8*)(lds + PG8_SA(b, h) + aoff + m * 2048 + k * 1024); } while (0)
; #define PG8_LDB(dst, b, h) do { _Pragma("unroll") for (int n = 0; n < 2; ++n) _Pragma("unroll") for (int k = 0; k < 2; ++k) dst[n][k] = *(const PG8_LAS bf16x8*)(lds + PG8_SB(b, h) + boff + n * 2048 + k * 1024); } while (0)
; #define PG8_MMA(ai, bj, At, Bt) do { __builtin_amdgcn_s_setprio(1); _Pragma("unroll") for (int m = 0; m < 4; ++m) _Pragma("unroll") for (int n = 0; n < 2; ++n) _Pragma("unroll") for (int k = 0; k < 2; ++k) \
;         acc[ai][bj][m][n] = __builtin_amdgcn_mfma_f32_16x16x32_bf16(Bt[n][k], At[m][k], acc[ai][bj][m][n], 0, 0, 0); __builtin_amdgcn_s_setprio(0); } while (0)
; #define PG8_WAIT_V(n) asm volatile("s_waitcnt vmcnt(" #n ")" ::: "memory")
; #define PG8_WAIT_L(n) asm volatile("s_waitcnt lgkmcnt(" #n ")" ::: "memory")
; #define PG8_BAR __builtin_amdgcn_s_barrier()
; #define PG8_SCHED __builtin_amdgcn_sched_barrier(0)
; template <class Epi, class Sched, bool ALIGN_EPI = false, bool SP2 = false>
; __device__ __forceinline__ void gemm_phase(PG8_LAS unsigned char* lds, const Gemm g, const Sched& S, const Epi& E) {
;     ...
;             PG8_WAIT_V(8); PG8_WAIT_L(0); PG8_BAR; PG8_MMA(1, 0, At, B0); PG8_MMA(1, 1, At, B1); PG8_BAR; PG8_SCHED;
;             PG8_LDB(B0, 1, 0); PG8_LDB(B1, 1, 1); PG8_SCHED; PG8_LDA(At, 1, 0); PG8_STAGE(PG8_SA(0, 1), a2 + hstepA, voffA);
;             PG8_WAIT_V(8); PG8_WAIT_L(0); PG8_BAR; PG8_MMA(0, 0, At, B0); PG8_MMA(0, 1, At, B1); PG8_BAR; PG8_SCHED;
	s_setprio 1
	v_mfma_f32_16x16x32_bf16 v[62:65], v[160:163], v[214:217], v[62:65]
	v_mfma_f32_16x16x32_bf16 v[58:61], v[186:189], v[214:217], v[58:61]
	v_mfma_f32_16x16x32_bf16 v[46:49], v[160:163], v[222:225], v[46:49]
	v_mfma_f32_16x16x32_bf16 v[42:45], v[186:189], v[222:225], v[42:45]
	v_mfma_f32_16x16x32_bf16 v[30:33], v[160:163], v[230:233], v[30:33]
	v_mfma_f32_16x16x32_bf16 v[26:29], v[186:189], v[230:233], v[26:29]
	v_mfma_f32_16x16x32_bf16 v[14:17], v[160:163], v[238:241], v[14:17]
	v_mfma_f32_16x16x32_bf16 v[10:13], v[186:189], v[238:241], v[10:13]
	v_mfma_f32_16x16x32_bf16 v[62:65], v[170:173], v[218:221], v[62:65]
	v_mfma_f32_16x16x32_bf16 v[58:61], v[190:193], v[218:221], v[58:61]
	v_mfma_f32_16x16x32_bf16 v[46:49], v[170:173], v[226:229], v[46:49]
	v_mfma_f32_16x16x32_bf16 v[42:45], v[190:193], v[226:229], v[42:45]
	v_mfma_f32_16x16x32_bf16 v[30:33], v[170:173], v[234:237], v[30:33]
	v_mfma_f32_16x16x32_bf16 v[26:29], v[190:193], v[234:237], v[26:29]
	v_mfma_f32_16x16x32_bf16 v[14:17], v[170:173], v[242:245], v[14:17]
	v_mfma_f32_16x16x32_bf16 v[10:13], v[190:193], v[242:245], v[10:13]
	s_setprio 0
	s_setprio 1
	v_mfma_f32_16x16x32_bf16 v[54:57], v[198:201], v[214:217], v[54:57]
	v_mfma_f32_16x16x32_bf16 v[50:53], v[206:209], v[214:217], v[50:53]
	v_mfma_f32_16x16x32_bf16 v[38:41], v[198:201], v[222:225], v[38:41]
	v_mfma_f32_16x16x32_bf16 v[34:37], v[206:209], v[222:225], v[34:37]
	v_mfma_f32_16x16x32_bf16 v[22:25], v[198:201], v[230:233], v[22:25]
	v_mfma_f32_16x16x32_bf16 v[18:21], v[206:209], v[230:233], v[18:21]
	v_mfma_f32_16x16x32_bf16 v[6:9], v[198:201], v[238:241], v[6:9]
	v_mfma_f32_16x16x32_bf16 v[2:5], v[206:209], v[238:241], v[2:5]
	v_mfma_f32_16x16x32_bf16 v[54:57], v[202:205], v[218:221], v[54:57]
	v_mfma_f32_16x16x32_bf16 v[50:53], v[210:213], v[218:221], v[50:53]
	v_mfma_f32_16x16x32_bf16 v[38:41], v[202:205], v[226:229], v[38:41]
	v_mfma_f32_16x16x32_bf16 v[34:37], v[210:213], v[226:229], v[34:37]
	v_mfma_f32_16x16x32_bf16 v[22:25], v[202:205], v[234:237], v[22:25]
	v_mfma_f32_16x16x32_bf16 v[18:21], v[210:213], v[234:237], v[18:21]
	v_mfma_f32_16x16x32_bf16 v[6:9], v[202:205], v[242:245], v[6:9]
	v_mfma_f32_16x16x32_bf16 v[2:5], v[210:213], v[242:245], v[2:5]
	s_setprio 0
	s_barrier
	s_add_i32 s12, 0, 0x18000
	s_add_i32 s13, 0, 0x1c000
	v_add_u32_e32 v190, s12, v167
	v_add_u32_e32 v210, s13, v167
	ds_read_b128 v[160:163], v190
	ds_read_b128 v[170:173], v190 offset:1024
	ds_read_b128 v[186:189], v190 offset:2048
	ds_read_b128 v[190:193], v190 offset:3072
	ds_read_b128 v[198:201], v210
	ds_read_b128 v[202:205], v210 offset:1024
	ds_read_b128 v[206:209], v210 offset:2048
	ds_read_b128 v[210:213], v210 offset:3072
	s_add_u32 s10, s52, 0x40000
	s_addc_u32 s11, s53, 0
	s_mov_b32 m0, s31
	v_lshl_add_u64 v[248:249], s[10:11], 0, v[154:155]
	ds_read_b128 v[214:217], v169 offset:32768
	ds_read_b128 v[218:221], v169 offset:33792
	ds_read_b128 v[222:225], v169 offset:34816
	ds_read_b128 v[226:229], v169 offset:35840
	ds_read_b128 v[230:233], v169 offset:36864
	ds_read_b128 v[234:237], v169 offset:37888
	ds_read_b128 v[238:241], v169 offset:38912
	ds_read_b128 v[242:245], v169 offset:39936
	global_load_lds_dwordx4 v[248:249], off
	v_lshl_add_u64 v[248:249], s[10:11], 0, v[152:153]
	s_mov_b32 m0, s34
	s_nop 0
	global_load_lds_dwordx4 v[248:249], off
	s_waitcnt vmcnt(8)
	s_waitcnt lgkmcnt(0)
	s_barrier
	s_setprio 1
	v_mfma_f32_16x16x32_bf16 v[126:129], v[160:163], v[214:217], v[126:129]
	v_mfma_f32_16x16x32_bf16 v[122:125], v[186:189], v[214:217], v[122:125]
	v_mfma_f32_16x16x32_bf16 v[110:113], v[160:163], v[222:225], v[110:113]
	v_mfma_f32_16x16x32_bf16 v[106:109], v[186:189], v[222:225], v[106:109]
	v_mfma_f32_16x16x32_bf16 v[94:97], v[160:163], v[230:233], v[94:97]
	v_mfma_f32_16x16x32_bf16 v[90:93], v[186:189], v[230:233], v[90:93]
	v_mfma_f32_16x16x32_bf16 v[78:81], v[160:163], v[238:241], v[78:81]
	v_mfma_f32_16x16x32_bf16 v[74:77], v[186:189], v[238:241], v[74:77]
	v_mfma_f32_16x16x32_bf16 v[126:129], v[170:173], v[218:221], v[126:129]
	v_mfma_f32_16x16x32_bf16 v[122:125], v[190:193], v[218:221], v[122:125]
	v_mfma_f32_16x16x32_bf16 v[110:113], v[170:173], v[226:229], v[110:113]
	v_mfma_f32_16x16x32_bf16 v[106:109], v[190:193], v[226:229], v[106:109]
	v_mfma_f32_16x16x32_bf16 v[94:97], v[170:173], v[234:237], v[94:97]
	v_mfma_f32_16x16x32_bf16 v[90:93], v[190:193], v[234:237], v[90:93]
	v_mfma_f32_16x16x32_bf16 v[78:81], v[170:173], v[242:245], v[78:81]
	v_mfma_f32_16x16x32_bf16 v[74:77], v[190:193], v[242:245], v[74:77]
	s_setprio 0
	s_setprio 1
	v_mfma_f32_16x16x32_bf16 v[118:121], v[198:201], v[214:217], v[118:121]
	v_mfma_f32_16x16x32_bf16 v[114:117], v[206:209], v[214:217], v[114:117]
	v_mfma_f32_16x16x32_bf16 v[102:105], v[198:201], v[222:225], v[102:105]
	v_mfma_f32_16x16x32_bf16 v[98:101], v[206:209], v[222:225], v[98:101]
	v_mfma_f32_16x16x32_bf16 v[86:89], v[198:201], v[230:233], v[86:89]
	v_mfma_f32_16x16x32_bf16 v[82:85], v[206:209], v[230:233], v[82:85]
	v_mfma_f32_16x16x32_bf16 v[70:73], v[198:201], v[238:241], v[70:73]
	v_mfma_f32_16x16x32_bf16 v[66:69], v[206:209], v[238:241], v[66:69]
	v_mfma_f32_16x16x32_bf16 v[118:121], v[202:205], v[218:221], v[118:121]
	v_mfma_f32_16x16x32_bf16 v[114:117], v[210:213], v[218:221], v[114:117]
	v_mfma_f32_16x16x32_bf16 v[102:105], v[202:205], v[226:229], v[102:105]
	v_mfma_f32_16x16x32_bf16 v[98:101], v[210:213], v[226:229], v[98:101]
	v_mfma_f32_16x16x32_bf16 v[86:89], v[202:205], v[234:237], v[86:89]
	v_mfma_f32_16x16x32_bf16 v[82:85], v[210:213], v[234:237], v[82:85]
	v_mfma_f32_16x16x32_bf16 v[70:73], v[202:205], v[242:245], v[70:73]
	v_mfma_f32_16x16x32_bf16 v[66:69], v[210:213], v[242:245], v[66:69]
	s_setprio 0
	s_barrier
; #define PG8_STAGE(bufoff, gbase, voff) do { _Pragma("unroll") for (int _i = 0; _i < 2; ++_i) \
;         __builtin_amdgcn_global_load_lds((const unsigned*)((const char*)(gbase) + (voff)[_i]), (PG8_LAS unsigned*)(lds + (bufoff) + ldsw + _i * 8192), 16, 0, 0); } while (0)
; #define PG8_LDA(dst, b, h) do { _Pragma("unroll") for (int m = 0; m < 4; ++m) _Pragma("unroll") for (int k = 0; k < 2; ++k) dst[m][k] = *(const PG8_LAS bf16x8*)(lds + PG8_SA(b, h) + aoff + m * 2048 + k * 1024); } while (0)
; #define PG8_MMA(ai, bj, At, Bt) do { __builtin_amdgcn_s_setprio(1); _Pragma("unroll") for (int m = 0; m < 4; ++m) _Pragma("unroll") for (int n = 0; n < 2; ++n) _Pragma("unroll") for (int k = 0; k < 2; ++k) \
;         acc[ai][bj][m][n] = __builtin_amdgcn_mfma_f32_16x16x32_bf16(Bt[n][k], At[m][k], acc[ai][bj][m][n], 0, 0, 0); __builtin_amdgcn_s_setprio(0); } while (0)
; #define PG8_WAIT_V(n) asm volatile("s_waitcnt vmcnt(" #n ")" ::: "memory")
; #define PG8_WAIT_L(n) asm volatile("s_waitcnt lgkmcnt(" #n ")" ::: "memory")
; #define PG8_BAR __builtin_amdgcn_s_barrier()
; #define PG8_SCHED __builtin_amdgcn_sched_barrier(0)
; template <class Epi, class Sched, bool ALIGN_EPI = false, bool SP2 = false>
; __device__ __forceinline__ void gemm_phase(PG8_LAS unsigned char* lds, const Gemm g, const Sched& S, const Epi& E) {
;     ...
;             PG8_LDA(At, 1, 1); PG8_STAGE(PG8_SB(1, 0), b3, voffB); PG8_STAGE(PG8_SB(1, 1), b3 + hstepB, voffB); PG8_STAGE(PG8_SA(1, 0), a3, voffA);
;             PG8_WAIT_V(8); PG8_WAIT_L(0); PG8_BAR; PG8_MMA(1, 0, At, B0); PG8_MMA(1, 1, At, B1); PG8_BAR; PG8_SCHED;
	s_add_i32 s10, s12, s8
	v_lshl_add_u64 v[130:131], v[130:131], 0, s[2:3]
	s_mov_b32 m0, s10
	ds_read_b128 v[214:217], v169 offset:49152
	ds_read_b128 v[218:221], v169 offset:50176
	ds_read_b128 v[222:225], v169 offset:51200
	ds_read_b128 v[226:229], v169 offset:52224
	ds_read_b128 v[230:233], v169 offset:53248
	ds_read_b128 v[234:237], v169 offset:54272
	ds_read_b128 v[238:241], v169 offset:55296
	ds_read_b128 v[242:245], v169 offset:56320
	global_load_lds_dwordx4 v[130:131], off
	s_add_i32 m0, s10, 0x2000
	s_add_u32 s10, s50, 0x40080
	v_lshl_add_u64 v[130:131], v[132:133], 0, s[2:3]
	s_addc_u32 s11, s51, 0
	s_add_i32 s12, s13, s8
	global_load_lds_dwordx4 v[130:131], off
	v_lshl_add_u64 v[130:131], s[10:11], 0, v[0:1]
	s_mov_b32 m0, s12
	s_nop 0
	global_load_lds_dwordx4 v[130:131], off
	v_lshl_add_u64 v[130:131], s[10:11], 0, v[150:151]
	s_add_i32 m0, s12, 0x2000
	s_nop 0
	global_load_lds_dwordx4 v[130:131], off
	v_lshl_add_u64 v[130:131], v[164:165], 0, s[2:3]
	s_mov_b32 m0, s35
	s_nop 0
	global_load_lds_dwordx4 v[130:131], off
	v_lshl_add_u64 v[130:131], v[246:247], 0, s[2:3]
	s_mov_b32 m0, s54
	s_nop 0
	global_load_lds_dwordx4 v[130:131], off
	s_waitcnt vmcnt(8)
	s_waitcnt lgkmcnt(0)
	s_barrier
	s_setprio 1
	v_mfma_f32_16x16x32_bf16 v[62:65], v[160:163], v[214:217], v[62:65]
	v_mfma_f32_16x16x32_bf16 v[58:61], v[186:189], v[214:217], v[58:61]
	v_mfma_f32_16x16x32_bf16 v[46:49], v[160:163], v[222:225], v[46:49]
	v_mfma_f32_16x16x32_bf16 v[42:45], v[186:189], v[222:225], v[42:45]
	v_mfma_f32_16x16x32_bf16 v[30:33], v[160:163], v[230:233], v[30:33]
	v_mfma_f32_16x16x32_bf16 v[26:29], v[186:189], v[230:233], v[26:29]
	v_mfma_f32_16x16x32_bf16 v[14:17], v[160:163], v[238:241], v[14:17]
	v_mfma_f32_16x16x32_bf16 v[10:13], v[186:189], v[238:241], v[10:13]
	v_mfma_f32_16x16x32_bf16 v[62:65], v[170:173], v[218:221], v[62:65]
	v_mfma_f32_16x16x32_bf16 v[58:61], v[190:193], v[218:221], v[58:61]
	v_mfma_f32_16x16x32_bf16 v[46:49], v[170:173], v[226:229], v[46:49]
	v_mfma_f32_16x16x32_bf16 v[42:45], v[190:193], v[226:229], v[42:45]
	v_mfma_f32_16x16x32_bf16 v[30:33], v[170:173], v[234:237], v[30:33]
	v_mfma_f32_16x16x32_bf16 v[26:29], v[190:193], v[234:237], v[26:29]
	v_mfma_f32_16x16x32_bf16 v[14:17], v[170:173], v[242:245], v[14:17]
	v_mfma_f32_16x16x32_bf16 v[10:13], v[190:193], v[242:245], v[10:13]
	s_setprio 0
	s_setprio 1
	v_mfma_f32_16x16x32_bf16 v[54:57], v[198:201], v[214:217], v[54:57]
	v_mfma_f32_16x16x32_bf16 v[50:53], v[206:209], v[214:217], v[50:53]
	v_mfma_f32_16x16x32_bf16 v[38:41], v[198:201], v[222:225], v[38:41]
	v_mfma_f32_16x16x32_bf16 v[34:37], v[206:209], v[222:225], v[34:37]
	v_mfma_f32_16x16x32_bf16 v[22:25], v[198:201], v[230:233], v[22:25]
	v_mfma_f32_16x16x32_bf16 v[18:21], v[206:209], v[230:233], v[18:21]
	v_mfma_f32_16x16x32_bf16 v[6:9], v[198:201], v[238:241], v[6:9]
	v_mfma_f32_16x16x32_bf16 v[2:5], v[206:209], v[238:241], v[2:5]
	v_mfma_f32_16x16x32_bf16 v[54:57], v[202:205], v[218:221], v[54:57]
	v_mfma_f32_16x16x32_bf16 v[50:53], v[210:213], v[218:221], v[50:53]
	v_mfma_f32_16x16x32_bf16 v[38:41], v[202:205], v[226:229], v[38:41]
	v_mfma_f32_16x16x32_bf16 v[34:37], v[210:213], v[226:229], v[34:37]
	v_mfma_f32_16x16x32_bf16 v[22:25], v[202:205], v[234:237], v[22:25]
	v_mfma_f32_16x16x32_bf16 v[18:21], v[210:213], v[234:237], v[18:21]
	v_mfma_f32_16x16x32_bf16 v[6:9], v[202:205], v[242:245], v[6:9]
	v_mfma_f32_16x16x32_bf16 v[2:5], v[210:213], v[242:245], v[2:5]
	s_setprio 0
	s_barrier
	s_add_i32 s69, s69, 2
	s_add_u32 s48, s48, 0x100
	s_addc_u32 s49, s49, 0
	s_add_u32 s63, s63, 0x100
	s_addc_u32 s68, s68, 0
	s_cmp_gt_u32 s69, 13
	s_cbranch_scc0 .LBB0_726
	s_and_b64 vcc, exec, s[20:21]
	s_mov_b64 s[62:63], s[14:15]
	s_cbranch_vccz .LBB0_729
	s_barrier

; #define PG8_STAGE(bufoff, gbase, voff) do { _Pragma("unroll") for (int _i = 0; _i < 2; ++_i) \
;         __builtin_amdgcn_global_load_lds((const unsigned*)((const char*)(gbase) + (voff)[_i]), (PG8_LAS unsigned*)(lds + (bufoff) + ldsw + _i * 8192), 16, 0, 0); } while (0)
; #define PG8_LDA(dst, b, h) do { _Pragma("unroll") for (int m = 0; m < 4; ++m) _Pragma("unroll") for (int k = 0; k < 2; ++k) dst[m][k] = *(const PG8_LAS bf16x8*)(lds + PG8_SA(b, h) + aoff + m * 2048 + k * 1024); } while (0)
; #define PG8_LDB(dst, b, h) do { _Pragma("unroll") for (int n = 0; n < 2; ++n) _Pragma("unroll") for (int k = 0; k < 2; ++k) dst[n][k] = *(const PG8_LAS bf16x8*)(lds + PG8_SB(b, h) + boff + n * 2048 + k * 1024); } while (0)
; #define PG8_MMA(ai, bj, At, Bt) do { __builtin_amdgcn_s_setprio(1); _Pragma("unroll") for (int m = 0; m < 4; ++m) _Pragma("unroll") for (int n = 0; n < 2; ++n) _Pragma("unroll") for (int k = 0; k < 2; ++k) \
;         acc[ai][bj][m][n] = __builtin_amdgcn_mfma_f32_16x16x32_bf16(Bt[n][k], At[m][k], acc[ai][bj][m][n], 0, 0, 0); __builtin_amdgcn_s_setprio(0); } while (0)
; #define PG8_WAIT_V(n) asm volatile("s_waitcnt vmcnt(" #n ")" ::: "memory")
; #define PG8_WAIT_L(n) asm volatile("s_waitcnt lgkmcnt(" #n ")" ::: "memory")
; #define PG8_BAR __builtin_amdgcn_s_barrier()
; #define PG8_SCHED __builtin_amdgcn_sched_barrier(0)
; template <class Epi, class Sched, bool ALIGN_EPI = false, bool SP2 = false>
; __device__ __forceinline__ void gemm_phase(PG8_LAS unsigned char* lds, const Gemm g, const Sched& S, const Epi& E) {
;     ...
;             const bool last = (t == nt - 2);
;             const char* a1 = cA + (size_t)(t + 1) * kstep;
;             const char* a2 = last ? nA : cA + (size_t)(t + 2) * kstep; const char* b2 = last ? nB : cB + (size_t)(t + 2) * kstep;
;             const char* a3 = a2 + kstep; const char* b3 = b2 + kstep;
;             if (last && has_next) S.a_ready(nxt);
;             if constexpr (SP2) {
;             PG8_LDB(B0, 0, 0); PG8_LDB(B1, 0, 1); PG8_SCHED; PG8_LDA(At, 0, 0); PG8_STAGE(PG8_SA(1, 1), a1 + hstepA, voffA);
;             PG8_WAIT_V(8); PG8_WAIT_L(0); PG8_BAR; PG8_MMA(0, 0, At, B0); PG8_MMA(0, 1, At, B1); PG8_BAR; PG8_SCHED;
;             PG8_LDA(At, 0, 1); PG8_STAGE(PG8_SB(0, 0), b2, voffB); PG8_STAGE(PG8_SB(0, 1), b2 + hstepB, voffB); PG8_STAGE(PG8_SA(0, 0), a2, voffA);
.LBB0_856:
	s_add_u32 s10, s48, 0xfffc0080
	s_addc_u32 s11, s49, -1
	s_add_i32 s12, 0, 0x10000
	s_cmp_eq_u32 s69, 12
	s_cselect_b32 s53, s43, s11
	s_cselect_b32 s52, s62, s10
	v_add_u32_e32 v130, s12, v161
	s_cselect_b32 s51, s4, s68
	s_cselect_b32 s50, s41, s63
	s_add_i32 s13, 0, 0x14000
	ds_read_b128 v[164:167], v130
	ds_read_b128 v[168:171], v130 offset:1024
	ds_read_b128 v[186:189], v130 offset:2048
	ds_read_b128 v[190:193], v130 offset:3072
	v_add_u32_e32 v130, s13, v161
	ds_read_b128 v[198:201], v130
	ds_read_b128 v[202:205], v130 offset:1024
	ds_read_b128 v[206:209], v130 offset:2048
	ds_read_b128 v[210:213], v130 offset:3072
	v_lshl_add_u64 v[130:131], s[48:49], 0, v[156:157]
	s_add_i32 m0, s9, 0xc000
	ds_read_b128 v[214:217], v163
	ds_read_b128 v[218:221], v163 offset:1024
	ds_read_b128 v[222:225], v163 offset:2048
	ds_read_b128 v[226:229], v163 offset:3072
	ds_read_b128 v[230:233], v163 offset:4096
	ds_read_b128 v[234:237], v163 offset:5120
	ds_read_b128 v[238:241], v163 offset:6144
	ds_read_b128 v[242:245], v163 offset:7168
	global_load_lds_dwordx4 v[130:131], off
	v_lshl_add_u64 v[130:131], s[48:49], 0, v[158:159]
	s_add_i32 m0, s9, 0xe000
	s_nop 0
	global_load_lds_dwordx4 v[130:131], off
	s_waitcnt vmcnt(8)
	s_waitcnt lgkmcnt(0)
	s_barrier
	s_setprio 1
	v_mfma_f32_16x16x32_bf16 v[126:129], v[164:167], v[214:217], v[126:129]
	v_mfma_f32_16x16x32_bf16 v[122:125], v[186:189], v[214:217], v[122:125]
	v_mfma_f32_16x16x32_bf16 v[110:113], v[164:167], v[222:225], v[110:113]
	v_mfma_f32_16x16x32_bf16 v[106:109], v[186:189], v[222:225], v[106:109]
	v_mfma_f32_16x16x32_bf16 v[94:97], v[164:167], v[230:233], v[94:97]
	v_mfma_f32_16x16x32_bf16 v[90:93], v[186:189], v[230:233], v[90:93]
	v_mfma_f32_16x16x32_bf16 v[78:81], v[164:167], v[238:241], v[78:81]
	v_mfma_f32_16x16x32_bf16 v[74:77], v[186:189], v[238:241], v[74:77]
	v_mfma_f32_16x16x32_bf16 v[126:129], v[168:171], v[218:221], v[126:129]
	v_mfma_f32_16x16x32_bf16 v[122:125], v[190:193], v[218:221], v[122:125]
	v_mfma_f32_16x16x32_bf16 v[110:113], v[168:171], v[226:229], v[110:113]
	v_mfma_f32_16x16x32_bf16 v[106:109], v[190:193], v[226:229], v[106:109]
	v_mfma_f32_16x16x32_bf16 v[94:97], v[168:171], v[234:237], v[94:97]
	v_mfma_f32_16x16x32_bf16 v[90:93], v[190:193], v[234:237], v[90:93]
	v_mfma_f32_16x16x32_bf16 v[78:81], v[168:171], v[242:245], v[78:81]
	v_mfma_f32_16x16x32_bf16 v[74:77], v[190:193], v[242:245], v[74:77]
	s_setprio 0
	s_setprio 1
	v_mfma_f32_16x16x32_bf16 v[118:121], v[198:201], v[214:217], v[118:121]
	v_mfma_f32_16x16x32_bf16 v[114:117], v[206:209], v[214:217], v[114:117]
	v_mfma_f32_16x16x32_bf16 v[102:105], v[198:201], v[222:225], v[102:105]
	v_mfma_f32_16x16x32_bf16 v[98:101], v[206:209], v[222:225], v[98:101]
	v_mfma_f32_16x16x32_bf16 v[86:89], v[198:201], v[230:233], v[86:89]
	v_mfma_f32_16x16x32_bf16 v[82:85], v[206:209], v[230:233], v[82:85]
	v_mfma_f32_16x16x32_bf16 v[70:73], v[198:201], v[238:241], v[70:73]
	v_mfma_f32_16x16x32_bf16 v[66:69], v[206:209], v[238:241], v[66:69]
	v_mfma_f32_16x16x32_bf16 v[118:121], v[202:205], v[218:221], v[118:121]
	v_mfma_f32_16x16x32_bf16 v[114:117], v[210:213], v[218:221], v[114:117]
	v_mfma_f32_16x16x32_bf16 v[102:105], v[202:205], v[226:229], v[102:105]
	v_mfma_f32_16x16x32_bf16 v[98:101], v[210:213], v[226:229], v[98:101]
	v_mfma_f32_16x16x32_bf16 v[86:89], v[202:205], v[234:237], v[86:89]
	v_mfma_f32_16x16x32_bf16 v[82:85], v[210:213], v[234:237], v[82:85]
	v_mfma_f32_16x16x32_bf16 v[70:73], v[202:205], v[242:245], v[70:73]
	v_mfma_f32_16x16x32_bf16 v[66:69], v[210:213], v[242:245], v[66:69]
	s_setprio 0
	s_barrier
	s_add_i32 s10, s12, s8
	v_lshl_add_u64 v[130:131], s[50:51], 0, v[0:1]
	s_mov_b32 m0, s10
	ds_read_b128 v[214:217], v163 offset:16384
	ds_read_b128 v[218:221], v163 offset:17408
	ds_read_b128 v[222:225], v163 offset:18432
	ds_read_b128 v[226:229], v163 offset:19456
	ds_read_b128 v[230:233], v163 offset:20480
	ds_read_b128 v[234:237], v163 offset:21504
	ds_read_b128 v[238:241], v163 offset:22528
	ds_read_b128 v[242:245], v163 offset:23552
	global_load_lds_dwordx4 v[130:131], off
	s_add_i32 m0, s10, 0x2000
	s_add_u32 s10, s50, 0x40000
	v_lshl_add_u64 v[132:133], s[50:51], 0, v[150:151]
	s_addc_u32 s11, s51, 0
	s_add_i32 s12, s13, s8
	global_load_lds_dwordx4 v[132:133], off
	v_lshl_add_u64 v[172:173], s[10:11], 0, v[0:1]
	s_mov_b32 m0, s12
	v_lshl_add_u64 v[246:247], s[52:53], 0, v[152:153]
	global_load_lds_dwordx4 v[172:173], off
	v_lshl_add_u64 v[172:173], s[10:11], 0, v[150:151]
	s_add_i32 m0, s12, 0x2000
	s_nop 0
	global_load_lds_dwordx4 v[172:173], off
	v_lshl_add_u64 v[172:173], s[52:53], 0, v[154:155]
	s_mov_b32 m0, s9
	s_nop 0
	global_load_lds_dwordx4 v[172:173], off
	s_mov_b32 m0, s30
	s_nop 0
	global_load_lds_dwordx4 v[246:247], off
	s_waitcnt vmcnt(8)
	s_waitcnt lgkmcnt(0)
	s_barrier
; #define PG8_STAGE(bufoff, gbase, voff) do { _Pragma("unroll") for (int _i = 0; _i < 2; ++_i) \
;         __builtin_amdgcn_global_load_lds((const unsigned*)((const char*)(gbase) + (voff)[_i]), (PG8_LAS unsigned*)(lds + (bufoff) + ldsw + _i * 8192), 16, 0, 0); } while (0)
; #define PG8_LDA(dst, b, h) do { _Pragma("unroll") for (int m = 0; m < 4; ++m) _Pragma("unroll") for (int k = 0; k < 2; ++k) dst[m][k] = *(const PG8_LAS bf16x8*)(lds + PG8_SA(b, h) + aoff + m * 2048 + k * 1024); } while (0)
; #define PG8_LDB(dst, b, h) do { _Pragma("unroll") for (int n = 0; n < 2; ++n) _Pragma("unroll") for (int k = 0; k < 2; ++k) dst[n][k] = *(const PG8_LAS bf16x8*)(lds + PG8_SB(b, h) + boff + n * 2048 + k * 1024); } while (0)
; #define PG8_MMA(ai, bj, At, Bt) do { __builtin_amdgcn_s_setprio(1); _Pragma("unroll") for (int m = 0; m < 4; ++m) _Pragma("unroll") for (int n = 0; n < 2; ++n) _Pragma("unroll") for (int k = 0; k < 2; ++k) \
;         acc[ai][bj][m][n] = __builtin_amdgcn_mfma_f32_16x16x32_bf16(Bt[n][k], At[m][k], acc[ai][bj][m][n], 0, 0, 0); __builtin_amdgcn_s_setprio(0); } while (0)
; #define PG8_WAIT_V(n) asm volatile("s_waitcnt vmcnt(" #n ")" ::: "memory")
; #define PG8_WAIT_L(n) asm volatile("s_waitcnt lgkmcnt(" #n ")" ::: "memory")
; #define PG8_BAR __builtin_amdgcn_s_barrier()
; #define PG8_SCHED __builtin_amdgcn_sched_barrier(0)
; template <class Epi, class Sched, bool ALIGN_EPI = false, bool SP2 = false>
; __device__ __forceinline__ void gemm_phase(PG8_LAS unsigned char* lds, const Gemm g, const Sched& S, const Epi& E) {
;     ...
;             PG8_WAIT_V(8); PG8_WAIT_L(0); PG8_BAR; PG8_MMA(1, 0, At, B0); PG8_MMA(1, 1, At, B1); PG8_BAR; PG8_SCHED;
;             PG8_LDB(B0, 1, 0); PG8_LDB(B1, 1, 1); PG8_SCHED; PG8_LDA(At, 1, 0); PG8_STAGE(PG8_SA(0, 1), a2 + hstepA, voffA);
;             PG8_WAIT_V(8); PG8_WAIT_L(0); PG8_BAR; PG8_MMA(0, 0, At, B0); PG8_MMA(0, 1, At, B1); PG8_BAR; PG8_SCHED;
	s_setprio 1
	v_mfma_f32_16x16x32_bf16 v[62:65], v[164:167], v[214:217], v[62:65]
	v_mfma_f32_16x16x32_bf16 v[58:61], v[186:189], v[214:217], v[58:61]
	v_mfma_f32_16x16x32_bf16 v[46:49], v[164:167], v[222:225], v[46:49]
	v_mfma_f32_16x16x32_bf16 v[42:45], v[186:189], v[222:225], v[42:45]
	v_mfma_f32_16x16x32_bf16 v[30:33], v[164:167], v[230:233], v[30:33]
	v_mfma_f32_16x16x32_bf16 v[26:29], v[186:189], v[230:233], v[26:29]
	v_mfma_f32_16x16x32_bf16 v[14:17], v[164:167], v[238:241], v[14:17]
	v_mfma_f32_16x16x32_bf16 v[10:13], v[186:189], v[238:241], v[10:13]
	v_mfma_f32_16x16x32_bf16 v[62:65], v[168:171], v[218:221], v[62:65]
	v_mfma_f32_16x16x32_bf16 v[58:61], v[190:193], v[218:221], v[58:61]
	v_mfma_f32_16x16x32_bf16 v[46:49], v[168:171], v[226:229], v[46:49]
	v_mfma_f32_16x16x32_bf16 v[42:45], v[190:193], v[226:229], v[42:45]
	v_mfma_f32_16x16x32_bf16 v[30:33], v[168:171], v[234:237], v[30:33]
	v_mfma_f32_16x16x32_bf16 v[26:29], v[190:193], v[234:237], v[26:29]
	v_mfma_f32_16x16x32_bf16 v[14:17], v[168:171], v[242:245], v[14:17]
	v_mfma_f32_16x16x32_bf16 v[10:13], v[190:193], v[242:245], v[10:13]
	s_setprio 0
	s_setprio 1
	v_mfma_f32_16x16x32_bf16 v[54:57], v[198:201], v[214:217], v[54:57]
	v_mfma_f32_16x16x32_bf16 v[50:53], v[206:209], v[214:217], v[50:53]
	v_mfma_f32_16x16x32_bf16 v[38:41], v[198:201], v[222:225], v[38:41]
	v_mfma_f32_16x16x32_bf16 v[34:37], v[206:209], v[222:225], v[34:37]
	v_mfma_f32_16x16x32_bf16 v[22:25], v[198:201], v[230:233], v[22:25]
	v_mfma_f32_16x16x32_bf16 v[18:21], v[206:209], v[230:233], v[18:21]
	v_mfma_f32_16x16x32_bf16 v[6:9], v[198:201], v[238:241], v[6:9]
	v_mfma_f32_16x16x32_bf16 v[2:5], v[206:209], v[238:241], v[2:5]
	v_mfma_f32_16x16x32_bf16 v[54:57], v[202:205], v[218:221], v[54:57]
	v_mfma_f32_16x16x32_bf16 v[50:53], v[210:213], v[218:221], v[50:53]
	v_mfma_f32_16x16x32_bf16 v[38:41], v[202:205], v[226:229], v[38:41]
	v_mfma_f32_16x16x32_bf16 v[34:37], v[210:213], v[226:229], v[34:37]
	v_mfma_f32_16x16x32_bf16 v[22:25], v[202:205], v[234:237], v[22:25]
	v_mfma_f32_16x16x32_bf16 v[18:21], v[210:213], v[234:237], v[18:21]
	v_mfma_f32_16x16x32_bf16 v[6:9], v[202:205], v[242:245], v[6:9]
	v_mfma_f32_16x16x32_bf16 v[2:5], v[210:213], v[242:245], v[2:5]
	s_setprio 0
	s_barrier
	s_add_i32 s12, 0, 0x18000
	s_add_i32 s13, 0, 0x1c000
	v_add_u32_e32 v190, s12, v161
	v_add_u32_e32 v210, s13, v161
	ds_read_b128 v[164:167], v190
	ds_read_b128 v[168:171], v190 offset:1024
	ds_read_b128 v[186:189], v190 offset:2048
	ds_read_b128 v[190:193], v190 offset:3072
	ds_read_b128 v[198:201], v210
	ds_read_b128 v[202:205], v210 offset:1024
	ds_read_b128 v[206:209], v210 offset:2048
	ds_read_b128 v[210:213], v210 offset:3072
	s_add_u32 s10, s52, 0x40000
	s_addc_u32 s11, s53, 0
	s_mov_b32 m0, s31
	v_lshl_add_u64 v[248:249], s[10:11], 0, v[154:155]
	ds_read_b128 v[214:217], v163 offset:32768
	ds_read_b128 v[218:221], v163 offset:33792
	ds_read_b128 v[222:225], v163 offset:34816
	ds_read_b128 v[226:229], v163 offset:35840
	ds_read_b128 v[230:233], v163 offset:36864
	ds_read_b128 v[234:237], v163 offset:37888
	ds_read_b128 v[238:241], v163 offset:38912
	ds_read_b128 v[242:245], v163 offset:39936
	global_load_lds_dwordx4 v[248:249], off
	v_lshl_add_u64 v[248:249], s[10:11], 0, v[152:153]
	s_mov_b32 m0, s34
	s_nop 0
	global_load_lds_dwordx4 v[248:249], off
	s_waitcnt vmcnt(8)
	s_waitcnt lgkmcnt(0)
	s_barrier
	s_setprio 1
	v_mfma_f32_16x16x32_bf16 v[126:129], v[164:167], v[214:217], v[126:129]
	v_mfma_f32_16x16x32_bf16 v[122:125], v[186:189], v[214:217], v[122:125]
	v_mfma_f32_16x16x32_bf16 v[110:113], v[164:167], v[222:225], v[110:113]
	v_mfma_f32_16x16x32_bf16 v[106:109], v[186:189], v[222:225], v[106:109]
	v_mfma_f32_16x16x32_bf16 v[94:97], v[164:167], v[230:233], v[94:97]
	v_mfma_f32_16x16x32_bf16 v[90:93], v[186:189], v[230:233], v[90:93]
	v_mfma_f32_16x16x32_bf16 v[78:81], v[164:167], v[238:241], v[78:81]
	v_mfma_f32_16x16x32_bf16 v[74:77], v[186:189], v[238:241], v[74:77]
	v_mfma_f32_16x16x32_bf16 v[126:129], v[168:171], v[218:221], v[126:129]
	v_mfma_f32_16x16x32_bf16 v[122:125], v[190:193], v[218:221], v[122:125]
	v_mfma_f32_16x16x32_bf16 v[110:113], v[168:171], v[226:229], v[110:113]
	v_mfma_f32_16x16x32_bf16 v[106:109], v[190:193], v[226:229], v[106:109]
	v_mfma_f32_16x16x32_bf16 v[94:97], v[168:171], v[234:237], v[94:97]
	v_mfma_f32_16x16x32_bf16 v[90:93], v[190:193], v[234:237], v[90:93]
	v_mfma_f32_16x16x32_bf16 v[78:81], v[168:171], v[242:245], v[78:81]
	v_mfma_f32_16x16x32_bf16 v[74:77], v[190:193], v[242:245], v[74:77]
	s_setprio 0
	s_setprio 1
	v_mfma_f32_16x16x32_bf16 v[118:121], v[198:201], v[214:217], v[118:121]
	v_mfma_f32_16x16x32_bf16 v[114:117], v[206:209], v[214:217], v[114:117]
	v_mfma_f32_16x16x32_bf16 v[102:105], v[198:201], v[222:225], v[102:105]
	v_mfma_f32_16x16x32_bf16 v[98:101], v[206:209], v[222:225], v[98:101]
	v_mfma_f32_16x16x32_bf16 v[86:89], v[198:201], v[230:233], v[86:89]
	v_mfma_f32_16x16x32_bf16 v[82:85], v[206:209], v[230:233], v[82:85]
	v_mfma_f32_16x16x32_bf16 v[70:73], v[198:201], v[238:241], v[70:73]
	v_mfma_f32_16x16x32_bf16 v[66:69], v[206:209], v[238:241], v[66:69]
	v_mfma_f32_16x16x32_bf16 v[118:121], v[202:205], v[218:221], v[118:121]
	v_mfma_f32_16x16x32_bf16 v[114:117], v[210:213], v[218:221], v[114:117]
	v_mfma_f32_16x16x32_bf16 v[102:105], v[202:205], v[226:229], v[102:105]
	v_mfma_f32_16x16x32_bf16 v[98:101], v[210:213], v[226:229], v[98:101]
	v_mfma_f32_16x16x32_bf16 v[86:89], v[202:205], v[234:237], v[86:89]
	v_mfma_f32_16x16x32_bf16 v[82:85], v[210:213], v[234:237], v[82:85]
	v_mfma_f32_16x16x32_bf16 v[70:73], v[202:205], v[242:245], v[70:73]
	v_mfma_f32_16x16x32_bf16 v[66:69], v[210:213], v[242:245], v[66:69]
	s_setprio 0
	s_barrier
; #define PG8_STAGE(bufoff, gbase, voff) do { _Pragma("unroll") for (int _i = 0; _i < 2; ++_i) \
;         __builtin_amdgcn_global_load_lds((const unsigned*)((const char*)(gbase) + (voff)[_i]), (PG8_LAS unsigned*)(lds + (bufoff) + ldsw + _i * 8192), 16, 0, 0); } while (0)
; #define PG8_LDA(dst, b, h) do { _Pragma("unroll") for (int m = 0; m < 4; ++m) _Pragma("unroll") for (int k = 0; k < 2; ++k) dst[m][k] = *(const PG8_LAS bf16x8*)(lds + PG8_SA(b, h) + aoff + m * 2048 + k * 1024); } while (0)
; #define PG8_MMA(ai, bj, At, Bt) do { __builtin_amdgcn_s_setprio(1); _Pragma("unroll") for (int m = 0; m < 4; ++m) _Pragma("unroll") for (int n = 0; n < 2; ++n) _Pragma("unroll") for (int k = 0; k < 2; ++k) \
;         acc[ai][bj][m][n] = __builtin_amdgcn_mfma_f32_16x16x32_bf16(Bt[n][k], At[m][k], acc[ai][bj][m][n], 0, 0, 0); __builtin_amdgcn_s_setprio(0); } while (0)
; #define PG8_WAIT_V(n) asm volatile("s_waitcnt vmcnt(" #n ")" ::: "memory")
; #define PG8_WAIT_L(n) asm volatile("s_waitcnt lgkmcnt(" #n ")" ::: "memory")
; #define PG8_BAR __builtin_amdgcn_s_barrier()
; #define PG8_SCHED __builtin_amdgcn_sched_barrier(0)
; template <class Epi, class Sched, bool ALIGN_EPI = false, bool SP2 = false>
; __device__ __forceinline__ void gemm_phase(PG8_LAS unsigned char* lds, const Gemm g, const Sched& S, const Epi& E) {
;     ...
;             PG8_LDA(At, 1, 1); PG8_STAGE(PG8_SB(1, 0), b3, voffB); PG8_STAGE(PG8_SB(1, 1), b3 + hstepB, voffB); PG8_STAGE(PG8_SA(1, 0), a3, voffA);
;             PG8_WAIT_V(8); PG8_WAIT_L(0); PG8_BAR; PG8_MMA(1, 0, At, B0); PG8_MMA(1, 1, At, B1); PG8_BAR; PG8_SCHED;
	s_add_i32 s10, s12, s8
	v_lshl_add_u64 v[130:131], v[130:131], 0, s[2:3]
	s_mov_b32 m0, s10
	ds_read_b128 v[214:217], v163 offset:49152
	ds_read_b128 v[218:221], v163 offset:50176
	ds_read_b128 v[222:225], v163 offset:51200
	ds_read_b128 v[226:229], v163 offset:52224
	ds_read_b128 v[230:233], v163 offset:53248
	ds_read_b128 v[234:237], v163 offset:54272
	ds_read_b128 v[238:241], v163 offset:55296
	ds_read_b128 v[242:245], v163 offset:56320
	global_load_lds_dwordx4 v[130:131], off
	s_add_i32 m0, s10, 0x2000
	s_add_u32 s10, s50, 0x40080
	v_lshl_add_u64 v[130:131], v[132:133], 0, s[2:3]
	s_addc_u32 s11, s51, 0
	s_add_i32 s12, s13, s8
	global_load_lds_dwordx4 v[130:131], off
	v_lshl_add_u64 v[130:131], s[10:11], 0, v[0:1]
	s_mov_b32 m0, s12
	s_nop 0
	global_load_lds_dwordx4 v[130:131], off
	v_lshl_add_u64 v[130:131], s[10:11], 0, v[150:151]
	s_add_i32 m0, s12, 0x2000
	s_nop 0
	global_load_lds_dwordx4 v[130:131], off
	v_lshl_add_u64 v[130:131], v[172:173], 0, s[2:3]
	s_mov_b32 m0, s35
	s_nop 0
	global_load_lds_dwordx4 v[130:131], off
	v_lshl_add_u64 v[130:131], v[246:247], 0, s[2:3]
	s_mov_b32 m0, s54
	s_nop 0
	global_load_lds_dwordx4 v[130:131], off
	s_waitcnt vmcnt(8)
	s_waitcnt lgkmcnt(0)
	s_barrier
	s_setprio 1
	v_mfma_f32_16x16x32_bf16 v[62:65], v[164:167], v[214:217], v[62:65]
	v_mfma_f32_16x16x32_bf16 v[58:61], v[186:189], v[214:217], v[58:61]
	v_mfma_f32_16x16x32_bf16 v[46:49], v[164:167], v[222:225], v[46:49]
	v_mfma_f32_16x16x32_bf16 v[42:45], v[186:189], v[222:225], v[42:45]
	v_mfma_f32_16x16x32_bf16 v[30:33], v[164:167], v[230:233], v[30:33]
	v_mfma_f32_16x16x32_bf16 v[26:29], v[186:189], v[230:233], v[26:29]
	v_mfma_f32_16x16x32_bf16 v[14:17], v[164:167], v[238:241], v[14:17]
	v_mfma_f32_16x16x32_bf16 v[10:13], v[186:189], v[238:241], v[10:13]
	v_mfma_f32_16x16x32_bf16 v[62:65], v[168:171], v[218:221], v[62:65]
	v_mfma_f32_16x16x32_bf16 v[58:61], v[190:193], v[218:221], v[58:61]
	v_mfma_f32_16x16x32_bf16 v[46:49], v[168:171], v[226:229], v[46:49]
	v_mfma_f32_16x16x32_bf16 v[42:45], v[190:193], v[226:229], v[42:45]
	v_mfma_f32_16x16x32_bf16 v[30:33], v[168:171], v[234:237], v[30:33]
	v_mfma_f32_16x16x32_bf16 v[26:29], v[190:193], v[234:237], v[26:29]
	v_mfma_f32_16x16x32_bf16 v[14:17], v[168:171], v[242:245], v[14:17]
	v_mfma_f32_16x16x32_bf16 v[10:13], v[190:193], v[242:245], v[10:13]
	s_setprio 0
	s_setprio 1
	v_mfma_f32_16x16x32_bf16 v[54:57], v[198:201], v[214:217], v[54:57]
	v_mfma_f32_16x16x32_bf16 v[50:53], v[206:209], v[214:217], v[50:53]
	v_mfma_f32_16x16x32_bf16 v[38:41], v[198:201], v[222:225], v[38:41]
	v_mfma_f32_16x16x32_bf16 v[34:37], v[206:209], v[222:225], v[34:37]
	v_mfma_f32_16x16x32_bf16 v[22:25], v[198:201], v[230:233], v[22:25]
	v_mfma_f32_16x16x32_bf16 v[18:21], v[206:209], v[230:233], v[18:21]
	v_mfma_f32_16x16x32_bf16 v[6:9], v[198:201], v[238:241], v[6:9]
	v_mfma_f32_16x16x32_bf16 v[2:5], v[206:209], v[238:241], v[2:5]
	v_mfma_f32_16x16x32_bf16 v[54:57], v[202:205], v[218:221], v[54:57]
	v_mfma_f32_16x16x32_bf16 v[50:53], v[210:213], v[218:221], v[50:53]
	v_mfma_f32_16x16x32_bf16 v[38:41], v[202:205], v[226:229], v[38:41]
	v_mfma_f32_16x16x32_bf16 v[34:37], v[210:213], v[226:229], v[34:37]
	v_mfma_f32_16x16x32_bf16 v[22:25], v[202:205], v[234:237], v[22:25]
	v_mfma_f32_16x16x32_bf16 v[18:21], v[210:213], v[234:237], v[18:21]
	v_mfma_f32_16x16x32_bf16 v[6:9], v[202:205], v[242:245], v[6:9]
	v_mfma_f32_16x16x32_bf16 v[2:5], v[210:213], v[242:245], v[2:5]
	s_setprio 0
	s_barrier
	s_add_i32 s69, s69, 2
	s_add_u32 s48, s48, 0x100
	s_addc_u32 s49, s49, 0
	s_add_u32 s63, s63, 0x100
	s_addc_u32 s68, s68, 0
	s_cmp_gt_u32 s69, 13
	s_cbranch_scc0 .LBB0_856
	s_and_b64 vcc, exec, s[20:21]
	s_mov_b64 s[62:63], s[14:15]
	s_cbranch_vccz .LBB0_859
	s_barrier

; #define PG8_STAGE(bufoff, gbase, voff) do { _Pragma("unroll") for (int _i = 0; _i < 2; ++_i) \
;         __builtin_amdgcn_global_load_lds((const unsigned*)((const char*)(gbase) + (voff)[_i]), (PG8_LAS unsigned*)(lds + (bufoff) + ldsw + _i * 8192), 16, 0, 0); } while (0)
; #define PG8_LDA(dst, b, h) do { _Pragma("unroll") for (int m = 0; m < 4; ++m) _Pragma("unroll") for (int k = 0; k < 2; ++k) dst[m][k] = *(const PG8_LAS bf16x8*)(lds + PG8_SA(b, h) + aoff + m * 2048 + k * 1024); } while (0)
; #define PG8_LDB(dst, b, h) do { _Pragma("unroll") for (int n = 0; n < 2; ++n) _Pragma("unroll") for (int k = 0; k < 2; ++k) dst[n][k] = *(const PG8_LAS bf16x8*)(lds + PG8_SB(b, h) + boff + n * 2048 + k * 1024); } while (0)
; #define PG8_MMA(ai, bj, At, Bt) do { __builtin_amdgcn_s_setprio(1); _Pragma("unroll") for (int m = 0; m < 4; ++m) _Pragma("unroll") for (int n = 0; n < 2; ++n) _Pragma("unroll") for (int k = 0; k < 2; ++k) \
;         acc[ai][bj][m][n] = __builtin_amdgcn_mfma_f32_16x16x32_bf16(Bt[n][k], At[m][k], acc[ai][bj][m][n], 0, 0, 0); __builtin_amdgcn_s_setprio(0); } while (0)
; #define PG8_WAIT_V(n) asm volatile("s_waitcnt vmcnt(" #n ")" ::: "memory")
; #define PG8_WAIT_L(n) asm volatile("s_waitcnt lgkmcnt(" #n ")" ::: "memory")
; #define PG8_BAR __builtin_amdgcn_s_barrier()
; #define PG8_SCHED __builtin_amdgcn_sched_barrier(0)
; template <class Epi, class Sched, bool ALIGN_EPI = false, bool SP2 = false>
; __device__ __forceinline__ void gemm_phase(PG8_LAS unsigned char* lds, const Gemm g, const Sched& S, const Epi& E) {
;     ...
;             const bool last = (t == nt - 2);
;             const char* a1 = cA + (size_t)(t + 1) * kstep;
;             const char* a2 = last ? nA : cA + (size_t)(t + 2) * kstep; const char* b2 = last ? nB : cB + (size_t)(t + 2) * kstep;
;             const char* a3 = a2 + kstep; const char* b3 = b2 + kstep;
;             if (last && has_next) S.a_ready(nxt);
;             if constexpr (SP2) {
;             PG8_LDB(B0, 0, 0); PG8_LDB(B1, 0, 1); PG8_SCHED; PG8_LDA(At, 0, 0); PG8_STAGE(PG8_SA(1, 1), a1 + hstepA, voffA);
;             PG8_WAIT_V(8); PG8_WAIT_L(0); PG8_BAR; PG8_MMA(0, 0, At, B0); PG8_MMA(0, 1, At, B1); PG8_BAR; PG8_SCHED;
;             PG8_LDA(At, 0, 1); PG8_STAGE(PG8_SB(0, 0), b2, voffB); PG8_STAGE(PG8_SB(0, 1), b2 + hstepB, voffB); PG8_STAGE(PG8_SA(0, 0), a2, voffA);
.LBB0_929:
	s_add_u32 s10, s46, 0xfff00080
	s_addc_u32 s11, s47, -1
	s_add_i32 s12, 0, 0x10000
	s_cmp_eq_u32 s63, 60
	s_cselect_b32 s51, s41, s11
	s_cselect_b32 s50, s56, s10
	v_add_u32_e32 v130, s12, v167
	s_cselect_b32 s49, s4, s62
	s_cselect_b32 s48, s39, s57
	s_add_i32 s13, 0, 0x14000
	ds_read_b128 v[160:163], v130
	ds_read_b128 v[170:173], v130 offset:1024
	ds_read_b128 v[186:189], v130 offset:2048
	ds_read_b128 v[190:193], v130 offset:3072
	v_add_u32_e32 v130, s13, v167
	ds_read_b128 v[198:201], v130
	ds_read_b128 v[202:205], v130 offset:1024
	ds_read_b128 v[206:209], v130 offset:2048
	ds_read_b128 v[210:213], v130 offset:3072
	v_lshl_add_u64 v[130:131], s[46:47], 0, v[156:157]
	s_add_i32 m0, s9, 0xc000
	ds_read_b128 v[214:217], v169
	ds_read_b128 v[218:221], v169 offset:1024
	ds_read_b128 v[222:225], v169 offset:2048
	ds_read_b128 v[226:229], v169 offset:3072
	ds_read_b128 v[230:233], v169 offset:4096
	ds_read_b128 v[234:237], v169 offset:5120
	ds_read_b128 v[238:241], v169 offset:6144
	ds_read_b128 v[242:245], v169 offset:7168
	global_load_lds_dwordx4 v[130:131], off
	v_lshl_add_u64 v[130:131], s[46:47], 0, v[158:159]
	s_add_i32 m0, s9, 0xe000
	s_nop 0
	global_load_lds_dwordx4 v[130:131], off
	s_waitcnt vmcnt(8)
	s_waitcnt lgkmcnt(0)
	s_barrier
	s_setprio 1
	v_mfma_f32_16x16x32_bf16 v[126:129], v[160:163], v[214:217], v[126:129]
	v_mfma_f32_16x16x32_bf16 v[122:125], v[186:189], v[214:217], v[122:125]
	v_mfma_f32_16x16x32_bf16 v[110:113], v[160:163], v[222:225], v[110:113]
	v_mfma_f32_16x16x32_bf16 v[106:109], v[186:189], v[222:225], v[106:109]
	v_mfma_f32_16x16x32_bf16 v[94:97], v[160:163], v[230:233], v[94:97]
	v_mfma_f32_16x16x32_bf16 v[90:93], v[186:189], v[230:233], v[90:93]
	v_mfma_f32_16x16x32_bf16 v[78:81], v[160:163], v[238:241], v[78:81]
	v_mfma_f32_16x16x32_bf16 v[74:77], v[186:189], v[238:241], v[74:77]
	v_mfma_f32_16x16x32_bf16 v[126:129], v[170:173], v[218:221], v[126:129]
	v_mfma_f32_16x16x32_bf16 v[122:125], v[190:193], v[218:221], v[122:125]
	v_mfma_f32_16x16x32_bf16 v[110:113], v[170:173], v[226:229], v[110:113]
	v_mfma_f32_16x16x32_bf16 v[106:109], v[190:193], v[226:229], v[106:109]
	v_mfma_f32_16x16x32_bf16 v[94:97], v[170:173], v[234:237], v[94:97]
	v_mfma_f32_16x16x32_bf16 v[90:93], v[190:193], v[234:237], v[90:93]
	v_mfma_f32_16x16x32_bf16 v[78:81], v[170:173], v[242:245], v[78:81]
	v_mfma_f32_16x16x32_bf16 v[74:77], v[190:193], v[242:245], v[74:77]
	s_setprio 0
	s_setprio 1
	v_mfma_f32_16x16x32_bf16 v[118:121], v[198:201], v[214:217], v[118:121]
	v_mfma_f32_16x16x32_bf16 v[114:117], v[206:209], v[214:217], v[114:117]
	v_mfma_f32_16x16x32_bf16 v[102:105], v[198:201], v[222:225], v[102:105]
	v_mfma_f32_16x16x32_bf16 v[98:101], v[206:209], v[222:225], v[98:101]
	v_mfma_f32_16x16x32_bf16 v[86:89], v[198:201], v[230:233], v[86:89]
	v_mfma_f32_16x16x32_bf16 v[82:85], v[206:209], v[230:233], v[82:85]
	v_mfma_f32_16x16x32_bf16 v[70:73], v[198:201], v[238:241], v[70:73]
	v_mfma_f32_16x16x32_bf16 v[66:69], v[206:209], v[238:241], v[66:69]
	v_mfma_f32_16x16x32_bf16 v[118:121], v[202:205], v[218:221], v[118:121]
	v_mfma_f32_16x16x32_bf16 v[114:117], v[210:213], v[218:221], v[114:117]
	v_mfma_f32_16x16x32_bf16 v[102:105], v[202:205], v[226:229], v[102:105]
	v_mfma_f32_16x16x32_bf16 v[98:101], v[210:213], v[226:229], v[98:101]
	v_mfma_f32_16x16x32_bf16 v[86:89], v[202:205], v[234:237], v[86:89]
	v_mfma_f32_16x16x32_bf16 v[82:85], v[210:213], v[234:237], v[82:85]
	v_mfma_f32_16x16x32_bf16 v[70:73], v[202:205], v[242:245], v[70:73]
	v_mfma_f32_16x16x32_bf16 v[66:69], v[210:213], v[242:245], v[66:69]
	s_setprio 0
	s_barrier
	s_add_i32 s10, s12, s8
	v_lshl_add_u64 v[130:131], s[48:49], 0, v[0:1]
	s_mov_b32 m0, s10
	ds_read_b128 v[214:217], v169 offset:16384
	ds_read_b128 v[218:221], v169 offset:17408
	ds_read_b128 v[222:225], v169 offset:18432
	ds_read_b128 v[226:229], v169 offset:19456
	ds_read_b128 v[230:233], v169 offset:20480
	ds_read_b128 v[234:237], v169 offset:21504
	ds_read_b128 v[238:241], v169 offset:22528
	ds_read_b128 v[242:245], v169 offset:23552
	global_load_lds_dwordx4 v[130:131], off
	s_add_i32 m0, s10, 0x2000
	s_add_u32 s10, s48, 0x100000
	v_lshl_add_u64 v[132:133], s[48:49], 0, v[150:151]
	s_addc_u32 s11, s49, 0
	s_add_i32 s12, s13, s8
	global_load_lds_dwordx4 v[132:133], off
	v_lshl_add_u64 v[164:165], s[10:11], 0, v[0:1]
	s_mov_b32 m0, s12
	v_lshl_add_u64 v[246:247], s[50:51], 0, v[152:153]
	global_load_lds_dwordx4 v[164:165], off
	v_lshl_add_u64 v[164:165], s[10:11], 0, v[150:151]
	s_add_i32 m0, s12, 0x2000
	s_nop 0
	global_load_lds_dwordx4 v[164:165], off
	v_lshl_add_u64 v[164:165], s[50:51], 0, v[154:155]
	s_mov_b32 m0, s9
	s_nop 0
	global_load_lds_dwordx4 v[164:165], off
	s_mov_b32 m0, s30
	s_nop 0
	global_load_lds_dwordx4 v[246:247], off
	s_waitcnt vmcnt(8)
	s_waitcnt lgkmcnt(0)
	s_barrier
; #define PG8_STAGE(bufoff, gbase, voff) do { _Pragma("unroll") for (int _i = 0; _i < 2; ++_i) \
;         __builtin_amdgcn_global_load_lds((const unsigned*)((const char*)(gbase) + (voff)[_i]), (PG8_LAS unsigned*)(lds + (bufoff) + ldsw + _i * 8192), 16, 0, 0); } while (0)
; #define PG8_LDA(dst, b, h) do { _Pragma("unroll") for (int m = 0; m < 4; ++m) _Pragma("unroll") for (int k = 0; k < 2; ++k) dst[m][k] = *(const PG8_LAS bf16x8*)(lds + PG8_SA(b, h) + aoff + m * 2048 + k * 1024); } while (0)
; #define PG8_LDB(dst, b, h) do { _Pragma("unroll") for (int n = 0; n < 2; ++n) _Pragma("unroll") for (int k = 0; k < 2; ++k) dst[n][k] = *(const PG8_LAS bf16x8*)(lds + PG8_SB(b, h) + boff + n * 2048 + k * 1024); } while (0)
; #define PG8_MMA(ai, bj, At, Bt) do { __builtin_amdgcn_s_setprio(1); _Pragma("unroll") for (int m = 0; m < 4; ++m) _Pragma("unroll") for (int n = 0; n < 2; ++n) _Pragma("unroll") for (int k = 0; k < 2; ++k) \
;         acc[ai][bj][m][n] = __builtin_amdgcn_mfma_f32_16x16x32_bf16(Bt[n][k], At[m][k], acc[ai][bj][m][n], 0, 0, 0); __builtin_amdgcn_s_setprio(0); } while (0)
; #define PG8_WAIT_V(n) asm volatile("s_waitcnt vmcnt(" #n ")" ::: "memory")
; #define PG8_WAIT_L(n) asm volatile("s_waitcnt lgkmcnt(" #n ")" ::: "memory")
; #define PG8_BAR __builtin_amdgcn_s_barrier()
; #define PG8_SCHED __builtin_amdgcn_sched_barrier(0)
; template <class Epi, class Sched, bool ALIGN_EPI = false, bool SP2 = false>
; __device__ __forceinline__ void gemm_phase(PG8_LAS unsigned char* lds, const Gemm g, const Sched& S, const Epi& E) {
;     ...
;             PG8_WAIT_V(8); PG8_WAIT_L(0); PG8_BAR; PG8_MMA(1, 0, At, B0); PG8_MMA(1, 1, At, B1); PG8_BAR; PG8_SCHED;
;             PG8_LDB(B0, 1, 0); PG8_LDB(B1, 1, 1); PG8_SCHED; PG8_LDA(At, 1, 0); PG8_STAGE(PG8_SA(0, 1), a2 + hstepA, voffA);
;             PG8_WAIT_V(8); PG8_WAIT_L(0); PG8_BAR; PG8_MMA(0, 0, At, B0); PG8_MMA(0, 1, At, B1); PG8_BAR; PG8_SCHED;
	s_setprio 1
	v_mfma_f32_16x16x32_bf16 v[62:65], v[160:163], v[214:217], v[62:65]
	v_mfma_f32_16x16x32_bf16 v[58:61], v[186:189], v[214:217], v[58:61]
	v_mfma_f32_16x16x32_bf16 v[46:49], v[160:163], v[222:225], v[46:49]
	v_mfma_f32_16x16x32_bf16 v[42:45], v[186:189], v[222:225], v[42:45]
	v_mfma_f32_16x16x32_bf16 v[30:33], v[160:163], v[230:233], v[30:33]
	v_mfma_f32_16x16x32_bf16 v[26:29], v[186:189], v[230:233], v[26:29]
	v_mfma_f32_16x16x32_bf16 v[14:17], v[160:163], v[238:241], v[14:17]
	v_mfma_f32_16x16x32_bf16 v[10:13], v[186:189], v[238:241], v[10:13]
	v_mfma_f32_16x16x32_bf16 v[62:65], v[170:173], v[218:221], v[62:65]
	v_mfma_f32_16x16x32_bf16 v[58:61], v[190:193], v[218:221], v[58:61]
	v_mfma_f32_16x16x32_bf16 v[46:49], v[170:173], v[226:229], v[46:49]
	v_mfma_f32_16x16x32_bf16 v[42:45], v[190:193], v[226:229], v[42:45]
	v_mfma_f32_16x16x32_bf16 v[30:33], v[170:173], v[234:237], v[30:33]
	v_mfma_f32_16x16x32_bf16 v[26:29], v[190:193], v[234:237], v[26:29]
	v_mfma_f32_16x16x32_bf16 v[14:17], v[170:173], v[242:245], v[14:17]
	v_mfma_f32_16x16x32_bf16 v[10:13], v[190:193], v[242:245], v[10:13]
	s_setprio 0
	s_setprio 1
	v_mfma_f32_16x16x32_bf16 v[54:57], v[198:201], v[214:217], v[54:57]
	v_mfma_f32_16x16x32_bf16 v[50:53], v[206:209], v[214:217], v[50:53]
	v_mfma_f32_16x16x32_bf16 v[38:41], v[198:201], v[222:225], v[38:41]
	v_mfma_f32_16x16x32_bf16 v[34:37], v[206:209], v[222:225], v[34:37]
	v_mfma_f32_16x16x32_bf16 v[22:25], v[198:201], v[230:233], v[22:25]
	v_mfma_f32_16x16x32_bf16 v[18:21], v[206:209], v[230:233], v[18:21]
	v_mfma_f32_16x16x32_bf16 v[6:9], v[198:201], v[238:241], v[6:9]
	v_mfma_f32_16x16x32_bf16 v[2:5], v[206:209], v[238:241], v[2:5]
	v_mfma_f32_16x16x32_bf16 v[54:57], v[202:205], v[218:221], v[54:57]
	v_mfma_f32_16x16x32_bf16 v[50:53], v[210:213], v[218:221], v[50:53]
	v_mfma_f32_16x16x32_bf16 v[38:41], v[202:205], v[226:229], v[38:41]
	v_mfma_f32_16x16x32_bf16 v[34:37], v[210:213], v[226:229], v[34:37]
	v_mfma_f32_16x16x32_bf16 v[22:25], v[202:205], v[234:237], v[22:25]
	v_mfma_f32_16x16x32_bf16 v[18:21], v[210:213], v[234:237], v[18:21]
	v_mfma_f32_16x16x32_bf16 v[6:9], v[202:205], v[242:245], v[6:9]
	v_mfma_f32_16x16x32_bf16 v[2:5], v[210:213], v[242:245], v[2:5]
	s_setprio 0
	s_barrier
	s_add_i32 s12, 0, 0x18000
	s_add_i32 s13, 0, 0x1c000
	v_add_u32_e32 v190, s12, v167
	v_add_u32_e32 v210, s13, v167
	ds_read_b128 v[160:163], v190
	ds_read_b128 v[170:173], v190 offset:1024
	ds_read_b128 v[186:189], v190 offset:2048
	ds_read_b128 v[190:193], v190 offset:3072
	ds_read_b128 v[198:201], v210
	ds_read_b128 v[202:205], v210 offset:1024
	ds_read_b128 v[206:209], v210 offset:2048
	ds_read_b128 v[210:213], v210 offset:3072
	s_add_u32 s10, s50, 0x100000
	s_addc_u32 s11, s51, 0
	s_mov_b32 m0, s31
	v_lshl_add_u64 v[248:249], s[10:11], 0, v[154:155]
	ds_read_b128 v[214:217], v169 offset:32768
	ds_read_b128 v[218:221], v169 offset:33792
	ds_read_b128 v[222:225], v169 offset:34816
	ds_read_b128 v[226:229], v169 offset:35840
	ds_read_b128 v[230:233], v169 offset:36864
	ds_read_b128 v[234:237], v169 offset:37888
	ds_read_b128 v[238:241], v169 offset:38912
	ds_read_b128 v[242:245], v169 offset:39936
	global_load_lds_dwordx4 v[248:249], off
	v_lshl_add_u64 v[248:249], s[10:11], 0, v[152:153]
	s_mov_b32 m0, s34
	s_nop 0
	global_load_lds_dwordx4 v[248:249], off
	s_waitcnt vmcnt(8)
	s_waitcnt lgkmcnt(0)
	s_barrier
	s_setprio 1
	v_mfma_f32_16x16x32_bf16 v[126:129], v[160:163], v[214:217], v[126:129]
	v_mfma_f32_16x16x32_bf16 v[122:125], v[186:189], v[214:217], v[122:125]
	v_mfma_f32_16x16x32_bf16 v[110:113], v[160:163], v[222:225], v[110:113]
	v_mfma_f32_16x16x32_bf16 v[106:109], v[186:189], v[222:225], v[106:109]
	v_mfma_f32_16x16x32_bf16 v[94:97], v[160:163], v[230:233], v[94:97]
	v_mfma_f32_16x16x32_bf16 v[90:93], v[186:189], v[230:233], v[90:93]
	v_mfma_f32_16x16x32_bf16 v[78:81], v[160:163], v[238:241], v[78:81]
	v_mfma_f32_16x16x32_bf16 v[74:77], v[186:189], v[238:241], v[74:77]
	v_mfma_f32_16x16x32_bf16 v[126:129], v[170:173], v[218:221], v[126:129]
	v_mfma_f32_16x16x32_bf16 v[122:125], v[190:193], v[218:221], v[122:125]
	v_mfma_f32_16x16x32_bf16 v[110:113], v[170:173], v[226:229], v[110:113]
	v_mfma_f32_16x16x32_bf16 v[106:109], v[190:193], v[226:229], v[106:109]
	v_mfma_f32_16x16x32_bf16 v[94:97], v[170:173], v[234:237], v[94:97]
	v_mfma_f32_16x16x32_bf16 v[90:93], v[190:193], v[234:237], v[90:93]
	v_mfma_f32_16x16x32_bf16 v[78:81], v[170:173], v[242:245], v[78:81]
	v_mfma_f32_16x16x32_bf16 v[74:77], v[190:193], v[242:245], v[74:77]
	s_setprio 0
	s_setprio 1
	v_mfma_f32_16x16x32_bf16 v[118:121], v[198:201], v[214:217], v[118:121]
	v_mfma_f32_16x16x32_bf16 v[114:117], v[206:209], v[214:217], v[114:117]
	v_mfma_f32_16x16x32_bf16 v[102:105], v[198:201], v[222:225], v[102:105]
	v_mfma_f32_16x16x32_bf16 v[98:101], v[206:209], v[222:225], v[98:101]
	v_mfma_f32_16x16x32_bf16 v[86:89], v[198:201], v[230:233], v[86:89]
	v_mfma_f32_16x16x32_bf16 v[82:85], v[206:209], v[230:233], v[82:85]
	v_mfma_f32_16x16x32_bf16 v[70:73], v[198:201], v[238:241], v[70:73]
	v_mfma_f32_16x16x32_bf16 v[66:69], v[206:209], v[238:241], v[66:69]
	v_mfma_f32_16x16x32_bf16 v[118:121], v[202:205], v[218:221], v[118:121]
	v_mfma_f32_16x16x32_bf16 v[114:117], v[210:213], v[218:221], v[114:117]
	v_mfma_f32_16x16x32_bf16 v[102:105], v[202:205], v[226:229], v[102:105]
	v_mfma_f32_16x16x32_bf16 v[98:101], v[210:213], v[226:229], v[98:101]
	v_mfma_f32_16x16x32_bf16 v[86:89], v[202:205], v[234:237], v[86:89]
	v_mfma_f32_16x16x32_bf16 v[82:85], v[210:213], v[234:237], v[82:85]
	v_mfma_f32_16x16x32_bf16 v[70:73], v[202:205], v[242:245], v[70:73]
	v_mfma_f32_16x16x32_bf16 v[66:69], v[210:213], v[242:245], v[66:69]
	s_setprio 0
	s_barrier
; #define PG8_STAGE(bufoff, gbase, voff) do { _Pragma("unroll") for (int _i = 0; _i < 2; ++_i) \
;         __builtin_amdgcn_global_load_lds((const unsigned*)((const char*)(gbase) + (voff)[_i]), (PG8_LAS unsigned*)(lds + (bufoff) + ldsw + _i * 8192), 16, 0, 0); } while (0)
; #define PG8_LDA(dst, b, h) do { _Pragma("unroll") for (int m = 0; m < 4; ++m) _Pragma("unroll") for (int k = 0; k < 2; ++k) dst[m][k] = *(const PG8_LAS bf16x8*)(lds + PG8_SA(b, h) + aoff + m * 2048 + k * 1024); } while (0)
; #define PG8_MMA(ai, bj, At, Bt) do { __builtin_amdgcn_s_setprio(1); _Pragma("unroll") for (int m = 0; m < 4; ++m) _Pragma("unroll") for (int n = 0; n < 2; ++n) _Pragma("unroll") for (int k = 0; k < 2; ++k) \
;         acc[ai][bj][m][n] = __builtin_amdgcn_mfma_f32_16x16x32_bf16(Bt[n][k], At[m][k], acc[ai][bj][m][n], 0, 0, 0); __builtin_amdgcn_s_setprio(0); } while (0)
; #define PG8_WAIT_V(n) asm volatile("s_waitcnt vmcnt(" #n ")" ::: "memory")
; #define PG8_WAIT_L(n) asm volatile("s_waitcnt lgkmcnt(" #n ")" ::: "memory")
; #define PG8_BAR __builtin_amdgcn_s_barrier()
; #define PG8_SCHED __builtin_amdgcn_sched_barrier(0)
; template <class Epi, class Sched, bool ALIGN_EPI = false, bool SP2 = false>
; __device__ __forceinline__ void gemm_phase(PG8_LAS unsigned char* lds, const Gemm g, const Sched& S, const Epi& E) {
;     ...
;             PG8_LDA(At, 1, 1); PG8_STAGE(PG8_SB(1, 0), b3, voffB); PG8_STAGE(PG8_SB(1, 1), b3 + hstepB, voffB); PG8_STAGE(PG8_SA(1, 0), a3, voffA);
;             PG8_WAIT_V(8); PG8_WAIT_L(0); PG8_BAR; PG8_MMA(1, 0, At, B0); PG8_MMA(1, 1, At, B1); PG8_BAR; PG8_SCHED;
	s_add_i32 s10, s12, s8
	v_lshl_add_u64 v[130:131], v[130:131], 0, s[2:3]
	s_mov_b32 m0, s10
	ds_read_b128 v[214:217], v169 offset:49152
	ds_read_b128 v[218:221], v169 offset:50176
	ds_read_b128 v[222:225], v169 offset:51200
	ds_read_b128 v[226:229], v169 offset:52224
	ds_read_b128 v[230:233], v169 offset:53248
	ds_read_b128 v[234:237], v169 offset:54272
	ds_read_b128 v[238:241], v169 offset:55296
	ds_read_b128 v[242:245], v169 offset:56320
	global_load_lds_dwordx4 v[130:131], off
	s_add_i32 m0, s10, 0x2000
	s_add_u32 s10, s48, 0x100080
	v_lshl_add_u64 v[130:131], v[132:133], 0, s[2:3]
	s_addc_u32 s11, s49, 0
	s_add_i32 s12, s13, s8
	global_load_lds_dwordx4 v[130:131], off
	v_lshl_add_u64 v[130:131], s[10:11], 0, v[0:1]
	s_mov_b32 m0, s12
	s_nop 0
	global_load_lds_dwordx4 v[130:131], off
	v_lshl_add_u64 v[130:131], s[10:11], 0, v[150:151]
	s_add_i32 m0, s12, 0x2000
	s_nop 0
	global_load_lds_dwordx4 v[130:131], off
	v_lshl_add_u64 v[130:131], v[164:165], 0, s[2:3]
	s_mov_b32 m0, s35
	s_nop 0
	global_load_lds_dwordx4 v[130:131], off
	v_lshl_add_u64 v[130:131], v[246:247], 0, s[2:3]
	s_mov_b32 m0, s52
	s_nop 0
	global_load_lds_dwordx4 v[130:131], off
	s_waitcnt vmcnt(8)
	s_waitcnt lgkmcnt(0)
	s_barrier
	s_setprio 1
	v_mfma_f32_16x16x32_bf16 v[62:65], v[160:163], v[214:217], v[62:65]
	v_mfma_f32_16x16x32_bf16 v[58:61], v[186:189], v[214:217], v[58:61]
	v_mfma_f32_16x16x32_bf16 v[46:49], v[160:163], v[222:225], v[46:49]
	v_mfma_f32_16x16x32_bf16 v[42:45], v[186:189], v[222:225], v[42:45]
	v_mfma_f32_16x16x32_bf16 v[30:33], v[160:163], v[230:233], v[30:33]
	v_mfma_f32_16x16x32_bf16 v[26:29], v[186:189], v[230:233], v[26:29]
	v_mfma_f32_16x16x32_bf16 v[14:17], v[160:163], v[238:241], v[14:17]
	v_mfma_f32_16x16x32_bf16 v[10:13], v[186:189], v[238:241], v[10:13]
	v_mfma_f32_16x16x32_bf16 v[62:65], v[170:173], v[218:221], v[62:65]
	v_mfma_f32_16x16x32_bf16 v[58:61], v[190:193], v[218:221], v[58:61]
	v_mfma_f32_16x16x32_bf16 v[46:49], v[170:173], v[226:229], v[46:49]
	v_mfma_f32_16x16x32_bf16 v[42:45], v[190:193], v[226:229], v[42:45]
	v_mfma_f32_16x16x32_bf16 v[30:33], v[170:173], v[234:237], v[30:33]
	v_mfma_f32_16x16x32_bf16 v[26:29], v[190:193], v[234:237], v[26:29]
	v_mfma_f32_16x16x32_bf16 v[14:17], v[170:173], v[242:245], v[14:17]
	v_mfma_f32_16x16x32_bf16 v[10:13], v[190:193], v[242:245], v[10:13]
	s_setprio 0
	s_setprio 1
	v_mfma_f32_16x16x32_bf16 v[54:57], v[198:201], v[214:217], v[54:57]
	v_mfma_f32_16x16x32_bf16 v[50:53], v[206:209], v[214:217], v[50:53]
	v_mfma_f32_16x16x32_bf16 v[38:41], v[198:201], v[222:225], v[38:41]
	v_mfma_f32_16x16x32_bf16 v[34:37], v[206:209], v[222:225], v[34:37]
	v_mfma_f32_16x16x32_bf16 v[22:25], v[198:201], v[230:233], v[22:25]
	v_mfma_f32_16x16x32_bf16 v[18:21], v[206:209], v[230:233], v[18:21]
	v_mfma_f32_16x16x32_bf16 v[6:9], v[198:201], v[238:241], v[6:9]
	v_mfma_f32_16x16x32_bf16 v[2:5], v[206:209], v[238:241], v[2:5]
	v_mfma_f32_16x16x32_bf16 v[54:57], v[202:205], v[218:221], v[54:57]
	v_mfma_f32_16x16x32_bf16 v[50:53], v[210:213], v[218:221], v[50:53]
	v_mfma_f32_16x16x32_bf16 v[38:41], v[202:205], v[226:229], v[38:41]
	v_mfma_f32_16x16x32_bf16 v[34:37], v[210:213], v[226:229], v[34:37]
	v_mfma_f32_16x16x32_bf16 v[22:25], v[202:205], v[234:237], v[22:25]
	v_mfma_f32_16x16x32_bf16 v[18:21], v[210:213], v[234:237], v[18:21]
	v_mfma_f32_16x16x32_bf16 v[6:9], v[202:205], v[242:245], v[6:9]
	v_mfma_f32_16x16x32_bf16 v[2:5], v[210:213], v[242:245], v[2:5]
	s_setprio 0
	s_barrier
	s_add_i32 s63, s63, 2
	s_add_u32 s46, s46, 0x100
	s_addc_u32 s47, s47, 0
	s_add_u32 s57, s57, 0x100
	s_addc_u32 s62, s62, 0
	s_cmp_gt_u32 s63, 61
	s_cbranch_scc0 .LBB0_929
	s_and_b64 vcc, exec, s[20:21]
	s_mov_b64 s[62:63], s[14:15]
	s_cbranch_vccz .LBB0_932
	s_barrier
